# v1 + gates GEMM k-loops re-emitted with v_mfma_f32_16x16x32_bf16 (swizzled LDS image, in-place accumulator layout conversion)
# speedup vs baseline: 1.0115x; 1.0075x over previous
.LBB0_746:
	s_or_b64 exec, exec, s[0:1]
	v_readlane_b32 s0, v248, 0
	s_cmpk_gt_u32 s0, 0x8ff
	s_cbranch_scc1 .LBB0_757
	v_readlane_b32 s0, v248, 0
	s_lshr_b32 s4, s0, 3
	s_and_b32 s0, s0, 7
	s_add_i32 s1, s0, 0xfffc
	s_and_b32 s1, s1, 0xffff
	v_lshlrev_b32_e32 v2, 4, v1
	s_lshr_b32 s5, s50, 3
	s_min_u32 s6, s0, s1
	v_and_b32_e32 v66, 0x70, v2
	v_mov_b32_e32 v67, 0
	s_cmp_gt_u32 s0, 3
	v_lshl_add_u64 v[2:3], s[82:83], 0, v[66:67]
	s_mov_b64 s[0:1], 0x8f00000
	v_lshl_add_u64 v[68:69], v[2:3], 0, s[0:1]
	s_mov_b64 s[0:1], 0xb100000
	v_lshl_add_u64 v[70:71], v[2:3], 0, s[0:1]
	v_lshrrev_b32_e32 v2, 1, v1
	v_and_b32_e32 v95, 0x1c0, v2
	v_lshrrev_b32_e32 v91, 3, v1
	v_or_b32_e32 v2, v95, v132
	s_movk_i32 s0, 0x90
	v_mad_u32_u24 v96, v2, s0, v34
	v_mul_u32_u24_e32 v2, 0x48, v91
	v_and_b32_e32 v90, 0x5f, v1
	v_lshl_add_u32 v98, v2, 1, v66
	v_lshrrev_b32_e32 v246, 3, v1
	v_and_b32_e32 v246, 15, v246
	v_add_u32_e32 v246, 4, v246
	v_bfe_u32 v246, v246, 3, 1
	v_and_b32_e32 v249, 1, v1
	v_lshlrev_b32_e32 v249, 1, v249
	v_sub_u32_e32 v249, 1, v249
	v_mul_i32_i24_e32 v246, v246, v249
	v_lshlrev_b32_e32 v246, 4, v246
	v_add_u32_e32 v98, v246, v98
	v_mov_b32_e32 v35, v67
	s_mul_i32 s6, s6, 6
	s_mov_b32 s7, 0
	s_cselect_b32 s8, 48, 0
	v_add_u32_e32 v92, 32, v91
	v_add_u32_e32 v93, 64, v91
	v_add_u32_e32 v94, 0x60, v91
	v_mad_u32_u24 v97, v90, s0, v34
	v_add_u32_e32 v99, 0x9000, v98
	v_lshl_add_u64 v[72:73], s[82:83], 0, v[34:35]
	s_mov_b64 s[0:1], 0x8000
	v_mov_b32_e32 v100, 0xc00000
	s_mov_b32 s9, s4
	s_mov_b32 s2, s4
	s_branch .LBB0_749

.LBB0_749:
	s_and_b32 s3, s2, 0xffff
	s_mul_i32 s3, s3, 0xaaab
	s_lshr_b32 s3, s3, 18
	s_mul_i32 s10, s3, 6
	s_sub_i32 s2, s2, s10
	s_and_b32 s2, s2, 0xffff
	s_add_i32 s2, s6, s2
	s_lshl_b32 s10, s2, 7
	v_or_b32_e32 v2, s10, v91
	v_lshlrev_b32_e32 v66, 11, v2
	v_lshl_add_u64 v[74:75], v[68:69], 0, v[66:67]
	v_add_lshl_u32 v66, s10, v92, 11
	s_add_i32 s3, s8, s3
	v_lshl_add_u64 v[76:77], v[68:69], 0, v[66:67]
	v_add_lshl_u32 v66, s10, v93, 11
	s_lshl_b32 s11, s3, 7
	v_lshl_add_u64 v[78:79], v[68:69], 0, v[66:67]
	v_add_lshl_u32 v66, s10, v94, 11
	v_lshl_add_u64 v[80:81], v[68:69], 0, v[66:67]
	v_or_b32_e32 v66, s11, v91
	v_lshlrev_b64 v[2:3], 11, v[66:67]
	v_add_u32_e32 v66, s11, v92
	v_lshl_add_u64 v[82:83], v[70:71], 0, v[2:3]
	v_lshlrev_b64 v[2:3], 11, v[66:67]
	v_add_u32_e32 v66, s11, v93
	v_lshl_add_u64 v[84:85], v[70:71], 0, v[2:3]
	v_lshlrev_b64 v[2:3], 11, v[66:67]
	v_add_u32_e32 v66, s11, v94
	v_lshl_add_u64 v[86:87], v[70:71], 0, v[2:3]
	v_lshlrev_b64 v[2:3], 11, v[66:67]
	v_lshl_add_u64 v[88:89], v[70:71], 0, v[2:3]
	global_load_dwordx4 v[2:5], v[74:75], off
	global_load_dwordx4 v[6:9], v[76:77], off
	global_load_dwordx4 v[10:13], v[78:79], off
	global_load_dwordx4 v[14:17], v[80:81], off
	global_load_dwordx4 v[18:21], v[82:83], off
	global_load_dwordx4 v[22:25], v[84:85], off
	global_load_dwordx4 v[26:29], v[86:87], off
	global_load_dwordx4 v[30:33], v[88:89], off
	global_load_dwordx4 v[102:105], v[74:75], off offset:128
	global_load_dwordx4 v[106:109], v[76:77], off offset:128
	global_load_dwordx4 v[110:113], v[78:79], off offset:128
	global_load_dwordx4 v[114:117], v[80:81], off offset:128
	global_load_dwordx4 v[118:121], v[82:83], off offset:128
	global_load_dwordx4 v[122:125], v[84:85], off offset:128
	global_load_dwordx4 v[126:129], v[86:87], off offset:128
	global_load_dwordx4 v[136:139], v[88:89], off offset:128
	s_waitcnt vmcnt(15)
	ds_write_b128 v98, v[2:5]
	s_waitcnt vmcnt(14)
	ds_write_b128 v98, v[6:9] offset:4608
	s_waitcnt vmcnt(13)
	ds_write_b128 v98, v[10:13] offset:9216
	s_waitcnt vmcnt(12)
	ds_write_b128 v98, v[14:17] offset:13824
	s_waitcnt vmcnt(11)
	ds_write_b128 v98, v[18:21] offset:36864
	s_waitcnt vmcnt(10)
	ds_write_b128 v98, v[22:25] offset:41472
	s_waitcnt vmcnt(9)
	ds_write_b128 v98, v[26:29] offset:46080
	s_waitcnt vmcnt(8)
	ds_write_b128 v98, v[30:33] offset:50688
	s_waitcnt lgkmcnt(0)
	s_barrier
	global_load_dwordx4 v[140:143], v[74:75], off offset:256
	global_load_dwordx4 v[144:147], v[76:77], off offset:256
	global_load_dwordx4 v[148:151], v[78:79], off offset:256
	global_load_dwordx4 v[152:155], v[80:81], off offset:256
	global_load_dwordx4 v[156:159], v[82:83], off offset:256
	global_load_dwordx4 v[160:163], v[84:85], off offset:256
	global_load_dwordx4 v[164:167], v[86:87], off offset:256
	global_load_dwordx4 v[168:171], v[88:89], off offset:256
	v_and_b32_e32 v246, 15, v1
	v_add_u32_e32 v246, 4, v246
	v_bfe_u32 v246, v246, 3, 1
	v_bfe_u32 v249, v1, 4, 2
	v_xor_b32_e32 v246, v246, v249
	v_bfe_u32 v249, v1, 5, 1
	v_sub_u32_e32 v246, v246, v249
	v_lshlrev_b32_e32 v246, 4, v246
	v_bfe_u32 v249, v1, 4, 1
	v_mul_u32_u24_e32 v249, 0x900, v249
	v_sub_u32_e32 v246, v246, v249
	v_add_u32_e32 v244, v246, v96
	v_add_u32_e32 v245, v246, v97
	ds_read_b128 v[212:215], v245 offset:36864
	ds_read_b128 v[196:199], v244
	ds_read_b128 v[216:219], v245 offset:39168
	ds_read_b128 v[220:223], v245 offset:41472
	ds_read_b128 v[224:227], v245 offset:43776
	ds_read_b128 v[200:203], v244 offset:2304
	ds_read_b128 v[204:207], v244 offset:4608
	ds_read_b128 v[208:211], v244 offset:6912
	s_waitcnt lgkmcnt(6)
	v_mfma_f32_16x16x32_bf16 v[50:53], v[196:199], v[212:215], 0
	ds_read_b128 v[228:231], v245 offset:36928
	s_waitcnt lgkmcnt(6)
	v_mfma_f32_16x16x32_bf16 v[54:57], v[196:199], v[216:219], 0
	ds_read_b128 v[232:235], v245 offset:39232
	s_waitcnt lgkmcnt(6)
	v_mfma_f32_16x16x32_bf16 v[18:21], v[196:199], v[220:223], 0
	ds_read_b128 v[236:239], v245 offset:41536
	s_waitcnt lgkmcnt(6)
	v_mfma_f32_16x16x32_bf16 v[22:25], v[196:199], v[224:227], 0
	ds_read_b128 v[240:243], v245 offset:43840
	ds_read_b128 v[196:199], v244 offset:64
	s_waitcnt lgkmcnt(7)
	v_mfma_f32_16x16x32_bf16 v[58:61], v[200:203], v[212:215], 0
	v_mfma_f32_16x16x32_bf16 v[62:65], v[200:203], v[216:219], 0
	v_mfma_f32_16x16x32_bf16 v[26:29], v[200:203], v[220:223], 0
	v_mfma_f32_16x16x32_bf16 v[30:33], v[200:203], v[224:227], 0
	ds_read_b128 v[200:203], v244 offset:2368
	s_waitcnt lgkmcnt(7)
	v_mfma_f32_16x16x32_bf16 v[34:37], v[204:207], v[212:215], 0
	v_mfma_f32_16x16x32_bf16 v[38:41], v[204:207], v[216:219], 0
	v_mfma_f32_16x16x32_bf16 v[2:5], v[204:207], v[220:223], 0
	v_mfma_f32_16x16x32_bf16 v[6:9], v[204:207], v[224:227], 0
	ds_read_b128 v[204:207], v244 offset:4672
	s_waitcnt lgkmcnt(7)
	v_mfma_f32_16x16x32_bf16 v[42:45], v[208:211], v[212:215], 0
	v_mfma_f32_16x16x32_bf16 v[46:49], v[208:211], v[216:219], 0
	v_mfma_f32_16x16x32_bf16 v[10:13], v[208:211], v[220:223], 0
	v_mfma_f32_16x16x32_bf16 v[14:17], v[208:211], v[224:227], 0
	ds_read_b128 v[208:211], v244 offset:6976
	s_waitcnt lgkmcnt(3)
	v_mfma_f32_16x16x32_bf16 v[50:53], v[196:199], v[228:231], v[50:53]
	v_mfma_f32_16x16x32_bf16 v[54:57], v[196:199], v[232:235], v[54:57]
	v_mfma_f32_16x16x32_bf16 v[18:21], v[196:199], v[236:239], v[18:21]
	v_mfma_f32_16x16x32_bf16 v[22:25], v[196:199], v[240:243], v[22:25]
	s_waitcnt vmcnt(15)
	ds_write_b128 v98, v[102:105] offset:18432
	s_waitcnt vmcnt(14)
	ds_write_b128 v98, v[106:109] offset:23040
	s_waitcnt lgkmcnt(4)
	v_mfma_f32_16x16x32_bf16 v[58:61], v[200:203], v[228:231], v[58:61]
	v_mfma_f32_16x16x32_bf16 v[62:65], v[200:203], v[232:235], v[62:65]
	v_mfma_f32_16x16x32_bf16 v[26:29], v[200:203], v[236:239], v[26:29]
	v_mfma_f32_16x16x32_bf16 v[30:33], v[200:203], v[240:243], v[30:33]
	s_waitcnt vmcnt(13)
	ds_write_b128 v98, v[110:113] offset:27648
	s_waitcnt vmcnt(12)
	ds_write_b128 v98, v[114:117] offset:32256
	s_waitcnt lgkmcnt(5)
	v_mfma_f32_16x16x32_bf16 v[34:37], v[204:207], v[228:231], v[34:37]
	v_mfma_f32_16x16x32_bf16 v[38:41], v[204:207], v[232:235], v[38:41]
	v_mfma_f32_16x16x32_bf16 v[2:5], v[204:207], v[236:239], v[2:5]
	v_mfma_f32_16x16x32_bf16 v[6:9], v[204:207], v[240:243], v[6:9]
	s_waitcnt vmcnt(11)
	ds_write_b128 v98, v[118:121] offset:55296
	s_waitcnt vmcnt(10)
	ds_write_b128 v98, v[122:125] offset:59904
	s_waitcnt lgkmcnt(6)
	v_mfma_f32_16x16x32_bf16 v[42:45], v[208:211], v[228:231], v[42:45]
	v_mfma_f32_16x16x32_bf16 v[46:49], v[208:211], v[232:235], v[46:49]
	v_mfma_f32_16x16x32_bf16 v[10:13], v[208:211], v[236:239], v[10:13]
	v_mfma_f32_16x16x32_bf16 v[14:17], v[208:211], v[240:243], v[14:17]
	s_waitcnt vmcnt(9)
	ds_write_b128 v98, v[126:129] offset:64512
	s_waitcnt vmcnt(8)
	ds_write_b128 v99, v[136:139] offset:32256
	s_waitcnt lgkmcnt(0)
	s_barrier
	global_load_dwordx4 v[102:105], v[74:75], off offset:384
	global_load_dwordx4 v[106:109], v[76:77], off offset:384
	global_load_dwordx4 v[110:113], v[78:79], off offset:384
	global_load_dwordx4 v[114:117], v[80:81], off offset:384
	global_load_dwordx4 v[118:121], v[82:83], off offset:384
	global_load_dwordx4 v[122:125], v[84:85], off offset:384
	global_load_dwordx4 v[126:129], v[86:87], off offset:384
	global_load_dwordx4 v[136:139], v[88:89], off offset:384
	ds_read_b128 v[212:215], v245 offset:55296
	ds_read_b128 v[196:199], v244 offset:18432
	ds_read_b128 v[216:219], v245 offset:57600
	ds_read_b128 v[220:223], v245 offset:59904
	ds_read_b128 v[224:227], v245 offset:62208
	ds_read_b128 v[200:203], v244 offset:20736
	ds_read_b128 v[204:207], v244 offset:23040
	ds_read_b128 v[208:211], v244 offset:25344
	s_waitcnt lgkmcnt(6)
	v_mfma_f32_16x16x32_bf16 v[50:53], v[196:199], v[212:215], v[50:53]
	ds_read_b128 v[228:231], v245 offset:55360
	s_waitcnt lgkmcnt(6)
	v_mfma_f32_16x16x32_bf16 v[54:57], v[196:199], v[216:219], v[54:57]
	ds_read_b128 v[232:235], v245 offset:57664
	s_waitcnt lgkmcnt(6)
	v_mfma_f32_16x16x32_bf16 v[18:21], v[196:199], v[220:223], v[18:21]
	ds_read_b128 v[236:239], v245 offset:59968
	s_waitcnt lgkmcnt(6)
	v_mfma_f32_16x16x32_bf16 v[22:25], v[196:199], v[224:227], v[22:25]
	ds_read_b128 v[240:243], v245 offset:62272
	ds_read_b128 v[196:199], v244 offset:18496
	s_waitcnt lgkmcnt(7)
	v_mfma_f32_16x16x32_bf16 v[58:61], v[200:203], v[212:215], v[58:61]
	v_mfma_f32_16x16x32_bf16 v[62:65], v[200:203], v[216:219], v[62:65]
	v_mfma_f32_16x16x32_bf16 v[26:29], v[200:203], v[220:223], v[26:29]
	v_mfma_f32_16x16x32_bf16 v[30:33], v[200:203], v[224:227], v[30:33]
	ds_read_b128 v[200:203], v244 offset:20800
	s_waitcnt lgkmcnt(7)
	v_mfma_f32_16x16x32_bf16 v[34:37], v[204:207], v[212:215], v[34:37]
	v_mfma_f32_16x16x32_bf16 v[38:41], v[204:207], v[216:219], v[38:41]
	v_mfma_f32_16x16x32_bf16 v[2:5], v[204:207], v[220:223], v[2:5]
	v_mfma_f32_16x16x32_bf16 v[6:9], v[204:207], v[224:227], v[6:9]
	ds_read_b128 v[204:207], v244 offset:23104
	s_waitcnt lgkmcnt(7)
	v_mfma_f32_16x16x32_bf16 v[42:45], v[208:211], v[212:215], v[42:45]
	v_mfma_f32_16x16x32_bf16 v[46:49], v[208:211], v[216:219], v[46:49]
	v_mfma_f32_16x16x32_bf16 v[10:13], v[208:211], v[220:223], v[10:13]
	v_mfma_f32_16x16x32_bf16 v[14:17], v[208:211], v[224:227], v[14:17]
	ds_read_b128 v[208:211], v244 offset:25408
	s_waitcnt lgkmcnt(3)
	v_mfma_f32_16x16x32_bf16 v[50:53], v[196:199], v[228:231], v[50:53]
	v_mfma_f32_16x16x32_bf16 v[54:57], v[196:199], v[232:235], v[54:57]
	v_mfma_f32_16x16x32_bf16 v[18:21], v[196:199], v[236:239], v[18:21]
	v_mfma_f32_16x16x32_bf16 v[22:25], v[196:199], v[240:243], v[22:25]
	s_waitcnt vmcnt(15)
	ds_write_b128 v98, v[140:143]
	s_waitcnt vmcnt(14)
	ds_write_b128 v98, v[144:147] offset:4608
	s_waitcnt lgkmcnt(4)
	v_mfma_f32_16x16x32_bf16 v[58:61], v[200:203], v[228:231], v[58:61]
	v_mfma_f32_16x16x32_bf16 v[62:65], v[200:203], v[232:235], v[62:65]
	v_mfma_f32_16x16x32_bf16 v[26:29], v[200:203], v[236:239], v[26:29]
	v_mfma_f32_16x16x32_bf16 v[30:33], v[200:203], v[240:243], v[30:33]
	s_waitcnt vmcnt(13)
	ds_write_b128 v98, v[148:151] offset:9216
	s_waitcnt vmcnt(12)
	ds_write_b128 v98, v[152:155] offset:13824
	s_waitcnt lgkmcnt(5)
	v_mfma_f32_16x16x32_bf16 v[34:37], v[204:207], v[228:231], v[34:37]
	v_mfma_f32_16x16x32_bf16 v[38:41], v[204:207], v[232:235], v[38:41]
	v_mfma_f32_16x16x32_bf16 v[2:5], v[204:207], v[236:239], v[2:5]
	v_mfma_f32_16x16x32_bf16 v[6:9], v[204:207], v[240:243], v[6:9]
	s_waitcnt vmcnt(11)
	ds_write_b128 v98, v[156:159] offset:36864
	s_waitcnt vmcnt(10)
	ds_write_b128 v98, v[160:163] offset:41472
	s_waitcnt lgkmcnt(6)
	v_mfma_f32_16x16x32_bf16 v[42:45], v[208:211], v[228:231], v[42:45]
	v_mfma_f32_16x16x32_bf16 v[46:49], v[208:211], v[232:235], v[46:49]
	v_mfma_f32_16x16x32_bf16 v[10:13], v[208:211], v[236:239], v[10:13]
	v_mfma_f32_16x16x32_bf16 v[14:17], v[208:211], v[240:243], v[14:17]
	s_waitcnt vmcnt(9)
	ds_write_b128 v98, v[164:167] offset:46080
	s_waitcnt vmcnt(8)
	ds_write_b128 v98, v[168:171] offset:50688
	s_waitcnt lgkmcnt(0)
	s_barrier
	global_load_dwordx4 v[140:143], v[74:75], off offset:512
	global_load_dwordx4 v[144:147], v[76:77], off offset:512
	global_load_dwordx4 v[148:151], v[78:79], off offset:512
	global_load_dwordx4 v[152:155], v[80:81], off offset:512
	global_load_dwordx4 v[156:159], v[82:83], off offset:512
	global_load_dwordx4 v[160:163], v[84:85], off offset:512
	global_load_dwordx4 v[164:167], v[86:87], off offset:512
	global_load_dwordx4 v[168:171], v[88:89], off offset:512
	ds_read_b128 v[212:215], v245 offset:36864
	ds_read_b128 v[196:199], v244
	ds_read_b128 v[216:219], v245 offset:39168
	ds_read_b128 v[220:223], v245 offset:41472
	ds_read_b128 v[224:227], v245 offset:43776
	ds_read_b128 v[200:203], v244 offset:2304
	ds_read_b128 v[204:207], v244 offset:4608
	ds_read_b128 v[208:211], v244 offset:6912
	s_waitcnt lgkmcnt(6)
	v_mfma_f32_16x16x32_bf16 v[50:53], v[196:199], v[212:215], v[50:53]
	ds_read_b128 v[228:231], v245 offset:36928
	s_waitcnt lgkmcnt(6)
	v_mfma_f32_16x16x32_bf16 v[54:57], v[196:199], v[216:219], v[54:57]
	ds_read_b128 v[232:235], v245 offset:39232
	s_waitcnt lgkmcnt(6)
	v_mfma_f32_16x16x32_bf16 v[18:21], v[196:199], v[220:223], v[18:21]
	ds_read_b128 v[236:239], v245 offset:41536
	s_waitcnt lgkmcnt(6)
	v_mfma_f32_16x16x32_bf16 v[22:25], v[196:199], v[224:227], v[22:25]
	ds_read_b128 v[240:243], v245 offset:43840
	ds_read_b128 v[196:199], v244 offset:64
	s_waitcnt lgkmcnt(7)
	v_mfma_f32_16x16x32_bf16 v[58:61], v[200:203], v[212:215], v[58:61]
	v_mfma_f32_16x16x32_bf16 v[62:65], v[200:203], v[216:219], v[62:65]
	v_mfma_f32_16x16x32_bf16 v[26:29], v[200:203], v[220:223], v[26:29]
	v_mfma_f32_16x16x32_bf16 v[30:33], v[200:203], v[224:227], v[30:33]
	ds_read_b128 v[200:203], v244 offset:2368
	s_waitcnt lgkmcnt(7)
	v_mfma_f32_16x16x32_bf16 v[34:37], v[204:207], v[212:215], v[34:37]
	v_mfma_f32_16x16x32_bf16 v[38:41], v[204:207], v[216:219], v[38:41]
	v_mfma_f32_16x16x32_bf16 v[2:5], v[204:207], v[220:223], v[2:5]
	v_mfma_f32_16x16x32_bf16 v[6:9], v[204:207], v[224:227], v[6:9]
	ds_read_b128 v[204:207], v244 offset:4672
	s_waitcnt lgkmcnt(7)
	v_mfma_f32_16x16x32_bf16 v[42:45], v[208:211], v[212:215], v[42:45]
	v_mfma_f32_16x16x32_bf16 v[46:49], v[208:211], v[216:219], v[46:49]
	v_mfma_f32_16x16x32_bf16 v[10:13], v[208:211], v[220:223], v[10:13]
	v_mfma_f32_16x16x32_bf16 v[14:17], v[208:211], v[224:227], v[14:17]
	ds_read_b128 v[208:211], v244 offset:6976
	s_waitcnt lgkmcnt(3)
	v_mfma_f32_16x16x32_bf16 v[50:53], v[196:199], v[228:231], v[50:53]
	v_mfma_f32_16x16x32_bf16 v[54:57], v[196:199], v[232:235], v[54:57]
	v_mfma_f32_16x16x32_bf16 v[18:21], v[196:199], v[236:239], v[18:21]
	v_mfma_f32_16x16x32_bf16 v[22:25], v[196:199], v[240:243], v[22:25]
	s_waitcnt vmcnt(15)
	ds_write_b128 v98, v[102:105] offset:18432
	s_waitcnt vmcnt(14)
	ds_write_b128 v98, v[106:109] offset:23040
	s_waitcnt lgkmcnt(4)
	v_mfma_f32_16x16x32_bf16 v[58:61], v[200:203], v[228:231], v[58:61]
	v_mfma_f32_16x16x32_bf16 v[62:65], v[200:203], v[232:235], v[62:65]
	v_mfma_f32_16x16x32_bf16 v[26:29], v[200:203], v[236:239], v[26:29]
	v_mfma_f32_16x16x32_bf16 v[30:33], v[200:203], v[240:243], v[30:33]
	s_waitcnt vmcnt(13)
	ds_write_b128 v98, v[110:113] offset:27648
	s_waitcnt vmcnt(12)
	ds_write_b128 v98, v[114:117] offset:32256
	s_waitcnt lgkmcnt(5)
	v_mfma_f32_16x16x32_bf16 v[34:37], v[204:207], v[228:231], v[34:37]
	v_mfma_f32_16x16x32_bf16 v[38:41], v[204:207], v[232:235], v[38:41]
	v_mfma_f32_16x16x32_bf16 v[2:5], v[204:207], v[236:239], v[2:5]
	v_mfma_f32_16x16x32_bf16 v[6:9], v[204:207], v[240:243], v[6:9]
	s_waitcnt vmcnt(11)
	ds_write_b128 v98, v[118:121] offset:55296
	s_waitcnt vmcnt(10)
	ds_write_b128 v98, v[122:125] offset:59904
	s_waitcnt lgkmcnt(6)
	v_mfma_f32_16x16x32_bf16 v[42:45], v[208:211], v[228:231], v[42:45]
	v_mfma_f32_16x16x32_bf16 v[46:49], v[208:211], v[232:235], v[46:49]
	v_mfma_f32_16x16x32_bf16 v[10:13], v[208:211], v[236:239], v[10:13]
	v_mfma_f32_16x16x32_bf16 v[14:17], v[208:211], v[240:243], v[14:17]
	s_waitcnt vmcnt(9)
	ds_write_b128 v98, v[126:129] offset:64512
	s_waitcnt vmcnt(8)
	ds_write_b128 v99, v[136:139] offset:32256
	s_waitcnt lgkmcnt(0)
	s_barrier
	global_load_dwordx4 v[102:105], v[74:75], off offset:640
	global_load_dwordx4 v[106:109], v[76:77], off offset:640
	global_load_dwordx4 v[110:113], v[78:79], off offset:640
	global_load_dwordx4 v[114:117], v[80:81], off offset:640
	global_load_dwordx4 v[118:121], v[82:83], off offset:640
	global_load_dwordx4 v[122:125], v[84:85], off offset:640
	global_load_dwordx4 v[126:129], v[86:87], off offset:640
	global_load_dwordx4 v[136:139], v[88:89], off offset:640
	ds_read_b128 v[212:215], v245 offset:55296
	ds_read_b128 v[196:199], v244 offset:18432
	ds_read_b128 v[216:219], v245 offset:57600
	ds_read_b128 v[220:223], v245 offset:59904
	ds_read_b128 v[224:227], v245 offset:62208
	ds_read_b128 v[200:203], v244 offset:20736
	ds_read_b128 v[204:207], v244 offset:23040
	ds_read_b128 v[208:211], v244 offset:25344
	s_waitcnt lgkmcnt(6)
	v_mfma_f32_16x16x32_bf16 v[50:53], v[196:199], v[212:215], v[50:53]
	ds_read_b128 v[228:231], v245 offset:55360
	s_waitcnt lgkmcnt(6)
	v_mfma_f32_16x16x32_bf16 v[54:57], v[196:199], v[216:219], v[54:57]
	ds_read_b128 v[232:235], v245 offset:57664
	s_waitcnt lgkmcnt(6)
	v_mfma_f32_16x16x32_bf16 v[18:21], v[196:199], v[220:223], v[18:21]
	ds_read_b128 v[236:239], v245 offset:59968
	s_waitcnt lgkmcnt(6)
	v_mfma_f32_16x16x32_bf16 v[22:25], v[196:199], v[224:227], v[22:25]
	ds_read_b128 v[240:243], v245 offset:62272
	ds_read_b128 v[196:199], v244 offset:18496
	s_waitcnt lgkmcnt(7)
	v_mfma_f32_16x16x32_bf16 v[58:61], v[200:203], v[212:215], v[58:61]
	v_mfma_f32_16x16x32_bf16 v[62:65], v[200:203], v[216:219], v[62:65]
	v_mfma_f32_16x16x32_bf16 v[26:29], v[200:203], v[220:223], v[26:29]
	v_mfma_f32_16x16x32_bf16 v[30:33], v[200:203], v[224:227], v[30:33]
	ds_read_b128 v[200:203], v244 offset:20800
	s_waitcnt lgkmcnt(7)
	v_mfma_f32_16x16x32_bf16 v[34:37], v[204:207], v[212:215], v[34:37]
	v_mfma_f32_16x16x32_bf16 v[38:41], v[204:207], v[216:219], v[38:41]
	v_mfma_f32_16x16x32_bf16 v[2:5], v[204:207], v[220:223], v[2:5]
	v_mfma_f32_16x16x32_bf16 v[6:9], v[204:207], v[224:227], v[6:9]
	ds_read_b128 v[204:207], v244 offset:23104
	s_waitcnt lgkmcnt(7)
	v_mfma_f32_16x16x32_bf16 v[42:45], v[208:211], v[212:215], v[42:45]
	v_mfma_f32_16x16x32_bf16 v[46:49], v[208:211], v[216:219], v[46:49]
	v_mfma_f32_16x16x32_bf16 v[10:13], v[208:211], v[220:223], v[10:13]
	v_mfma_f32_16x16x32_bf16 v[14:17], v[208:211], v[224:227], v[14:17]
	ds_read_b128 v[208:211], v244 offset:25408
	s_waitcnt lgkmcnt(3)
	v_mfma_f32_16x16x32_bf16 v[50:53], v[196:199], v[228:231], v[50:53]
	v_mfma_f32_16x16x32_bf16 v[54:57], v[196:199], v[232:235], v[54:57]
	v_mfma_f32_16x16x32_bf16 v[18:21], v[196:199], v[236:239], v[18:21]
	v_mfma_f32_16x16x32_bf16 v[22:25], v[196:199], v[240:243], v[22:25]
	s_waitcnt vmcnt(15)
	ds_write_b128 v98, v[140:143]
	s_waitcnt vmcnt(14)
	ds_write_b128 v98, v[144:147] offset:4608
	s_waitcnt lgkmcnt(4)
	v_mfma_f32_16x16x32_bf16 v[58:61], v[200:203], v[228:231], v[58:61]
	v_mfma_f32_16x16x32_bf16 v[62:65], v[200:203], v[232:235], v[62:65]
	v_mfma_f32_16x16x32_bf16 v[26:29], v[200:203], v[236:239], v[26:29]
	v_mfma_f32_16x16x32_bf16 v[30:33], v[200:203], v[240:243], v[30:33]
	s_waitcnt vmcnt(13)
	ds_write_b128 v98, v[148:151] offset:9216
	s_waitcnt vmcnt(12)
	ds_write_b128 v98, v[152:155] offset:13824
	s_waitcnt lgkmcnt(5)
	v_mfma_f32_16x16x32_bf16 v[34:37], v[204:207], v[228:231], v[34:37]
	v_mfma_f32_16x16x32_bf16 v[38:41], v[204:207], v[232:235], v[38:41]
	v_mfma_f32_16x16x32_bf16 v[2:5], v[204:207], v[236:239], v[2:5]
	v_mfma_f32_16x16x32_bf16 v[6:9], v[204:207], v[240:243], v[6:9]
	s_waitcnt vmcnt(11)
	ds_write_b128 v98, v[156:159] offset:36864
	s_waitcnt vmcnt(10)
	ds_write_b128 v98, v[160:163] offset:41472
	s_waitcnt lgkmcnt(6)
	v_mfma_f32_16x16x32_bf16 v[42:45], v[208:211], v[228:231], v[42:45]
	v_mfma_f32_16x16x32_bf16 v[46:49], v[208:211], v[232:235], v[46:49]
	v_mfma_f32_16x16x32_bf16 v[10:13], v[208:211], v[236:239], v[10:13]
	v_mfma_f32_16x16x32_bf16 v[14:17], v[208:211], v[240:243], v[14:17]
	s_waitcnt vmcnt(9)
	ds_write_b128 v98, v[164:167] offset:46080
	s_waitcnt vmcnt(8)
	ds_write_b128 v98, v[168:171] offset:50688
	s_waitcnt lgkmcnt(0)
	s_barrier
	global_load_dwordx4 v[140:143], v[74:75], off offset:768
	global_load_dwordx4 v[144:147], v[76:77], off offset:768
	global_load_dwordx4 v[148:151], v[78:79], off offset:768
	global_load_dwordx4 v[152:155], v[80:81], off offset:768
	global_load_dwordx4 v[156:159], v[82:83], off offset:768
	global_load_dwordx4 v[160:163], v[84:85], off offset:768
	global_load_dwordx4 v[164:167], v[86:87], off offset:768
	global_load_dwordx4 v[168:171], v[88:89], off offset:768
	ds_read_b128 v[212:215], v245 offset:36864
	ds_read_b128 v[196:199], v244
	ds_read_b128 v[216:219], v245 offset:39168
	ds_read_b128 v[220:223], v245 offset:41472
	ds_read_b128 v[224:227], v245 offset:43776
	ds_read_b128 v[200:203], v244 offset:2304
	ds_read_b128 v[204:207], v244 offset:4608
	ds_read_b128 v[208:211], v244 offset:6912
	s_waitcnt lgkmcnt(6)
	v_mfma_f32_16x16x32_bf16 v[50:53], v[196:199], v[212:215], v[50:53]
	ds_read_b128 v[228:231], v245 offset:36928
	s_waitcnt lgkmcnt(6)
	v_mfma_f32_16x16x32_bf16 v[54:57], v[196:199], v[216:219], v[54:57]
	ds_read_b128 v[232:235], v245 offset:39232
	s_waitcnt lgkmcnt(6)
	v_mfma_f32_16x16x32_bf16 v[18:21], v[196:199], v[220:223], v[18:21]
	ds_read_b128 v[236:239], v245 offset:41536
	s_waitcnt lgkmcnt(6)
	v_mfma_f32_16x16x32_bf16 v[22:25], v[196:199], v[224:227], v[22:25]
	ds_read_b128 v[240:243], v245 offset:43840
	ds_read_b128 v[196:199], v244 offset:64
	s_waitcnt lgkmcnt(7)
	v_mfma_f32_16x16x32_bf16 v[58:61], v[200:203], v[212:215], v[58:61]
	v_mfma_f32_16x16x32_bf16 v[62:65], v[200:203], v[216:219], v[62:65]
	v_mfma_f32_16x16x32_bf16 v[26:29], v[200:203], v[220:223], v[26:29]
	v_mfma_f32_16x16x32_bf16 v[30:33], v[200:203], v[224:227], v[30:33]
	ds_read_b128 v[200:203], v244 offset:2368
	s_waitcnt lgkmcnt(7)
	v_mfma_f32_16x16x32_bf16 v[34:37], v[204:207], v[212:215], v[34:37]
	v_mfma_f32_16x16x32_bf16 v[38:41], v[204:207], v[216:219], v[38:41]
	v_mfma_f32_16x16x32_bf16 v[2:5], v[204:207], v[220:223], v[2:5]
	v_mfma_f32_16x16x32_bf16 v[6:9], v[204:207], v[224:227], v[6:9]
	ds_read_b128 v[204:207], v244 offset:4672
	s_waitcnt lgkmcnt(7)
	v_mfma_f32_16x16x32_bf16 v[42:45], v[208:211], v[212:215], v[42:45]
	v_mfma_f32_16x16x32_bf16 v[46:49], v[208:211], v[216:219], v[46:49]
	v_mfma_f32_16x16x32_bf16 v[10:13], v[208:211], v[220:223], v[10:13]
	v_mfma_f32_16x16x32_bf16 v[14:17], v[208:211], v[224:227], v[14:17]
	ds_read_b128 v[208:211], v244 offset:6976
	s_waitcnt lgkmcnt(3)
	v_mfma_f32_16x16x32_bf16 v[50:53], v[196:199], v[228:231], v[50:53]
	v_mfma_f32_16x16x32_bf16 v[54:57], v[196:199], v[232:235], v[54:57]
	v_mfma_f32_16x16x32_bf16 v[18:21], v[196:199], v[236:239], v[18:21]
	v_mfma_f32_16x16x32_bf16 v[22:25], v[196:199], v[240:243], v[22:25]
	s_waitcnt vmcnt(15)
	ds_write_b128 v98, v[102:105] offset:18432
	s_waitcnt vmcnt(14)
	ds_write_b128 v98, v[106:109] offset:23040
	s_waitcnt lgkmcnt(4)
	v_mfma_f32_16x16x32_bf16 v[58:61], v[200:203], v[228:231], v[58:61]
	v_mfma_f32_16x16x32_bf16 v[62:65], v[200:203], v[232:235], v[62:65]
	v_mfma_f32_16x16x32_bf16 v[26:29], v[200:203], v[236:239], v[26:29]
	v_mfma_f32_16x16x32_bf16 v[30:33], v[200:203], v[240:243], v[30:33]
	s_waitcnt vmcnt(13)
	ds_write_b128 v98, v[110:113] offset:27648
	s_waitcnt vmcnt(12)
	ds_write_b128 v98, v[114:117] offset:32256
	s_waitcnt lgkmcnt(5)
	v_mfma_f32_16x16x32_bf16 v[34:37], v[204:207], v[228:231], v[34:37]
	v_mfma_f32_16x16x32_bf16 v[38:41], v[204:207], v[232:235], v[38:41]
	v_mfma_f32_16x16x32_bf16 v[2:5], v[204:207], v[236:239], v[2:5]
	v_mfma_f32_16x16x32_bf16 v[6:9], v[204:207], v[240:243], v[6:9]
	s_waitcnt vmcnt(11)
	ds_write_b128 v98, v[118:121] offset:55296
	s_waitcnt vmcnt(10)
	ds_write_b128 v98, v[122:125] offset:59904
	s_waitcnt lgkmcnt(6)
	v_mfma_f32_16x16x32_bf16 v[42:45], v[208:211], v[228:231], v[42:45]
	v_mfma_f32_16x16x32_bf16 v[46:49], v[208:211], v[232:235], v[46:49]
	v_mfma_f32_16x16x32_bf16 v[10:13], v[208:211], v[236:239], v[10:13]
	v_mfma_f32_16x16x32_bf16 v[14:17], v[208:211], v[240:243], v[14:17]
	s_waitcnt vmcnt(9)
	ds_write_b128 v98, v[126:129] offset:64512
	s_waitcnt vmcnt(8)
	ds_write_b128 v99, v[136:139] offset:32256
	s_waitcnt lgkmcnt(0)
	s_barrier
	global_load_dwordx4 v[102:105], v[74:75], off offset:896
	global_load_dwordx4 v[106:109], v[76:77], off offset:896
	global_load_dwordx4 v[110:113], v[78:79], off offset:896
	global_load_dwordx4 v[114:117], v[80:81], off offset:896
	global_load_dwordx4 v[118:121], v[82:83], off offset:896
	global_load_dwordx4 v[122:125], v[84:85], off offset:896
	global_load_dwordx4 v[126:129], v[86:87], off offset:896
	global_load_dwordx4 v[136:139], v[88:89], off offset:896
	ds_read_b128 v[212:215], v245 offset:55296
	ds_read_b128 v[196:199], v244 offset:18432
	ds_read_b128 v[216:219], v245 offset:57600
	ds_read_b128 v[220:223], v245 offset:59904
	ds_read_b128 v[224:227], v245 offset:62208
	ds_read_b128 v[200:203], v244 offset:20736
	ds_read_b128 v[204:207], v244 offset:23040
	ds_read_b128 v[208:211], v244 offset:25344
	s_waitcnt lgkmcnt(6)
	v_mfma_f32_16x16x32_bf16 v[50:53], v[196:199], v[212:215], v[50:53]
	ds_read_b128 v[228:231], v245 offset:55360
	s_waitcnt lgkmcnt(6)
	v_mfma_f32_16x16x32_bf16 v[54:57], v[196:199], v[216:219], v[54:57]
	ds_read_b128 v[232:235], v245 offset:57664
	s_waitcnt lgkmcnt(6)
	v_mfma_f32_16x16x32_bf16 v[18:21], v[196:199], v[220:223], v[18:21]
	ds_read_b128 v[236:239], v245 offset:59968
	s_waitcnt lgkmcnt(6)
	v_mfma_f32_16x16x32_bf16 v[22:25], v[196:199], v[224:227], v[22:25]
	ds_read_b128 v[240:243], v245 offset:62272
	ds_read_b128 v[196:199], v244 offset:18496
	s_waitcnt lgkmcnt(7)
	v_mfma_f32_16x16x32_bf16 v[58:61], v[200:203], v[212:215], v[58:61]
	v_mfma_f32_16x16x32_bf16 v[62:65], v[200:203], v[216:219], v[62:65]
	v_mfma_f32_16x16x32_bf16 v[26:29], v[200:203], v[220:223], v[26:29]
	v_mfma_f32_16x16x32_bf16 v[30:33], v[200:203], v[224:227], v[30:33]
	ds_read_b128 v[200:203], v244 offset:20800
	s_waitcnt lgkmcnt(7)
	v_mfma_f32_16x16x32_bf16 v[34:37], v[204:207], v[212:215], v[34:37]
	v_mfma_f32_16x16x32_bf16 v[38:41], v[204:207], v[216:219], v[38:41]
	v_mfma_f32_16x16x32_bf16 v[2:5], v[204:207], v[220:223], v[2:5]
	v_mfma_f32_16x16x32_bf16 v[6:9], v[204:207], v[224:227], v[6:9]
	ds_read_b128 v[204:207], v244 offset:23104
	s_waitcnt lgkmcnt(7)
	v_mfma_f32_16x16x32_bf16 v[42:45], v[208:211], v[212:215], v[42:45]
	v_mfma_f32_16x16x32_bf16 v[46:49], v[208:211], v[216:219], v[46:49]
	v_mfma_f32_16x16x32_bf16 v[10:13], v[208:211], v[220:223], v[10:13]
	v_mfma_f32_16x16x32_bf16 v[14:17], v[208:211], v[224:227], v[14:17]
	ds_read_b128 v[208:211], v244 offset:25408
	s_waitcnt lgkmcnt(3)
	v_mfma_f32_16x16x32_bf16 v[50:53], v[196:199], v[228:231], v[50:53]
	v_mfma_f32_16x16x32_bf16 v[54:57], v[196:199], v[232:235], v[54:57]
	v_mfma_f32_16x16x32_bf16 v[18:21], v[196:199], v[236:239], v[18:21]
	v_mfma_f32_16x16x32_bf16 v[22:25], v[196:199], v[240:243], v[22:25]
	s_waitcnt vmcnt(15)
	ds_write_b128 v98, v[140:143]
	s_waitcnt vmcnt(14)
	ds_write_b128 v98, v[144:147] offset:4608
	s_waitcnt lgkmcnt(4)
	v_mfma_f32_16x16x32_bf16 v[58:61], v[200:203], v[228:231], v[58:61]
	v_mfma_f32_16x16x32_bf16 v[62:65], v[200:203], v[232:235], v[62:65]
	v_mfma_f32_16x16x32_bf16 v[26:29], v[200:203], v[236:239], v[26:29]
	v_mfma_f32_16x16x32_bf16 v[30:33], v[200:203], v[240:243], v[30:33]
	s_waitcnt vmcnt(13)
	ds_write_b128 v98, v[148:151] offset:9216
	s_waitcnt vmcnt(12)
	ds_write_b128 v98, v[152:155] offset:13824
	s_waitcnt lgkmcnt(5)
	v_mfma_f32_16x16x32_bf16 v[34:37], v[204:207], v[228:231], v[34:37]
	v_mfma_f32_16x16x32_bf16 v[38:41], v[204:207], v[232:235], v[38:41]
	v_mfma_f32_16x16x32_bf16 v[2:5], v[204:207], v[236:239], v[2:5]
	v_mfma_f32_16x16x32_bf16 v[6:9], v[204:207], v[240:243], v[6:9]
	s_waitcnt vmcnt(11)
	ds_write_b128 v98, v[156:159] offset:36864
	s_waitcnt vmcnt(10)
	ds_write_b128 v98, v[160:163] offset:41472
	s_waitcnt lgkmcnt(6)
	v_mfma_f32_16x16x32_bf16 v[42:45], v[208:211], v[228:231], v[42:45]
	v_mfma_f32_16x16x32_bf16 v[46:49], v[208:211], v[232:235], v[46:49]
	v_mfma_f32_16x16x32_bf16 v[10:13], v[208:211], v[236:239], v[10:13]
	v_mfma_f32_16x16x32_bf16 v[14:17], v[208:211], v[240:243], v[14:17]
	s_waitcnt vmcnt(9)
	ds_write_b128 v98, v[164:167] offset:46080
	s_waitcnt vmcnt(8)
	ds_write_b128 v98, v[168:171] offset:50688
	s_waitcnt lgkmcnt(0)
	s_barrier
	global_load_dwordx4 v[140:143], v[74:75], off offset:1024
	global_load_dwordx4 v[144:147], v[76:77], off offset:1024
	global_load_dwordx4 v[148:151], v[78:79], off offset:1024
	global_load_dwordx4 v[152:155], v[80:81], off offset:1024
	global_load_dwordx4 v[156:159], v[82:83], off offset:1024
	global_load_dwordx4 v[160:163], v[84:85], off offset:1024
	global_load_dwordx4 v[164:167], v[86:87], off offset:1024
	global_load_dwordx4 v[168:171], v[88:89], off offset:1024
	ds_read_b128 v[212:215], v245 offset:36864
	ds_read_b128 v[196:199], v244
	ds_read_b128 v[216:219], v245 offset:39168
	ds_read_b128 v[220:223], v245 offset:41472
	ds_read_b128 v[224:227], v245 offset:43776
	ds_read_b128 v[200:203], v244 offset:2304
	ds_read_b128 v[204:207], v244 offset:4608
	ds_read_b128 v[208:211], v244 offset:6912
	s_waitcnt lgkmcnt(6)
	v_mfma_f32_16x16x32_bf16 v[50:53], v[196:199], v[212:215], v[50:53]
	ds_read_b128 v[228:231], v245 offset:36928
	s_waitcnt lgkmcnt(6)
	v_mfma_f32_16x16x32_bf16 v[54:57], v[196:199], v[216:219], v[54:57]
	ds_read_b128 v[232:235], v245 offset:39232
	s_waitcnt lgkmcnt(6)
	v_mfma_f32_16x16x32_bf16 v[18:21], v[196:199], v[220:223], v[18:21]
	ds_read_b128 v[236:239], v245 offset:41536
	s_waitcnt lgkmcnt(6)
	v_mfma_f32_16x16x32_bf16 v[22:25], v[196:199], v[224:227], v[22:25]
	ds_read_b128 v[240:243], v245 offset:43840
	ds_read_b128 v[196:199], v244 offset:64
	s_waitcnt lgkmcnt(7)
	v_mfma_f32_16x16x32_bf16 v[58:61], v[200:203], v[212:215], v[58:61]
	v_mfma_f32_16x16x32_bf16 v[62:65], v[200:203], v[216:219], v[62:65]
	v_mfma_f32_16x16x32_bf16 v[26:29], v[200:203], v[220:223], v[26:29]
	v_mfma_f32_16x16x32_bf16 v[30:33], v[200:203], v[224:227], v[30:33]
	ds_read_b128 v[200:203], v244 offset:2368
	s_waitcnt lgkmcnt(7)
	v_mfma_f32_16x16x32_bf16 v[34:37], v[204:207], v[212:215], v[34:37]
	v_mfma_f32_16x16x32_bf16 v[38:41], v[204:207], v[216:219], v[38:41]
	v_mfma_f32_16x16x32_bf16 v[2:5], v[204:207], v[220:223], v[2:5]
	v_mfma_f32_16x16x32_bf16 v[6:9], v[204:207], v[224:227], v[6:9]
	ds_read_b128 v[204:207], v244 offset:4672
	s_waitcnt lgkmcnt(7)
	v_mfma_f32_16x16x32_bf16 v[42:45], v[208:211], v[212:215], v[42:45]
	v_mfma_f32_16x16x32_bf16 v[46:49], v[208:211], v[216:219], v[46:49]
	v_mfma_f32_16x16x32_bf16 v[10:13], v[208:211], v[220:223], v[10:13]
	v_mfma_f32_16x16x32_bf16 v[14:17], v[208:211], v[224:227], v[14:17]
	ds_read_b128 v[208:211], v244 offset:6976
	s_waitcnt lgkmcnt(3)
	v_mfma_f32_16x16x32_bf16 v[50:53], v[196:199], v[228:231], v[50:53]
	v_mfma_f32_16x16x32_bf16 v[54:57], v[196:199], v[232:235], v[54:57]
	v_mfma_f32_16x16x32_bf16 v[18:21], v[196:199], v[236:239], v[18:21]
	v_mfma_f32_16x16x32_bf16 v[22:25], v[196:199], v[240:243], v[22:25]
	s_waitcnt vmcnt(15)
	ds_write_b128 v98, v[102:105] offset:18432
	s_waitcnt vmcnt(14)
	ds_write_b128 v98, v[106:109] offset:23040
	s_waitcnt lgkmcnt(4)
	v_mfma_f32_16x16x32_bf16 v[58:61], v[200:203], v[228:231], v[58:61]
	v_mfma_f32_16x16x32_bf16 v[62:65], v[200:203], v[232:235], v[62:65]
	v_mfma_f32_16x16x32_bf16 v[26:29], v[200:203], v[236:239], v[26:29]
	v_mfma_f32_16x16x32_bf16 v[30:33], v[200:203], v[240:243], v[30:33]
	s_waitcnt vmcnt(13)
	ds_write_b128 v98, v[110:113] offset:27648
	s_waitcnt vmcnt(12)
	ds_write_b128 v98, v[114:117] offset:32256
	s_waitcnt lgkmcnt(5)
	v_mfma_f32_16x16x32_bf16 v[34:37], v[204:207], v[228:231], v[34:37]
	v_mfma_f32_16x16x32_bf16 v[38:41], v[204:207], v[232:235], v[38:41]
	v_mfma_f32_16x16x32_bf16 v[2:5], v[204:207], v[236:239], v[2:5]
	v_mfma_f32_16x16x32_bf16 v[6:9], v[204:207], v[240:243], v[6:9]
	s_waitcnt vmcnt(11)
	ds_write_b128 v98, v[118:121] offset:55296
	s_waitcnt vmcnt(10)
	ds_write_b128 v98, v[122:125] offset:59904
	s_waitcnt lgkmcnt(6)
	v_mfma_f32_16x16x32_bf16 v[42:45], v[208:211], v[228:231], v[42:45]
	v_mfma_f32_16x16x32_bf16 v[46:49], v[208:211], v[232:235], v[46:49]
	v_mfma_f32_16x16x32_bf16 v[10:13], v[208:211], v[236:239], v[10:13]
	v_mfma_f32_16x16x32_bf16 v[14:17], v[208:211], v[240:243], v[14:17]
	s_waitcnt vmcnt(9)
	ds_write_b128 v98, v[126:129] offset:64512
	s_waitcnt vmcnt(8)
	ds_write_b128 v99, v[136:139] offset:32256
	s_waitcnt lgkmcnt(0)
	s_barrier
	global_load_dwordx4 v[102:105], v[74:75], off offset:1152
	global_load_dwordx4 v[106:109], v[76:77], off offset:1152
	global_load_dwordx4 v[110:113], v[78:79], off offset:1152
	global_load_dwordx4 v[114:117], v[80:81], off offset:1152
	global_load_dwordx4 v[118:121], v[82:83], off offset:1152
	global_load_dwordx4 v[122:125], v[84:85], off offset:1152
	global_load_dwordx4 v[126:129], v[86:87], off offset:1152
	global_load_dwordx4 v[136:139], v[88:89], off offset:1152
	ds_read_b128 v[212:215], v245 offset:55296
	ds_read_b128 v[196:199], v244 offset:18432
	ds_read_b128 v[216:219], v245 offset:57600
	ds_read_b128 v[220:223], v245 offset:59904
	ds_read_b128 v[224:227], v245 offset:62208
	ds_read_b128 v[200:203], v244 offset:20736
	ds_read_b128 v[204:207], v244 offset:23040
	ds_read_b128 v[208:211], v244 offset:25344
	s_waitcnt lgkmcnt(6)
	v_mfma_f32_16x16x32_bf16 v[50:53], v[196:199], v[212:215], v[50:53]
	ds_read_b128 v[228:231], v245 offset:55360
	s_waitcnt lgkmcnt(6)
	v_mfma_f32_16x16x32_bf16 v[54:57], v[196:199], v[216:219], v[54:57]
	ds_read_b128 v[232:235], v245 offset:57664
	s_waitcnt lgkmcnt(6)
	v_mfma_f32_16x16x32_bf16 v[18:21], v[196:199], v[220:223], v[18:21]
	ds_read_b128 v[236:239], v245 offset:59968
	s_waitcnt lgkmcnt(6)
	v_mfma_f32_16x16x32_bf16 v[22:25], v[196:199], v[224:227], v[22:25]
	ds_read_b128 v[240:243], v245 offset:62272
	ds_read_b128 v[196:199], v244 offset:18496
	s_waitcnt lgkmcnt(7)
	v_mfma_f32_16x16x32_bf16 v[58:61], v[200:203], v[212:215], v[58:61]
	v_mfma_f32_16x16x32_bf16 v[62:65], v[200:203], v[216:219], v[62:65]
	v_mfma_f32_16x16x32_bf16 v[26:29], v[200:203], v[220:223], v[26:29]
	v_mfma_f32_16x16x32_bf16 v[30:33], v[200:203], v[224:227], v[30:33]
	ds_read_b128 v[200:203], v244 offset:20800
	s_waitcnt lgkmcnt(7)
	v_mfma_f32_16x16x32_bf16 v[34:37], v[204:207], v[212:215], v[34:37]
	v_mfma_f32_16x16x32_bf16 v[38:41], v[204:207], v[216:219], v[38:41]
	v_mfma_f32_16x16x32_bf16 v[2:5], v[204:207], v[220:223], v[2:5]
	v_mfma_f32_16x16x32_bf16 v[6:9], v[204:207], v[224:227], v[6:9]
	ds_read_b128 v[204:207], v244 offset:23104
	s_waitcnt lgkmcnt(7)
	v_mfma_f32_16x16x32_bf16 v[42:45], v[208:211], v[212:215], v[42:45]
	v_mfma_f32_16x16x32_bf16 v[46:49], v[208:211], v[216:219], v[46:49]
	v_mfma_f32_16x16x32_bf16 v[10:13], v[208:211], v[220:223], v[10:13]
	v_mfma_f32_16x16x32_bf16 v[14:17], v[208:211], v[224:227], v[14:17]
	ds_read_b128 v[208:211], v244 offset:25408
	s_waitcnt lgkmcnt(3)
	v_mfma_f32_16x16x32_bf16 v[50:53], v[196:199], v[228:231], v[50:53]
	v_mfma_f32_16x16x32_bf16 v[54:57], v[196:199], v[232:235], v[54:57]
	v_mfma_f32_16x16x32_bf16 v[18:21], v[196:199], v[236:239], v[18:21]
	v_mfma_f32_16x16x32_bf16 v[22:25], v[196:199], v[240:243], v[22:25]
	s_waitcnt vmcnt(15)
	ds_write_b128 v98, v[140:143]
	s_waitcnt vmcnt(14)
	ds_write_b128 v98, v[144:147] offset:4608
	s_waitcnt lgkmcnt(4)
	v_mfma_f32_16x16x32_bf16 v[58:61], v[200:203], v[228:231], v[58:61]
	v_mfma_f32_16x16x32_bf16 v[62:65], v[200:203], v[232:235], v[62:65]
	v_mfma_f32_16x16x32_bf16 v[26:29], v[200:203], v[236:239], v[26:29]
	v_mfma_f32_16x16x32_bf16 v[30:33], v[200:203], v[240:243], v[30:33]
	s_waitcnt vmcnt(13)
	ds_write_b128 v98, v[148:151] offset:9216
	s_waitcnt vmcnt(12)
	ds_write_b128 v98, v[152:155] offset:13824
	s_waitcnt lgkmcnt(5)
	v_mfma_f32_16x16x32_bf16 v[34:37], v[204:207], v[228:231], v[34:37]
	v_mfma_f32_16x16x32_bf16 v[38:41], v[204:207], v[232:235], v[38:41]
	v_mfma_f32_16x16x32_bf16 v[2:5], v[204:207], v[236:239], v[2:5]
	v_mfma_f32_16x16x32_bf16 v[6:9], v[204:207], v[240:243], v[6:9]
	s_waitcnt vmcnt(11)
	ds_write_b128 v98, v[156:159] offset:36864
	s_waitcnt vmcnt(10)
	ds_write_b128 v98, v[160:163] offset:41472
	s_waitcnt lgkmcnt(6)
	v_mfma_f32_16x16x32_bf16 v[42:45], v[208:211], v[228:231], v[42:45]
	v_mfma_f32_16x16x32_bf16 v[46:49], v[208:211], v[232:235], v[46:49]
	v_mfma_f32_16x16x32_bf16 v[10:13], v[208:211], v[236:239], v[10:13]
	v_mfma_f32_16x16x32_bf16 v[14:17], v[208:211], v[240:243], v[14:17]
	s_waitcnt vmcnt(9)
	ds_write_b128 v98, v[164:167] offset:46080
	s_waitcnt vmcnt(8)
	ds_write_b128 v98, v[168:171] offset:50688
	s_waitcnt lgkmcnt(0)
	s_barrier
	global_load_dwordx4 v[140:143], v[74:75], off offset:1280
	global_load_dwordx4 v[144:147], v[76:77], off offset:1280
	global_load_dwordx4 v[148:151], v[78:79], off offset:1280
	global_load_dwordx4 v[152:155], v[80:81], off offset:1280
	global_load_dwordx4 v[156:159], v[82:83], off offset:1280
	global_load_dwordx4 v[160:163], v[84:85], off offset:1280
	global_load_dwordx4 v[164:167], v[86:87], off offset:1280
	global_load_dwordx4 v[168:171], v[88:89], off offset:1280
	ds_read_b128 v[212:215], v245 offset:36864
	ds_read_b128 v[196:199], v244
	ds_read_b128 v[216:219], v245 offset:39168
	ds_read_b128 v[220:223], v245 offset:41472
	ds_read_b128 v[224:227], v245 offset:43776
	ds_read_b128 v[200:203], v244 offset:2304
	ds_read_b128 v[204:207], v244 offset:4608
	ds_read_b128 v[208:211], v244 offset:6912
	s_waitcnt lgkmcnt(6)
	v_mfma_f32_16x16x32_bf16 v[50:53], v[196:199], v[212:215], v[50:53]
	ds_read_b128 v[228:231], v245 offset:36928
	s_waitcnt lgkmcnt(6)
	v_mfma_f32_16x16x32_bf16 v[54:57], v[196:199], v[216:219], v[54:57]
	ds_read_b128 v[232:235], v245 offset:39232
	s_waitcnt lgkmcnt(6)
	v_mfma_f32_16x16x32_bf16 v[18:21], v[196:199], v[220:223], v[18:21]
	ds_read_b128 v[236:239], v245 offset:41536
	s_waitcnt lgkmcnt(6)
	v_mfma_f32_16x16x32_bf16 v[22:25], v[196:199], v[224:227], v[22:25]
	ds_read_b128 v[240:243], v245 offset:43840
	ds_read_b128 v[196:199], v244 offset:64
	s_waitcnt lgkmcnt(7)
	v_mfma_f32_16x16x32_bf16 v[58:61], v[200:203], v[212:215], v[58:61]
	v_mfma_f32_16x16x32_bf16 v[62:65], v[200:203], v[216:219], v[62:65]
	v_mfma_f32_16x16x32_bf16 v[26:29], v[200:203], v[220:223], v[26:29]
	v_mfma_f32_16x16x32_bf16 v[30:33], v[200:203], v[224:227], v[30:33]
	ds_read_b128 v[200:203], v244 offset:2368
	s_waitcnt lgkmcnt(7)
	v_mfma_f32_16x16x32_bf16 v[34:37], v[204:207], v[212:215], v[34:37]
	v_mfma_f32_16x16x32_bf16 v[38:41], v[204:207], v[216:219], v[38:41]
	v_mfma_f32_16x16x32_bf16 v[2:5], v[204:207], v[220:223], v[2:5]
	v_mfma_f32_16x16x32_bf16 v[6:9], v[204:207], v[224:227], v[6:9]
	ds_read_b128 v[204:207], v244 offset:4672
	s_waitcnt lgkmcnt(7)
	v_mfma_f32_16x16x32_bf16 v[42:45], v[208:211], v[212:215], v[42:45]
	v_mfma_f32_16x16x32_bf16 v[46:49], v[208:211], v[216:219], v[46:49]
	v_mfma_f32_16x16x32_bf16 v[10:13], v[208:211], v[220:223], v[10:13]
	v_mfma_f32_16x16x32_bf16 v[14:17], v[208:211], v[224:227], v[14:17]
	ds_read_b128 v[208:211], v244 offset:6976
	s_waitcnt lgkmcnt(3)
	v_mfma_f32_16x16x32_bf16 v[50:53], v[196:199], v[228:231], v[50:53]
	v_mfma_f32_16x16x32_bf16 v[54:57], v[196:199], v[232:235], v[54:57]
	v_mfma_f32_16x16x32_bf16 v[18:21], v[196:199], v[236:239], v[18:21]
	v_mfma_f32_16x16x32_bf16 v[22:25], v[196:199], v[240:243], v[22:25]
	s_waitcnt vmcnt(15)
	ds_write_b128 v98, v[102:105] offset:18432
	s_waitcnt vmcnt(14)
	ds_write_b128 v98, v[106:109] offset:23040
	s_waitcnt lgkmcnt(4)
	v_mfma_f32_16x16x32_bf16 v[58:61], v[200:203], v[228:231], v[58:61]
	v_mfma_f32_16x16x32_bf16 v[62:65], v[200:203], v[232:235], v[62:65]
	v_mfma_f32_16x16x32_bf16 v[26:29], v[200:203], v[236:239], v[26:29]
	v_mfma_f32_16x16x32_bf16 v[30:33], v[200:203], v[240:243], v[30:33]
	s_waitcnt vmcnt(13)
	ds_write_b128 v98, v[110:113] offset:27648
	s_waitcnt vmcnt(12)
	ds_write_b128 v98, v[114:117] offset:32256
	s_waitcnt lgkmcnt(5)
	v_mfma_f32_16x16x32_bf16 v[34:37], v[204:207], v[228:231], v[34:37]
	v_mfma_f32_16x16x32_bf16 v[38:41], v[204:207], v[232:235], v[38:41]
	v_mfma_f32_16x16x32_bf16 v[2:5], v[204:207], v[236:239], v[2:5]
	v_mfma_f32_16x16x32_bf16 v[6:9], v[204:207], v[240:243], v[6:9]
	s_waitcnt vmcnt(11)
	ds_write_b128 v98, v[118:121] offset:55296
	s_waitcnt vmcnt(10)
	ds_write_b128 v98, v[122:125] offset:59904
	s_waitcnt lgkmcnt(6)
	v_mfma_f32_16x16x32_bf16 v[42:45], v[208:211], v[228:231], v[42:45]
	v_mfma_f32_16x16x32_bf16 v[46:49], v[208:211], v[232:235], v[46:49]
	v_mfma_f32_16x16x32_bf16 v[10:13], v[208:211], v[236:239], v[10:13]
	v_mfma_f32_16x16x32_bf16 v[14:17], v[208:211], v[240:243], v[14:17]
	s_waitcnt vmcnt(9)
	ds_write_b128 v98, v[126:129] offset:64512
	s_waitcnt vmcnt(8)
	ds_write_b128 v99, v[136:139] offset:32256
	s_waitcnt lgkmcnt(0)
	s_barrier
	global_load_dwordx4 v[102:105], v[74:75], off offset:1408
	global_load_dwordx4 v[106:109], v[76:77], off offset:1408
	global_load_dwordx4 v[110:113], v[78:79], off offset:1408
	global_load_dwordx4 v[114:117], v[80:81], off offset:1408
	global_load_dwordx4 v[118:121], v[82:83], off offset:1408
	global_load_dwordx4 v[122:125], v[84:85], off offset:1408
	global_load_dwordx4 v[126:129], v[86:87], off offset:1408
	global_load_dwordx4 v[136:139], v[88:89], off offset:1408
	ds_read_b128 v[212:215], v245 offset:55296
	ds_read_b128 v[196:199], v244 offset:18432
	ds_read_b128 v[216:219], v245 offset:57600
	ds_read_b128 v[220:223], v245 offset:59904
	ds_read_b128 v[224:227], v245 offset:62208
	ds_read_b128 v[200:203], v244 offset:20736
	ds_read_b128 v[204:207], v244 offset:23040
	ds_read_b128 v[208:211], v244 offset:25344
	s_waitcnt lgkmcnt(6)
	v_mfma_f32_16x16x32_bf16 v[50:53], v[196:199], v[212:215], v[50:53]
	ds_read_b128 v[228:231], v245 offset:55360
	s_waitcnt lgkmcnt(6)
	v_mfma_f32_16x16x32_bf16 v[54:57], v[196:199], v[216:219], v[54:57]
	ds_read_b128 v[232:235], v245 offset:57664
	s_waitcnt lgkmcnt(6)
	v_mfma_f32_16x16x32_bf16 v[18:21], v[196:199], v[220:223], v[18:21]
	ds_read_b128 v[236:239], v245 offset:59968
	s_waitcnt lgkmcnt(6)
	v_mfma_f32_16x16x32_bf16 v[22:25], v[196:199], v[224:227], v[22:25]
	ds_read_b128 v[240:243], v245 offset:62272
	ds_read_b128 v[196:199], v244 offset:18496
	s_waitcnt lgkmcnt(7)
	v_mfma_f32_16x16x32_bf16 v[58:61], v[200:203], v[212:215], v[58:61]
	v_mfma_f32_16x16x32_bf16 v[62:65], v[200:203], v[216:219], v[62:65]
	v_mfma_f32_16x16x32_bf16 v[26:29], v[200:203], v[220:223], v[26:29]
	v_mfma_f32_16x16x32_bf16 v[30:33], v[200:203], v[224:227], v[30:33]
	ds_read_b128 v[200:203], v244 offset:20800
	s_waitcnt lgkmcnt(7)
	v_mfma_f32_16x16x32_bf16 v[34:37], v[204:207], v[212:215], v[34:37]
	v_mfma_f32_16x16x32_bf16 v[38:41], v[204:207], v[216:219], v[38:41]
	v_mfma_f32_16x16x32_bf16 v[2:5], v[204:207], v[220:223], v[2:5]
	v_mfma_f32_16x16x32_bf16 v[6:9], v[204:207], v[224:227], v[6:9]
	ds_read_b128 v[204:207], v244 offset:23104
	s_waitcnt lgkmcnt(7)
	v_mfma_f32_16x16x32_bf16 v[42:45], v[208:211], v[212:215], v[42:45]
	v_mfma_f32_16x16x32_bf16 v[46:49], v[208:211], v[216:219], v[46:49]
	v_mfma_f32_16x16x32_bf16 v[10:13], v[208:211], v[220:223], v[10:13]
	v_mfma_f32_16x16x32_bf16 v[14:17], v[208:211], v[224:227], v[14:17]
	ds_read_b128 v[208:211], v244 offset:25408
	s_waitcnt lgkmcnt(3)
	v_mfma_f32_16x16x32_bf16 v[50:53], v[196:199], v[228:231], v[50:53]
	v_mfma_f32_16x16x32_bf16 v[54:57], v[196:199], v[232:235], v[54:57]
	v_mfma_f32_16x16x32_bf16 v[18:21], v[196:199], v[236:239], v[18:21]
	v_mfma_f32_16x16x32_bf16 v[22:25], v[196:199], v[240:243], v[22:25]
	s_waitcnt vmcnt(15)
	ds_write_b128 v98, v[140:143]
	s_waitcnt vmcnt(14)
	ds_write_b128 v98, v[144:147] offset:4608
	s_waitcnt lgkmcnt(4)
	v_mfma_f32_16x16x32_bf16 v[58:61], v[200:203], v[228:231], v[58:61]
	v_mfma_f32_16x16x32_bf16 v[62:65], v[200:203], v[232:235], v[62:65]
	v_mfma_f32_16x16x32_bf16 v[26:29], v[200:203], v[236:239], v[26:29]
	v_mfma_f32_16x16x32_bf16 v[30:33], v[200:203], v[240:243], v[30:33]
	s_waitcnt vmcnt(13)
	ds_write_b128 v98, v[148:151] offset:9216
	s_waitcnt vmcnt(12)
	ds_write_b128 v98, v[152:155] offset:13824
	s_waitcnt lgkmcnt(5)
	v_mfma_f32_16x16x32_bf16 v[34:37], v[204:207], v[228:231], v[34:37]
	v_mfma_f32_16x16x32_bf16 v[38:41], v[204:207], v[232:235], v[38:41]
	v_mfma_f32_16x16x32_bf16 v[2:5], v[204:207], v[236:239], v[2:5]
	v_mfma_f32_16x16x32_bf16 v[6:9], v[204:207], v[240:243], v[6:9]
	s_waitcnt vmcnt(11)
	ds_write_b128 v98, v[156:159] offset:36864
	s_waitcnt vmcnt(10)
	ds_write_b128 v98, v[160:163] offset:41472
	s_waitcnt lgkmcnt(6)
	v_mfma_f32_16x16x32_bf16 v[42:45], v[208:211], v[228:231], v[42:45]
	v_mfma_f32_16x16x32_bf16 v[46:49], v[208:211], v[232:235], v[46:49]
	v_mfma_f32_16x16x32_bf16 v[10:13], v[208:211], v[236:239], v[10:13]
	v_mfma_f32_16x16x32_bf16 v[14:17], v[208:211], v[240:243], v[14:17]
	s_waitcnt vmcnt(9)
	ds_write_b128 v98, v[164:167] offset:46080
	s_waitcnt vmcnt(8)
	ds_write_b128 v98, v[168:171] offset:50688
	s_waitcnt lgkmcnt(0)
	s_barrier
	global_load_dwordx4 v[140:143], v[74:75], off offset:1536
	global_load_dwordx4 v[144:147], v[76:77], off offset:1536
	global_load_dwordx4 v[148:151], v[78:79], off offset:1536
	global_load_dwordx4 v[152:155], v[80:81], off offset:1536
	global_load_dwordx4 v[156:159], v[82:83], off offset:1536
	global_load_dwordx4 v[160:163], v[84:85], off offset:1536
	global_load_dwordx4 v[164:167], v[86:87], off offset:1536
	global_load_dwordx4 v[168:171], v[88:89], off offset:1536
	ds_read_b128 v[212:215], v245 offset:36864
	ds_read_b128 v[196:199], v244
	ds_read_b128 v[216:219], v245 offset:39168
	ds_read_b128 v[220:223], v245 offset:41472
	ds_read_b128 v[224:227], v245 offset:43776
	ds_read_b128 v[200:203], v244 offset:2304
	ds_read_b128 v[204:207], v244 offset:4608
	ds_read_b128 v[208:211], v244 offset:6912
	s_waitcnt lgkmcnt(6)
	v_mfma_f32_16x16x32_bf16 v[50:53], v[196:199], v[212:215], v[50:53]
	ds_read_b128 v[228:231], v245 offset:36928
	s_waitcnt lgkmcnt(6)
	v_mfma_f32_16x16x32_bf16 v[54:57], v[196:199], v[216:219], v[54:57]
	ds_read_b128 v[232:235], v245 offset:39232
	s_waitcnt lgkmcnt(6)
	v_mfma_f32_16x16x32_bf16 v[18:21], v[196:199], v[220:223], v[18:21]
	ds_read_b128 v[236:239], v245 offset:41536
	s_waitcnt lgkmcnt(6)
	v_mfma_f32_16x16x32_bf16 v[22:25], v[196:199], v[224:227], v[22:25]
	ds_read_b128 v[240:243], v245 offset:43840
	ds_read_b128 v[196:199], v244 offset:64
	s_waitcnt lgkmcnt(7)
	v_mfma_f32_16x16x32_bf16 v[58:61], v[200:203], v[212:215], v[58:61]
	v_mfma_f32_16x16x32_bf16 v[62:65], v[200:203], v[216:219], v[62:65]
	v_mfma_f32_16x16x32_bf16 v[26:29], v[200:203], v[220:223], v[26:29]
	v_mfma_f32_16x16x32_bf16 v[30:33], v[200:203], v[224:227], v[30:33]
	ds_read_b128 v[200:203], v244 offset:2368
	s_waitcnt lgkmcnt(7)
	v_mfma_f32_16x16x32_bf16 v[34:37], v[204:207], v[212:215], v[34:37]
	v_mfma_f32_16x16x32_bf16 v[38:41], v[204:207], v[216:219], v[38:41]
	v_mfma_f32_16x16x32_bf16 v[2:5], v[204:207], v[220:223], v[2:5]
	v_mfma_f32_16x16x32_bf16 v[6:9], v[204:207], v[224:227], v[6:9]
	ds_read_b128 v[204:207], v244 offset:4672
	s_waitcnt lgkmcnt(7)
	v_mfma_f32_16x16x32_bf16 v[42:45], v[208:211], v[212:215], v[42:45]
	v_mfma_f32_16x16x32_bf16 v[46:49], v[208:211], v[216:219], v[46:49]
	v_mfma_f32_16x16x32_bf16 v[10:13], v[208:211], v[220:223], v[10:13]
	v_mfma_f32_16x16x32_bf16 v[14:17], v[208:211], v[224:227], v[14:17]
	ds_read_b128 v[208:211], v244 offset:6976
	s_waitcnt lgkmcnt(3)
	v_mfma_f32_16x16x32_bf16 v[50:53], v[196:199], v[228:231], v[50:53]
	v_mfma_f32_16x16x32_bf16 v[54:57], v[196:199], v[232:235], v[54:57]
	v_mfma_f32_16x16x32_bf16 v[18:21], v[196:199], v[236:239], v[18:21]
	v_mfma_f32_16x16x32_bf16 v[22:25], v[196:199], v[240:243], v[22:25]
	s_waitcnt vmcnt(15)
	ds_write_b128 v98, v[102:105] offset:18432
	s_waitcnt vmcnt(14)
	ds_write_b128 v98, v[106:109] offset:23040
	s_waitcnt lgkmcnt(4)
	v_mfma_f32_16x16x32_bf16 v[58:61], v[200:203], v[228:231], v[58:61]
	v_mfma_f32_16x16x32_bf16 v[62:65], v[200:203], v[232:235], v[62:65]
	v_mfma_f32_16x16x32_bf16 v[26:29], v[200:203], v[236:239], v[26:29]
	v_mfma_f32_16x16x32_bf16 v[30:33], v[200:203], v[240:243], v[30:33]
	s_waitcnt vmcnt(13)
	ds_write_b128 v98, v[110:113] offset:27648
	s_waitcnt vmcnt(12)
	ds_write_b128 v98, v[114:117] offset:32256
	s_waitcnt lgkmcnt(5)
	v_mfma_f32_16x16x32_bf16 v[34:37], v[204:207], v[228:231], v[34:37]
	v_mfma_f32_16x16x32_bf16 v[38:41], v[204:207], v[232:235], v[38:41]
	v_mfma_f32_16x16x32_bf16 v[2:5], v[204:207], v[236:239], v[2:5]
	v_mfma_f32_16x16x32_bf16 v[6:9], v[204:207], v[240:243], v[6:9]
	s_waitcnt vmcnt(11)
	ds_write_b128 v98, v[118:121] offset:55296
	s_waitcnt vmcnt(10)
	ds_write_b128 v98, v[122:125] offset:59904
	s_waitcnt lgkmcnt(6)
	v_mfma_f32_16x16x32_bf16 v[42:45], v[208:211], v[228:231], v[42:45]
	v_mfma_f32_16x16x32_bf16 v[46:49], v[208:211], v[232:235], v[46:49]
	v_mfma_f32_16x16x32_bf16 v[10:13], v[208:211], v[236:239], v[10:13]
	v_mfma_f32_16x16x32_bf16 v[14:17], v[208:211], v[240:243], v[14:17]
	s_waitcnt vmcnt(9)
	ds_write_b128 v98, v[126:129] offset:64512
	s_waitcnt vmcnt(8)
	ds_write_b128 v99, v[136:139] offset:32256
	s_waitcnt lgkmcnt(0)
	s_barrier
	global_load_dwordx4 v[102:105], v[74:75], off offset:1664
	global_load_dwordx4 v[106:109], v[76:77], off offset:1664
	global_load_dwordx4 v[110:113], v[78:79], off offset:1664
	global_load_dwordx4 v[114:117], v[80:81], off offset:1664
	global_load_dwordx4 v[118:121], v[82:83], off offset:1664
	global_load_dwordx4 v[122:125], v[84:85], off offset:1664
	global_load_dwordx4 v[126:129], v[86:87], off offset:1664
	global_load_dwordx4 v[136:139], v[88:89], off offset:1664
	ds_read_b128 v[212:215], v245 offset:55296
	ds_read_b128 v[196:199], v244 offset:18432
	ds_read_b128 v[216:219], v245 offset:57600
	ds_read_b128 v[220:223], v245 offset:59904
	ds_read_b128 v[224:227], v245 offset:62208
	ds_read_b128 v[200:203], v244 offset:20736
	ds_read_b128 v[204:207], v244 offset:23040
	ds_read_b128 v[208:211], v244 offset:25344
	s_waitcnt lgkmcnt(6)
	v_mfma_f32_16x16x32_bf16 v[50:53], v[196:199], v[212:215], v[50:53]
	ds_read_b128 v[228:231], v245 offset:55360
	s_waitcnt lgkmcnt(6)
	v_mfma_f32_16x16x32_bf16 v[54:57], v[196:199], v[216:219], v[54:57]
	ds_read_b128 v[232:235], v245 offset:57664
	s_waitcnt lgkmcnt(6)
	v_mfma_f32_16x16x32_bf16 v[18:21], v[196:199], v[220:223], v[18:21]
	ds_read_b128 v[236:239], v245 offset:59968
	s_waitcnt lgkmcnt(6)
	v_mfma_f32_16x16x32_bf16 v[22:25], v[196:199], v[224:227], v[22:25]
	ds_read_b128 v[240:243], v245 offset:62272
	ds_read_b128 v[196:199], v244 offset:18496
	s_waitcnt lgkmcnt(7)
	v_mfma_f32_16x16x32_bf16 v[58:61], v[200:203], v[212:215], v[58:61]
	v_mfma_f32_16x16x32_bf16 v[62:65], v[200:203], v[216:219], v[62:65]
	v_mfma_f32_16x16x32_bf16 v[26:29], v[200:203], v[220:223], v[26:29]
	v_mfma_f32_16x16x32_bf16 v[30:33], v[200:203], v[224:227], v[30:33]
	ds_read_b128 v[200:203], v244 offset:20800
	s_waitcnt lgkmcnt(7)
	v_mfma_f32_16x16x32_bf16 v[34:37], v[204:207], v[212:215], v[34:37]
	v_mfma_f32_16x16x32_bf16 v[38:41], v[204:207], v[216:219], v[38:41]
	v_mfma_f32_16x16x32_bf16 v[2:5], v[204:207], v[220:223], v[2:5]
	v_mfma_f32_16x16x32_bf16 v[6:9], v[204:207], v[224:227], v[6:9]
	ds_read_b128 v[204:207], v244 offset:23104
	s_waitcnt lgkmcnt(7)
	v_mfma_f32_16x16x32_bf16 v[42:45], v[208:211], v[212:215], v[42:45]
	v_mfma_f32_16x16x32_bf16 v[46:49], v[208:211], v[216:219], v[46:49]
	v_mfma_f32_16x16x32_bf16 v[10:13], v[208:211], v[220:223], v[10:13]
	v_mfma_f32_16x16x32_bf16 v[14:17], v[208:211], v[224:227], v[14:17]
	ds_read_b128 v[208:211], v244 offset:25408
	s_waitcnt lgkmcnt(3)
	v_mfma_f32_16x16x32_bf16 v[50:53], v[196:199], v[228:231], v[50:53]
	v_mfma_f32_16x16x32_bf16 v[54:57], v[196:199], v[232:235], v[54:57]
	v_mfma_f32_16x16x32_bf16 v[18:21], v[196:199], v[236:239], v[18:21]
	v_mfma_f32_16x16x32_bf16 v[22:25], v[196:199], v[240:243], v[22:25]
	s_waitcnt vmcnt(15)
	ds_write_b128 v98, v[140:143]
	s_waitcnt vmcnt(14)
	ds_write_b128 v98, v[144:147] offset:4608
	s_waitcnt lgkmcnt(4)
	v_mfma_f32_16x16x32_bf16 v[58:61], v[200:203], v[228:231], v[58:61]
	v_mfma_f32_16x16x32_bf16 v[62:65], v[200:203], v[232:235], v[62:65]
	v_mfma_f32_16x16x32_bf16 v[26:29], v[200:203], v[236:239], v[26:29]
	v_mfma_f32_16x16x32_bf16 v[30:33], v[200:203], v[240:243], v[30:33]
	s_waitcnt vmcnt(13)
	ds_write_b128 v98, v[148:151] offset:9216
	s_waitcnt vmcnt(12)
	ds_write_b128 v98, v[152:155] offset:13824
	s_waitcnt lgkmcnt(5)
	v_mfma_f32_16x16x32_bf16 v[34:37], v[204:207], v[228:231], v[34:37]
	v_mfma_f32_16x16x32_bf16 v[38:41], v[204:207], v[232:235], v[38:41]
	v_mfma_f32_16x16x32_bf16 v[2:5], v[204:207], v[236:239], v[2:5]
	v_mfma_f32_16x16x32_bf16 v[6:9], v[204:207], v[240:243], v[6:9]
	s_waitcnt vmcnt(11)
	ds_write_b128 v98, v[156:159] offset:36864
	s_waitcnt vmcnt(10)
	ds_write_b128 v98, v[160:163] offset:41472
	s_waitcnt lgkmcnt(6)
	v_mfma_f32_16x16x32_bf16 v[42:45], v[208:211], v[228:231], v[42:45]
	v_mfma_f32_16x16x32_bf16 v[46:49], v[208:211], v[232:235], v[46:49]
	v_mfma_f32_16x16x32_bf16 v[10:13], v[208:211], v[236:239], v[10:13]
	v_mfma_f32_16x16x32_bf16 v[14:17], v[208:211], v[240:243], v[14:17]
	s_waitcnt vmcnt(9)
	ds_write_b128 v98, v[164:167] offset:46080
	s_waitcnt vmcnt(8)
	ds_write_b128 v98, v[168:171] offset:50688
	s_waitcnt lgkmcnt(0)
	s_barrier
	global_load_dwordx4 v[140:143], v[74:75], off offset:1792
	global_load_dwordx4 v[144:147], v[76:77], off offset:1792
	global_load_dwordx4 v[148:151], v[78:79], off offset:1792
	global_load_dwordx4 v[152:155], v[80:81], off offset:1792
	global_load_dwordx4 v[156:159], v[82:83], off offset:1792
	global_load_dwordx4 v[160:163], v[84:85], off offset:1792
	global_load_dwordx4 v[164:167], v[86:87], off offset:1792
	global_load_dwordx4 v[168:171], v[88:89], off offset:1792
	ds_read_b128 v[212:215], v245 offset:36864
	ds_read_b128 v[196:199], v244
	ds_read_b128 v[216:219], v245 offset:39168
	ds_read_b128 v[220:223], v245 offset:41472
	ds_read_b128 v[224:227], v245 offset:43776
	ds_read_b128 v[200:203], v244 offset:2304
	ds_read_b128 v[204:207], v244 offset:4608
	ds_read_b128 v[208:211], v244 offset:6912
	s_waitcnt lgkmcnt(6)
	v_mfma_f32_16x16x32_bf16 v[50:53], v[196:199], v[212:215], v[50:53]
	ds_read_b128 v[228:231], v245 offset:36928
	s_waitcnt lgkmcnt(6)
	v_mfma_f32_16x16x32_bf16 v[54:57], v[196:199], v[216:219], v[54:57]
	ds_read_b128 v[232:235], v245 offset:39232
	s_waitcnt lgkmcnt(6)
	v_mfma_f32_16x16x32_bf16 v[18:21], v[196:199], v[220:223], v[18:21]
	ds_read_b128 v[236:239], v245 offset:41536
	s_waitcnt lgkmcnt(6)
	v_mfma_f32_16x16x32_bf16 v[22:25], v[196:199], v[224:227], v[22:25]
	ds_read_b128 v[240:243], v245 offset:43840
	ds_read_b128 v[196:199], v244 offset:64
	s_waitcnt lgkmcnt(7)
	v_mfma_f32_16x16x32_bf16 v[58:61], v[200:203], v[212:215], v[58:61]
	v_mfma_f32_16x16x32_bf16 v[62:65], v[200:203], v[216:219], v[62:65]
	v_mfma_f32_16x16x32_bf16 v[26:29], v[200:203], v[220:223], v[26:29]
	v_mfma_f32_16x16x32_bf16 v[30:33], v[200:203], v[224:227], v[30:33]
	ds_read_b128 v[200:203], v244 offset:2368
	s_waitcnt lgkmcnt(7)
	v_mfma_f32_16x16x32_bf16 v[34:37], v[204:207], v[212:215], v[34:37]
	v_mfma_f32_16x16x32_bf16 v[38:41], v[204:207], v[216:219], v[38:41]
	v_mfma_f32_16x16x32_bf16 v[2:5], v[204:207], v[220:223], v[2:5]
	v_mfma_f32_16x16x32_bf16 v[6:9], v[204:207], v[224:227], v[6:9]
	ds_read_b128 v[204:207], v244 offset:4672
	s_waitcnt lgkmcnt(7)
	v_mfma_f32_16x16x32_bf16 v[42:45], v[208:211], v[212:215], v[42:45]
	v_mfma_f32_16x16x32_bf16 v[46:49], v[208:211], v[216:219], v[46:49]
	v_mfma_f32_16x16x32_bf16 v[10:13], v[208:211], v[220:223], v[10:13]
	v_mfma_f32_16x16x32_bf16 v[14:17], v[208:211], v[224:227], v[14:17]
	ds_read_b128 v[208:211], v244 offset:6976
	s_waitcnt lgkmcnt(3)
	v_mfma_f32_16x16x32_bf16 v[50:53], v[196:199], v[228:231], v[50:53]
	v_mfma_f32_16x16x32_bf16 v[54:57], v[196:199], v[232:235], v[54:57]
	v_mfma_f32_16x16x32_bf16 v[18:21], v[196:199], v[236:239], v[18:21]
	v_mfma_f32_16x16x32_bf16 v[22:25], v[196:199], v[240:243], v[22:25]
	s_waitcnt vmcnt(15)
	ds_write_b128 v98, v[102:105] offset:18432
	s_waitcnt vmcnt(14)
	ds_write_b128 v98, v[106:109] offset:23040
	s_waitcnt lgkmcnt(4)
	v_mfma_f32_16x16x32_bf16 v[58:61], v[200:203], v[228:231], v[58:61]
	v_mfma_f32_16x16x32_bf16 v[62:65], v[200:203], v[232:235], v[62:65]
	v_mfma_f32_16x16x32_bf16 v[26:29], v[200:203], v[236:239], v[26:29]
	v_mfma_f32_16x16x32_bf16 v[30:33], v[200:203], v[240:243], v[30:33]
	s_waitcnt vmcnt(13)
	ds_write_b128 v98, v[110:113] offset:27648
	s_waitcnt vmcnt(12)
	ds_write_b128 v98, v[114:117] offset:32256
	s_waitcnt lgkmcnt(5)
	v_mfma_f32_16x16x32_bf16 v[34:37], v[204:207], v[228:231], v[34:37]
	v_mfma_f32_16x16x32_bf16 v[38:41], v[204:207], v[232:235], v[38:41]
	v_mfma_f32_16x16x32_bf16 v[2:5], v[204:207], v[236:239], v[2:5]
	v_mfma_f32_16x16x32_bf16 v[6:9], v[204:207], v[240:243], v[6:9]
	s_waitcnt vmcnt(11)
	ds_write_b128 v98, v[118:121] offset:55296
	s_waitcnt vmcnt(10)
	ds_write_b128 v98, v[122:125] offset:59904
	s_waitcnt lgkmcnt(6)
	v_mfma_f32_16x16x32_bf16 v[42:45], v[208:211], v[228:231], v[42:45]
	v_mfma_f32_16x16x32_bf16 v[46:49], v[208:211], v[232:235], v[46:49]
	v_mfma_f32_16x16x32_bf16 v[10:13], v[208:211], v[236:239], v[10:13]
	v_mfma_f32_16x16x32_bf16 v[14:17], v[208:211], v[240:243], v[14:17]
	s_waitcnt vmcnt(9)
	ds_write_b128 v98, v[126:129] offset:64512
	s_waitcnt vmcnt(8)
	ds_write_b128 v99, v[136:139] offset:32256
	s_waitcnt lgkmcnt(0)
	s_barrier
	global_load_dwordx4 v[102:105], v[74:75], off offset:1920
	s_nop 0
	global_load_dwordx4 v[74:77], v[76:77], off offset:1920
	s_nop 0
	global_load_dwordx4 v[106:109], v[78:79], off offset:1920
	s_nop 0
	global_load_dwordx4 v[78:81], v[80:81], off offset:1920
	s_nop 0
	global_load_dwordx4 v[110:113], v[82:83], off offset:1920
	s_nop 0
	global_load_dwordx4 v[82:85], v[84:85], off offset:1920
	s_nop 0
	global_load_dwordx4 v[114:117], v[86:87], off offset:1920
	s_nop 0
	global_load_dwordx4 v[86:89], v[88:89], off offset:1920
	ds_read_b128 v[212:215], v245 offset:55296
	ds_read_b128 v[196:199], v244 offset:18432
	ds_read_b128 v[216:219], v245 offset:57600
	ds_read_b128 v[220:223], v245 offset:59904
	ds_read_b128 v[224:227], v245 offset:62208
	ds_read_b128 v[200:203], v244 offset:20736
	ds_read_b128 v[204:207], v244 offset:23040
	ds_read_b128 v[208:211], v244 offset:25344
	s_waitcnt lgkmcnt(6)
	v_mfma_f32_16x16x32_bf16 v[50:53], v[196:199], v[212:215], v[50:53]
	ds_read_b128 v[228:231], v245 offset:55360
	s_waitcnt lgkmcnt(6)
	v_mfma_f32_16x16x32_bf16 v[54:57], v[196:199], v[216:219], v[54:57]
	ds_read_b128 v[232:235], v245 offset:57664
	s_waitcnt lgkmcnt(6)
	v_mfma_f32_16x16x32_bf16 v[18:21], v[196:199], v[220:223], v[18:21]
	ds_read_b128 v[236:239], v245 offset:59968
	s_waitcnt lgkmcnt(6)
	v_mfma_f32_16x16x32_bf16 v[22:25], v[196:199], v[224:227], v[22:25]
	ds_read_b128 v[240:243], v245 offset:62272
	ds_read_b128 v[196:199], v244 offset:18496
	s_waitcnt lgkmcnt(7)
	v_mfma_f32_16x16x32_bf16 v[58:61], v[200:203], v[212:215], v[58:61]
	v_mfma_f32_16x16x32_bf16 v[62:65], v[200:203], v[216:219], v[62:65]
	v_mfma_f32_16x16x32_bf16 v[26:29], v[200:203], v[220:223], v[26:29]
	v_mfma_f32_16x16x32_bf16 v[30:33], v[200:203], v[224:227], v[30:33]
	ds_read_b128 v[200:203], v244 offset:20800
	s_waitcnt lgkmcnt(7)
	v_mfma_f32_16x16x32_bf16 v[34:37], v[204:207], v[212:215], v[34:37]
	v_mfma_f32_16x16x32_bf16 v[38:41], v[204:207], v[216:219], v[38:41]
	v_mfma_f32_16x16x32_bf16 v[2:5], v[204:207], v[220:223], v[2:5]
	v_mfma_f32_16x16x32_bf16 v[6:9], v[204:207], v[224:227], v[6:9]
	ds_read_b128 v[204:207], v244 offset:23104
	s_waitcnt lgkmcnt(7)
	v_mfma_f32_16x16x32_bf16 v[42:45], v[208:211], v[212:215], v[42:45]
	v_mfma_f32_16x16x32_bf16 v[46:49], v[208:211], v[216:219], v[46:49]
	v_mfma_f32_16x16x32_bf16 v[10:13], v[208:211], v[220:223], v[10:13]
	v_mfma_f32_16x16x32_bf16 v[14:17], v[208:211], v[224:227], v[14:17]
	ds_read_b128 v[208:211], v244 offset:25408
	s_waitcnt lgkmcnt(3)
	v_mfma_f32_16x16x32_bf16 v[50:53], v[196:199], v[228:231], v[50:53]
	v_mfma_f32_16x16x32_bf16 v[54:57], v[196:199], v[232:235], v[54:57]
	v_mfma_f32_16x16x32_bf16 v[18:21], v[196:199], v[236:239], v[18:21]
	v_mfma_f32_16x16x32_bf16 v[22:25], v[196:199], v[240:243], v[22:25]
	s_waitcnt vmcnt(15)
	ds_write_b128 v98, v[140:143]
	s_waitcnt vmcnt(14)
	ds_write_b128 v98, v[144:147] offset:4608
	s_waitcnt lgkmcnt(4)
	v_mfma_f32_16x16x32_bf16 v[58:61], v[200:203], v[228:231], v[58:61]
	v_mfma_f32_16x16x32_bf16 v[62:65], v[200:203], v[232:235], v[62:65]
	v_mfma_f32_16x16x32_bf16 v[26:29], v[200:203], v[236:239], v[26:29]
	v_mfma_f32_16x16x32_bf16 v[30:33], v[200:203], v[240:243], v[30:33]
	s_waitcnt vmcnt(13)
	ds_write_b128 v98, v[148:151] offset:9216
	s_waitcnt vmcnt(12)
	ds_write_b128 v98, v[152:155] offset:13824
	s_waitcnt lgkmcnt(5)
	v_mfma_f32_16x16x32_bf16 v[34:37], v[204:207], v[228:231], v[34:37]
	v_mfma_f32_16x16x32_bf16 v[38:41], v[204:207], v[232:235], v[38:41]
	v_mfma_f32_16x16x32_bf16 v[2:5], v[204:207], v[236:239], v[2:5]
	v_mfma_f32_16x16x32_bf16 v[6:9], v[204:207], v[240:243], v[6:9]
	s_waitcnt vmcnt(11)
	ds_write_b128 v98, v[156:159] offset:36864
	s_waitcnt vmcnt(10)
	ds_write_b128 v98, v[160:163] offset:41472
	s_waitcnt lgkmcnt(6)
	v_mfma_f32_16x16x32_bf16 v[42:45], v[208:211], v[228:231], v[42:45]
	v_mfma_f32_16x16x32_bf16 v[46:49], v[208:211], v[232:235], v[46:49]
	v_mfma_f32_16x16x32_bf16 v[10:13], v[208:211], v[236:239], v[10:13]
	v_mfma_f32_16x16x32_bf16 v[14:17], v[208:211], v[240:243], v[14:17]
	s_waitcnt vmcnt(9)
	ds_write_b128 v98, v[164:167] offset:46080
	s_waitcnt vmcnt(8)
	ds_write_b128 v98, v[168:171] offset:50688
	s_waitcnt lgkmcnt(0)
	s_barrier
	ds_read_b128 v[212:215], v245 offset:36864
	ds_read_b128 v[196:199], v244
	ds_read_b128 v[216:219], v245 offset:39168
	ds_read_b128 v[220:223], v245 offset:41472
	ds_read_b128 v[224:227], v245 offset:43776
	ds_read_b128 v[200:203], v244 offset:2304
	ds_read_b128 v[204:207], v244 offset:4608
	ds_read_b128 v[208:211], v244 offset:6912
	s_waitcnt lgkmcnt(6)
	v_mfma_f32_16x16x32_bf16 v[50:53], v[196:199], v[212:215], v[50:53]
	ds_read_b128 v[228:231], v245 offset:36928
	s_waitcnt lgkmcnt(6)
	v_mfma_f32_16x16x32_bf16 v[54:57], v[196:199], v[216:219], v[54:57]
	ds_read_b128 v[232:235], v245 offset:39232
	s_waitcnt lgkmcnt(6)
	v_mfma_f32_16x16x32_bf16 v[18:21], v[196:199], v[220:223], v[18:21]
	ds_read_b128 v[236:239], v245 offset:41536
	s_waitcnt lgkmcnt(6)
	v_mfma_f32_16x16x32_bf16 v[22:25], v[196:199], v[224:227], v[22:25]
	ds_read_b128 v[240:243], v245 offset:43840
	ds_read_b128 v[196:199], v244 offset:64
	s_waitcnt lgkmcnt(7)
	v_mfma_f32_16x16x32_bf16 v[58:61], v[200:203], v[212:215], v[58:61]
	v_mfma_f32_16x16x32_bf16 v[62:65], v[200:203], v[216:219], v[62:65]
	v_mfma_f32_16x16x32_bf16 v[26:29], v[200:203], v[220:223], v[26:29]
	v_mfma_f32_16x16x32_bf16 v[30:33], v[200:203], v[224:227], v[30:33]
	ds_read_b128 v[200:203], v244 offset:2368
	s_waitcnt lgkmcnt(7)
	v_mfma_f32_16x16x32_bf16 v[34:37], v[204:207], v[212:215], v[34:37]
	v_mfma_f32_16x16x32_bf16 v[38:41], v[204:207], v[216:219], v[38:41]
	v_mfma_f32_16x16x32_bf16 v[2:5], v[204:207], v[220:223], v[2:5]
	v_mfma_f32_16x16x32_bf16 v[6:9], v[204:207], v[224:227], v[6:9]
	ds_read_b128 v[204:207], v244 offset:4672
	s_waitcnt lgkmcnt(7)
	v_mfma_f32_16x16x32_bf16 v[42:45], v[208:211], v[212:215], v[42:45]
	v_mfma_f32_16x16x32_bf16 v[46:49], v[208:211], v[216:219], v[46:49]
	v_mfma_f32_16x16x32_bf16 v[10:13], v[208:211], v[220:223], v[10:13]
	v_mfma_f32_16x16x32_bf16 v[14:17], v[208:211], v[224:227], v[14:17]
	ds_read_b128 v[208:211], v244 offset:6976
	s_waitcnt lgkmcnt(3)
	v_mfma_f32_16x16x32_bf16 v[50:53], v[196:199], v[228:231], v[50:53]
	v_mfma_f32_16x16x32_bf16 v[54:57], v[196:199], v[232:235], v[54:57]
	v_mfma_f32_16x16x32_bf16 v[18:21], v[196:199], v[236:239], v[18:21]
	v_mfma_f32_16x16x32_bf16 v[22:25], v[196:199], v[240:243], v[22:25]
	s_waitcnt vmcnt(7)
	ds_write_b128 v98, v[102:105] offset:18432
	s_waitcnt vmcnt(6)
	ds_write_b128 v98, v[74:77] offset:23040
	s_waitcnt lgkmcnt(4)
	v_mfma_f32_16x16x32_bf16 v[58:61], v[200:203], v[228:231], v[58:61]
	v_mfma_f32_16x16x32_bf16 v[62:65], v[200:203], v[232:235], v[62:65]
	v_mfma_f32_16x16x32_bf16 v[26:29], v[200:203], v[236:239], v[26:29]
	v_mfma_f32_16x16x32_bf16 v[30:33], v[200:203], v[240:243], v[30:33]
	s_waitcnt vmcnt(5)
	ds_write_b128 v98, v[106:109] offset:27648
	s_waitcnt vmcnt(4)
	ds_write_b128 v98, v[78:81] offset:32256
	s_waitcnt lgkmcnt(5)
	v_mfma_f32_16x16x32_bf16 v[34:37], v[204:207], v[228:231], v[34:37]
	v_mfma_f32_16x16x32_bf16 v[38:41], v[204:207], v[232:235], v[38:41]
	v_mfma_f32_16x16x32_bf16 v[2:5], v[204:207], v[236:239], v[2:5]
	v_mfma_f32_16x16x32_bf16 v[6:9], v[204:207], v[240:243], v[6:9]
	s_waitcnt vmcnt(3)
	ds_write_b128 v98, v[110:113] offset:55296
	s_waitcnt vmcnt(2)
	ds_write_b128 v98, v[82:85] offset:59904
	s_waitcnt lgkmcnt(6)
	v_mfma_f32_16x16x32_bf16 v[42:45], v[208:211], v[228:231], v[42:45]
	v_mfma_f32_16x16x32_bf16 v[46:49], v[208:211], v[232:235], v[46:49]
	v_mfma_f32_16x16x32_bf16 v[10:13], v[208:211], v[236:239], v[10:13]
	v_mfma_f32_16x16x32_bf16 v[14:17], v[208:211], v[240:243], v[14:17]
	s_waitcnt vmcnt(1)
	ds_write_b128 v98, v[114:117] offset:64512
	s_waitcnt vmcnt(0)
	ds_write_b128 v99, v[86:89] offset:32256
	s_waitcnt lgkmcnt(0)
	s_barrier
	ds_read_b128 v[212:215], v245 offset:55296
	ds_read_b128 v[196:199], v244 offset:18432
	ds_read_b128 v[216:219], v245 offset:57600
	ds_read_b128 v[220:223], v245 offset:59904
	ds_read_b128 v[224:227], v245 offset:62208
	ds_read_b128 v[200:203], v244 offset:20736
	ds_read_b128 v[204:207], v244 offset:23040
	ds_read_b128 v[208:211], v244 offset:25344
	s_waitcnt lgkmcnt(6)
	v_mfma_f32_16x16x32_bf16 v[50:53], v[196:199], v[212:215], v[50:53]
	ds_read_b128 v[228:231], v245 offset:55360
	s_waitcnt lgkmcnt(6)
	v_mfma_f32_16x16x32_bf16 v[54:57], v[196:199], v[216:219], v[54:57]
	ds_read_b128 v[232:235], v245 offset:57664
	s_waitcnt lgkmcnt(6)
	v_mfma_f32_16x16x32_bf16 v[18:21], v[196:199], v[220:223], v[18:21]
	ds_read_b128 v[236:239], v245 offset:59968
	s_waitcnt lgkmcnt(6)
	v_mfma_f32_16x16x32_bf16 v[22:25], v[196:199], v[224:227], v[22:25]
	ds_read_b128 v[240:243], v245 offset:62272
	ds_read_b128 v[196:199], v244 offset:18496
	s_waitcnt lgkmcnt(7)
	v_mfma_f32_16x16x32_bf16 v[58:61], v[200:203], v[212:215], v[58:61]
	v_mfma_f32_16x16x32_bf16 v[62:65], v[200:203], v[216:219], v[62:65]
	v_mfma_f32_16x16x32_bf16 v[26:29], v[200:203], v[220:223], v[26:29]
	v_mfma_f32_16x16x32_bf16 v[30:33], v[200:203], v[224:227], v[30:33]
	ds_read_b128 v[200:203], v244 offset:20800
	s_waitcnt lgkmcnt(7)
	v_mfma_f32_16x16x32_bf16 v[34:37], v[204:207], v[212:215], v[34:37]
	v_mfma_f32_16x16x32_bf16 v[38:41], v[204:207], v[216:219], v[38:41]
	v_mfma_f32_16x16x32_bf16 v[2:5], v[204:207], v[220:223], v[2:5]
	v_mfma_f32_16x16x32_bf16 v[6:9], v[204:207], v[224:227], v[6:9]
	ds_read_b128 v[204:207], v244 offset:23104
	s_waitcnt lgkmcnt(7)
	v_mfma_f32_16x16x32_bf16 v[42:45], v[208:211], v[212:215], v[42:45]
	v_mfma_f32_16x16x32_bf16 v[46:49], v[208:211], v[216:219], v[46:49]
	v_mfma_f32_16x16x32_bf16 v[10:13], v[208:211], v[220:223], v[10:13]
	v_mfma_f32_16x16x32_bf16 v[14:17], v[208:211], v[224:227], v[14:17]
	ds_read_b128 v[208:211], v244 offset:25408
	s_waitcnt lgkmcnt(3)
	v_mfma_f32_16x16x32_bf16 v[50:53], v[196:199], v[228:231], v[50:53]
	v_mfma_f32_16x16x32_bf16 v[54:57], v[196:199], v[232:235], v[54:57]
	v_mfma_f32_16x16x32_bf16 v[18:21], v[196:199], v[236:239], v[18:21]
	v_mfma_f32_16x16x32_bf16 v[22:25], v[196:199], v[240:243], v[22:25]
	s_waitcnt lgkmcnt(2)
	v_mfma_f32_16x16x32_bf16 v[58:61], v[200:203], v[228:231], v[58:61]
	v_mfma_f32_16x16x32_bf16 v[62:65], v[200:203], v[232:235], v[62:65]
	v_mfma_f32_16x16x32_bf16 v[26:29], v[200:203], v[236:239], v[26:29]
	v_mfma_f32_16x16x32_bf16 v[30:33], v[200:203], v[240:243], v[30:33]
	s_waitcnt lgkmcnt(1)
	v_mfma_f32_16x16x32_bf16 v[34:37], v[204:207], v[228:231], v[34:37]
	v_mfma_f32_16x16x32_bf16 v[38:41], v[204:207], v[232:235], v[38:41]
	v_mfma_f32_16x16x32_bf16 v[2:5], v[204:207], v[236:239], v[2:5]
	v_mfma_f32_16x16x32_bf16 v[6:9], v[204:207], v[240:243], v[6:9]
	s_waitcnt lgkmcnt(0)
	v_mfma_f32_16x16x32_bf16 v[42:45], v[208:211], v[228:231], v[42:45]
	v_mfma_f32_16x16x32_bf16 v[46:49], v[208:211], v[232:235], v[46:49]
	v_mfma_f32_16x16x32_bf16 v[10:13], v[208:211], v[236:239], v[10:13]
	v_mfma_f32_16x16x32_bf16 v[14:17], v[208:211], v[240:243], v[14:17]
	s_lshr_b32 s14, s2, 3
	s_bfe_u32 s13, s2, 0x10002
	s_cmp_lt_i32 s14, 1
	s_mov_b64 s[2:3], -1
	s_waitcnt lgkmcnt(0)
	s_barrier
	s_nop 7
	v_permlane16_swap_b32_e32 v50, v54
	v_permlane16_swap_b32_e32 v51, v55
	v_permlane16_swap_b32_e32 v52, v56
	v_permlane16_swap_b32_e32 v53, v57
	v_permlane16_swap_b32_e32 v58, v62
	v_permlane16_swap_b32_e32 v59, v63
	v_permlane16_swap_b32_e32 v60, v64
	v_permlane16_swap_b32_e32 v61, v65
	v_permlane16_swap_b32_e32 v18, v22
	v_permlane16_swap_b32_e32 v19, v23
	v_permlane16_swap_b32_e32 v20, v24
	v_permlane16_swap_b32_e32 v21, v25
	v_permlane16_swap_b32_e32 v26, v30
	v_permlane16_swap_b32_e32 v27, v31
	v_permlane16_swap_b32_e32 v28, v32
	v_permlane16_swap_b32_e32 v29, v33
	v_permlane16_swap_b32_e32 v34, v38
	v_permlane16_swap_b32_e32 v35, v39
	v_permlane16_swap_b32_e32 v36, v40
	v_permlane16_swap_b32_e32 v37, v41
	v_permlane16_swap_b32_e32 v42, v46
	v_permlane16_swap_b32_e32 v43, v47
	v_permlane16_swap_b32_e32 v44, v48
	v_permlane16_swap_b32_e32 v45, v49
	v_permlane16_swap_b32_e32 v2, v6
	v_permlane16_swap_b32_e32 v3, v7
	v_permlane16_swap_b32_e32 v4, v8
	v_permlane16_swap_b32_e32 v5, v9
	v_permlane16_swap_b32_e32 v10, v14
	v_permlane16_swap_b32_e32 v11, v15
	v_permlane16_swap_b32_e32 v12, v16
	v_permlane16_swap_b32_e32 v13, v17
	v_permlane32_swap_b32_e32 v50, v54
	v_permlane32_swap_b32_e32 v51, v55
	v_permlane32_swap_b32_e32 v52, v56
	v_permlane32_swap_b32_e32 v53, v57
	v_permlane32_swap_b32_e32 v58, v62
	v_permlane32_swap_b32_e32 v59, v63
	v_permlane32_swap_b32_e32 v60, v64
	v_permlane32_swap_b32_e32 v61, v65
	v_permlane32_swap_b32_e32 v18, v22
	v_permlane32_swap_b32_e32 v19, v23
	v_permlane32_swap_b32_e32 v20, v24
	v_permlane32_swap_b32_e32 v21, v25
	v_permlane32_swap_b32_e32 v26, v30
	v_permlane32_swap_b32_e32 v27, v31
	v_permlane32_swap_b32_e32 v28, v32
	v_permlane32_swap_b32_e32 v29, v33
	v_permlane32_swap_b32_e32 v34, v38
	v_permlane32_swap_b32_e32 v35, v39
	v_permlane32_swap_b32_e32 v36, v40
	v_permlane32_swap_b32_e32 v37, v41
	v_permlane32_swap_b32_e32 v42, v46
	v_permlane32_swap_b32_e32 v43, v47
	v_permlane32_swap_b32_e32 v44, v48
	v_permlane32_swap_b32_e32 v45, v49
	v_permlane32_swap_b32_e32 v2, v6
	v_permlane32_swap_b32_e32 v3, v7
	v_permlane32_swap_b32_e32 v4, v8
	v_permlane32_swap_b32_e32 v5, v9
	v_permlane32_swap_b32_e32 v10, v14
	v_permlane32_swap_b32_e32 v11, v15
	v_permlane32_swap_b32_e32 v12, v16
	v_permlane32_swap_b32_e32 v13, v17
	s_cbranch_scc1 .LBB0_755
	s_and_b32 s2, 0xffff, s14
	s_cmp_lg_u32 s2, 1
	s_mov_b64 s[2:3], -1
	s_cbranch_scc0 .LBB0_752
	s_cmp_eq_u32 s13, 0
	s_cselect_b32 s12, 3, 10
	s_mov_b64 s[2:3], 0

.LBB0_1638:
	s_or_b64 exec, exec, s[0:1]
	v_readlane_b32 s0, v248, 0
	s_cmpk_gt_u32 s0, 0x8ff
	s_cbranch_scc1 .LBB0_1649
	v_readlane_b32 s0, v248, 0
	s_lshr_b32 s4, s0, 3
	s_and_b32 s0, s0, 7
	s_add_i32 s1, s0, 0xfffc
	s_and_b32 s1, s1, 0xffff
	v_lshlrev_b32_e32 v2, 4, v1
	s_lshr_b32 s5, s50, 3
	s_min_u32 s6, s0, s1
	v_and_b32_e32 v66, 0x70, v2
	v_mov_b32_e32 v67, 0
	s_cmp_gt_u32 s0, 3
	v_lshl_add_u64 v[2:3], s[82:83], 0, v[66:67]
	s_mov_b64 s[0:1], 0xa000000
	v_lshl_add_u64 v[68:69], v[2:3], 0, s[0:1]
	s_mov_b64 s[0:1], 0xb100000
	v_lshl_add_u64 v[70:71], v[2:3], 0, s[0:1]
	v_lshrrev_b32_e32 v2, 1, v1
	v_and_b32_e32 v95, 0x1c0, v2
	v_lshrrev_b32_e32 v91, 3, v1
	v_or_b32_e32 v2, v95, v132
	s_movk_i32 s0, 0x90
	v_mad_u32_u24 v96, v2, s0, v34
	v_mul_u32_u24_e32 v2, 0x48, v91
	v_and_b32_e32 v90, 0x5f, v1
	v_lshl_add_u32 v98, v2, 1, v66
	v_lshrrev_b32_e32 v246, 3, v1
	v_and_b32_e32 v246, 15, v246
	v_add_u32_e32 v246, 4, v246
	v_bfe_u32 v246, v246, 3, 1
	v_and_b32_e32 v249, 1, v1
	v_lshlrev_b32_e32 v249, 1, v249
	v_sub_u32_e32 v249, 1, v249
	v_mul_i32_i24_e32 v246, v246, v249
	v_lshlrev_b32_e32 v246, 4, v246
	v_add_u32_e32 v98, v246, v98
	v_mov_b32_e32 v35, v67
	s_mul_i32 s6, s6, 6
	s_mov_b32 s7, 0
	s_cselect_b32 s8, 48, 0
	v_add_u32_e32 v92, 32, v91
	v_add_u32_e32 v93, 64, v91
	v_add_u32_e32 v94, 0x60, v91
	v_mad_u32_u24 v97, v90, s0, v34
	v_add_u32_e32 v99, 0x9000, v98
	v_lshl_add_u64 v[72:73], s[82:83], 0, v[34:35]
	s_mov_b64 s[0:1], 0x8000
	v_mov_b32_e32 v100, 0xc00000
	s_mov_b32 s9, s4
	s_mov_b32 s2, s4
	s_branch .LBB0_1641

.LBB0_1641:
	s_and_b32 s3, s2, 0xffff
	s_mul_i32 s3, s3, 0xaaab
	s_lshr_b32 s3, s3, 18
	s_mul_i32 s10, s3, 6
	s_sub_i32 s2, s2, s10
	s_and_b32 s2, s2, 0xffff
	s_add_i32 s2, s6, s2
	s_lshl_b32 s10, s2, 7
	v_or_b32_e32 v2, s10, v91
	v_lshlrev_b32_e32 v66, 11, v2
	v_lshl_add_u64 v[74:75], v[68:69], 0, v[66:67]
	v_add_lshl_u32 v66, s10, v92, 11
	s_add_i32 s3, s8, s3
	v_lshl_add_u64 v[76:77], v[68:69], 0, v[66:67]
	v_add_lshl_u32 v66, s10, v93, 11
	s_lshl_b32 s11, s3, 7
	v_lshl_add_u64 v[78:79], v[68:69], 0, v[66:67]
	v_add_lshl_u32 v66, s10, v94, 11
	v_lshl_add_u64 v[80:81], v[68:69], 0, v[66:67]
	v_or_b32_e32 v66, s11, v91
	v_lshlrev_b64 v[2:3], 11, v[66:67]
	v_add_u32_e32 v66, s11, v92
	v_lshl_add_u64 v[82:83], v[70:71], 0, v[2:3]
	v_lshlrev_b64 v[2:3], 11, v[66:67]
	v_add_u32_e32 v66, s11, v93
	v_lshl_add_u64 v[84:85], v[70:71], 0, v[2:3]
	v_lshlrev_b64 v[2:3], 11, v[66:67]
	v_add_u32_e32 v66, s11, v94
	v_lshl_add_u64 v[86:87], v[70:71], 0, v[2:3]
	v_lshlrev_b64 v[2:3], 11, v[66:67]
	v_lshl_add_u64 v[88:89], v[70:71], 0, v[2:3]
	global_load_dwordx4 v[2:5], v[74:75], off
	global_load_dwordx4 v[6:9], v[76:77], off
	global_load_dwordx4 v[10:13], v[78:79], off
	global_load_dwordx4 v[14:17], v[80:81], off
	global_load_dwordx4 v[18:21], v[82:83], off
	global_load_dwordx4 v[22:25], v[84:85], off
	global_load_dwordx4 v[26:29], v[86:87], off
	global_load_dwordx4 v[30:33], v[88:89], off
	global_load_dwordx4 v[102:105], v[74:75], off offset:128
	global_load_dwordx4 v[106:109], v[76:77], off offset:128
	global_load_dwordx4 v[110:113], v[78:79], off offset:128
	global_load_dwordx4 v[114:117], v[80:81], off offset:128
	global_load_dwordx4 v[118:121], v[82:83], off offset:128
	global_load_dwordx4 v[122:125], v[84:85], off offset:128
	global_load_dwordx4 v[126:129], v[86:87], off offset:128
	global_load_dwordx4 v[132:135], v[88:89], off offset:128
	s_waitcnt vmcnt(15)
	ds_write_b128 v98, v[2:5]
	s_waitcnt vmcnt(14)
	ds_write_b128 v98, v[6:9] offset:4608
	s_waitcnt vmcnt(13)
	ds_write_b128 v98, v[10:13] offset:9216
	s_waitcnt vmcnt(12)
	ds_write_b128 v98, v[14:17] offset:13824
	s_waitcnt vmcnt(11)
	ds_write_b128 v98, v[18:21] offset:36864
	s_waitcnt vmcnt(10)
	ds_write_b128 v98, v[22:25] offset:41472
	s_waitcnt vmcnt(9)
	ds_write_b128 v98, v[26:29] offset:46080
	s_waitcnt vmcnt(8)
	ds_write_b128 v98, v[30:33] offset:50688
	s_waitcnt lgkmcnt(0)
	s_barrier
	global_load_dwordx4 v[136:139], v[74:75], off offset:256
	global_load_dwordx4 v[140:143], v[76:77], off offset:256
	global_load_dwordx4 v[144:147], v[78:79], off offset:256
	global_load_dwordx4 v[148:151], v[80:81], off offset:256
	global_load_dwordx4 v[152:155], v[82:83], off offset:256
	global_load_dwordx4 v[156:159], v[84:85], off offset:256
	global_load_dwordx4 v[160:163], v[86:87], off offset:256
	global_load_dwordx4 v[164:167], v[88:89], off offset:256
	v_and_b32_e32 v246, 15, v1
	v_add_u32_e32 v246, 4, v246
	v_bfe_u32 v246, v246, 3, 1
	v_bfe_u32 v249, v1, 4, 2
	v_xor_b32_e32 v246, v246, v249
	v_bfe_u32 v249, v1, 5, 1
	v_sub_u32_e32 v246, v246, v249
	v_lshlrev_b32_e32 v246, 4, v246
	v_bfe_u32 v249, v1, 4, 1
	v_mul_u32_u24_e32 v249, 0x900, v249
	v_sub_u32_e32 v246, v246, v249
	v_add_u32_e32 v244, v246, v96
	v_add_u32_e32 v245, v246, v97
	ds_read_b128 v[212:215], v245 offset:36864
	ds_read_b128 v[196:199], v244
	ds_read_b128 v[216:219], v245 offset:39168
	ds_read_b128 v[220:223], v245 offset:41472
	ds_read_b128 v[224:227], v245 offset:43776
	ds_read_b128 v[200:203], v244 offset:2304
	ds_read_b128 v[204:207], v244 offset:4608
	ds_read_b128 v[208:211], v244 offset:6912
	s_waitcnt lgkmcnt(6)
	v_mfma_f32_16x16x32_bf16 v[50:53], v[196:199], v[212:215], 0
	ds_read_b128 v[228:231], v245 offset:36928
	s_waitcnt lgkmcnt(6)
	v_mfma_f32_16x16x32_bf16 v[54:57], v[196:199], v[216:219], 0
	ds_read_b128 v[232:235], v245 offset:39232
	s_waitcnt lgkmcnt(6)
	v_mfma_f32_16x16x32_bf16 v[18:21], v[196:199], v[220:223], 0
	ds_read_b128 v[236:239], v245 offset:41536
	s_waitcnt lgkmcnt(6)
	v_mfma_f32_16x16x32_bf16 v[22:25], v[196:199], v[224:227], 0
	ds_read_b128 v[240:243], v245 offset:43840
	ds_read_b128 v[196:199], v244 offset:64
	s_waitcnt lgkmcnt(7)
	v_mfma_f32_16x16x32_bf16 v[58:61], v[200:203], v[212:215], 0
	v_mfma_f32_16x16x32_bf16 v[62:65], v[200:203], v[216:219], 0
	v_mfma_f32_16x16x32_bf16 v[26:29], v[200:203], v[220:223], 0
	v_mfma_f32_16x16x32_bf16 v[30:33], v[200:203], v[224:227], 0
	ds_read_b128 v[200:203], v244 offset:2368
	s_waitcnt lgkmcnt(7)
	v_mfma_f32_16x16x32_bf16 v[34:37], v[204:207], v[212:215], 0
	v_mfma_f32_16x16x32_bf16 v[38:41], v[204:207], v[216:219], 0
	v_mfma_f32_16x16x32_bf16 v[2:5], v[204:207], v[220:223], 0
	v_mfma_f32_16x16x32_bf16 v[6:9], v[204:207], v[224:227], 0
	ds_read_b128 v[204:207], v244 offset:4672
	s_waitcnt lgkmcnt(7)
	v_mfma_f32_16x16x32_bf16 v[42:45], v[208:211], v[212:215], 0
	v_mfma_f32_16x16x32_bf16 v[46:49], v[208:211], v[216:219], 0
	v_mfma_f32_16x16x32_bf16 v[10:13], v[208:211], v[220:223], 0
	v_mfma_f32_16x16x32_bf16 v[14:17], v[208:211], v[224:227], 0
	ds_read_b128 v[208:211], v244 offset:6976
	s_waitcnt lgkmcnt(3)
	v_mfma_f32_16x16x32_bf16 v[50:53], v[196:199], v[228:231], v[50:53]
	v_mfma_f32_16x16x32_bf16 v[54:57], v[196:199], v[232:235], v[54:57]
	v_mfma_f32_16x16x32_bf16 v[18:21], v[196:199], v[236:239], v[18:21]
	v_mfma_f32_16x16x32_bf16 v[22:25], v[196:199], v[240:243], v[22:25]
	s_waitcnt vmcnt(15)
	ds_write_b128 v98, v[102:105] offset:18432
	s_waitcnt vmcnt(14)
	ds_write_b128 v98, v[106:109] offset:23040
	s_waitcnt lgkmcnt(4)
	v_mfma_f32_16x16x32_bf16 v[58:61], v[200:203], v[228:231], v[58:61]
	v_mfma_f32_16x16x32_bf16 v[62:65], v[200:203], v[232:235], v[62:65]
	v_mfma_f32_16x16x32_bf16 v[26:29], v[200:203], v[236:239], v[26:29]
	v_mfma_f32_16x16x32_bf16 v[30:33], v[200:203], v[240:243], v[30:33]
	s_waitcnt vmcnt(13)
	ds_write_b128 v98, v[110:113] offset:27648
	s_waitcnt vmcnt(12)
	ds_write_b128 v98, v[114:117] offset:32256
	s_waitcnt lgkmcnt(5)
	v_mfma_f32_16x16x32_bf16 v[34:37], v[204:207], v[228:231], v[34:37]
	v_mfma_f32_16x16x32_bf16 v[38:41], v[204:207], v[232:235], v[38:41]
	v_mfma_f32_16x16x32_bf16 v[2:5], v[204:207], v[236:239], v[2:5]
	v_mfma_f32_16x16x32_bf16 v[6:9], v[204:207], v[240:243], v[6:9]
	s_waitcnt vmcnt(11)
	ds_write_b128 v98, v[118:121] offset:55296
	s_waitcnt vmcnt(10)
	ds_write_b128 v98, v[122:125] offset:59904
	s_waitcnt lgkmcnt(6)
	v_mfma_f32_16x16x32_bf16 v[42:45], v[208:211], v[228:231], v[42:45]
	v_mfma_f32_16x16x32_bf16 v[46:49], v[208:211], v[232:235], v[46:49]
	v_mfma_f32_16x16x32_bf16 v[10:13], v[208:211], v[236:239], v[10:13]
	v_mfma_f32_16x16x32_bf16 v[14:17], v[208:211], v[240:243], v[14:17]
	s_waitcnt vmcnt(9)
	ds_write_b128 v98, v[126:129] offset:64512
	s_waitcnt vmcnt(8)
	ds_write_b128 v99, v[132:135] offset:32256
	s_waitcnt lgkmcnt(0)
	s_barrier
	global_load_dwordx4 v[102:105], v[74:75], off offset:384
	global_load_dwordx4 v[106:109], v[76:77], off offset:384
	global_load_dwordx4 v[110:113], v[78:79], off offset:384
	global_load_dwordx4 v[114:117], v[80:81], off offset:384
	global_load_dwordx4 v[118:121], v[82:83], off offset:384
	global_load_dwordx4 v[122:125], v[84:85], off offset:384
	global_load_dwordx4 v[126:129], v[86:87], off offset:384
	global_load_dwordx4 v[132:135], v[88:89], off offset:384
	ds_read_b128 v[212:215], v245 offset:55296
	ds_read_b128 v[196:199], v244 offset:18432
	ds_read_b128 v[216:219], v245 offset:57600
	ds_read_b128 v[220:223], v245 offset:59904
	ds_read_b128 v[224:227], v245 offset:62208
	ds_read_b128 v[200:203], v244 offset:20736
	ds_read_b128 v[204:207], v244 offset:23040
	ds_read_b128 v[208:211], v244 offset:25344
	s_waitcnt lgkmcnt(6)
	v_mfma_f32_16x16x32_bf16 v[50:53], v[196:199], v[212:215], v[50:53]
	ds_read_b128 v[228:231], v245 offset:55360
	s_waitcnt lgkmcnt(6)
	v_mfma_f32_16x16x32_bf16 v[54:57], v[196:199], v[216:219], v[54:57]
	ds_read_b128 v[232:235], v245 offset:57664
	s_waitcnt lgkmcnt(6)
	v_mfma_f32_16x16x32_bf16 v[18:21], v[196:199], v[220:223], v[18:21]
	ds_read_b128 v[236:239], v245 offset:59968
	s_waitcnt lgkmcnt(6)
	v_mfma_f32_16x16x32_bf16 v[22:25], v[196:199], v[224:227], v[22:25]
	ds_read_b128 v[240:243], v245 offset:62272
	ds_read_b128 v[196:199], v244 offset:18496
	s_waitcnt lgkmcnt(7)
	v_mfma_f32_16x16x32_bf16 v[58:61], v[200:203], v[212:215], v[58:61]
	v_mfma_f32_16x16x32_bf16 v[62:65], v[200:203], v[216:219], v[62:65]
	v_mfma_f32_16x16x32_bf16 v[26:29], v[200:203], v[220:223], v[26:29]
	v_mfma_f32_16x16x32_bf16 v[30:33], v[200:203], v[224:227], v[30:33]
	ds_read_b128 v[200:203], v244 offset:20800
	s_waitcnt lgkmcnt(7)
	v_mfma_f32_16x16x32_bf16 v[34:37], v[204:207], v[212:215], v[34:37]
	v_mfma_f32_16x16x32_bf16 v[38:41], v[204:207], v[216:219], v[38:41]
	v_mfma_f32_16x16x32_bf16 v[2:5], v[204:207], v[220:223], v[2:5]
	v_mfma_f32_16x16x32_bf16 v[6:9], v[204:207], v[224:227], v[6:9]
	ds_read_b128 v[204:207], v244 offset:23104
	s_waitcnt lgkmcnt(7)
	v_mfma_f32_16x16x32_bf16 v[42:45], v[208:211], v[212:215], v[42:45]
	v_mfma_f32_16x16x32_bf16 v[46:49], v[208:211], v[216:219], v[46:49]
	v_mfma_f32_16x16x32_bf16 v[10:13], v[208:211], v[220:223], v[10:13]
	v_mfma_f32_16x16x32_bf16 v[14:17], v[208:211], v[224:227], v[14:17]
	ds_read_b128 v[208:211], v244 offset:25408
	s_waitcnt lgkmcnt(3)
	v_mfma_f32_16x16x32_bf16 v[50:53], v[196:199], v[228:231], v[50:53]
	v_mfma_f32_16x16x32_bf16 v[54:57], v[196:199], v[232:235], v[54:57]
	v_mfma_f32_16x16x32_bf16 v[18:21], v[196:199], v[236:239], v[18:21]
	v_mfma_f32_16x16x32_bf16 v[22:25], v[196:199], v[240:243], v[22:25]
	s_waitcnt vmcnt(15)
	ds_write_b128 v98, v[136:139]
	s_waitcnt vmcnt(14)
	ds_write_b128 v98, v[140:143] offset:4608
	s_waitcnt lgkmcnt(4)
	v_mfma_f32_16x16x32_bf16 v[58:61], v[200:203], v[228:231], v[58:61]
	v_mfma_f32_16x16x32_bf16 v[62:65], v[200:203], v[232:235], v[62:65]
	v_mfma_f32_16x16x32_bf16 v[26:29], v[200:203], v[236:239], v[26:29]
	v_mfma_f32_16x16x32_bf16 v[30:33], v[200:203], v[240:243], v[30:33]
	s_waitcnt vmcnt(13)
	ds_write_b128 v98, v[144:147] offset:9216
	s_waitcnt vmcnt(12)
	ds_write_b128 v98, v[148:151] offset:13824
	s_waitcnt lgkmcnt(5)
	v_mfma_f32_16x16x32_bf16 v[34:37], v[204:207], v[228:231], v[34:37]
	v_mfma_f32_16x16x32_bf16 v[38:41], v[204:207], v[232:235], v[38:41]
	v_mfma_f32_16x16x32_bf16 v[2:5], v[204:207], v[236:239], v[2:5]
	v_mfma_f32_16x16x32_bf16 v[6:9], v[204:207], v[240:243], v[6:9]
	s_waitcnt vmcnt(11)
	ds_write_b128 v98, v[152:155] offset:36864
	s_waitcnt vmcnt(10)
	ds_write_b128 v98, v[156:159] offset:41472
	s_waitcnt lgkmcnt(6)
	v_mfma_f32_16x16x32_bf16 v[42:45], v[208:211], v[228:231], v[42:45]
	v_mfma_f32_16x16x32_bf16 v[46:49], v[208:211], v[232:235], v[46:49]
	v_mfma_f32_16x16x32_bf16 v[10:13], v[208:211], v[236:239], v[10:13]
	v_mfma_f32_16x16x32_bf16 v[14:17], v[208:211], v[240:243], v[14:17]
	s_waitcnt vmcnt(9)
	ds_write_b128 v98, v[160:163] offset:46080
	s_waitcnt vmcnt(8)
	ds_write_b128 v98, v[164:167] offset:50688
	s_waitcnt lgkmcnt(0)
	s_barrier
	global_load_dwordx4 v[136:139], v[74:75], off offset:512
	global_load_dwordx4 v[140:143], v[76:77], off offset:512
	global_load_dwordx4 v[144:147], v[78:79], off offset:512
	global_load_dwordx4 v[148:151], v[80:81], off offset:512
	global_load_dwordx4 v[152:155], v[82:83], off offset:512
	global_load_dwordx4 v[156:159], v[84:85], off offset:512
	global_load_dwordx4 v[160:163], v[86:87], off offset:512
	global_load_dwordx4 v[164:167], v[88:89], off offset:512
	ds_read_b128 v[212:215], v245 offset:36864
	ds_read_b128 v[196:199], v244
	ds_read_b128 v[216:219], v245 offset:39168
	ds_read_b128 v[220:223], v245 offset:41472
	ds_read_b128 v[224:227], v245 offset:43776
	ds_read_b128 v[200:203], v244 offset:2304
	ds_read_b128 v[204:207], v244 offset:4608
	ds_read_b128 v[208:211], v244 offset:6912
	s_waitcnt lgkmcnt(6)
	v_mfma_f32_16x16x32_bf16 v[50:53], v[196:199], v[212:215], v[50:53]
	ds_read_b128 v[228:231], v245 offset:36928
	s_waitcnt lgkmcnt(6)
	v_mfma_f32_16x16x32_bf16 v[54:57], v[196:199], v[216:219], v[54:57]
	ds_read_b128 v[232:235], v245 offset:39232
	s_waitcnt lgkmcnt(6)
	v_mfma_f32_16x16x32_bf16 v[18:21], v[196:199], v[220:223], v[18:21]
	ds_read_b128 v[236:239], v245 offset:41536
	s_waitcnt lgkmcnt(6)
	v_mfma_f32_16x16x32_bf16 v[22:25], v[196:199], v[224:227], v[22:25]
	ds_read_b128 v[240:243], v245 offset:43840
	ds_read_b128 v[196:199], v244 offset:64
	s_waitcnt lgkmcnt(7)
	v_mfma_f32_16x16x32_bf16 v[58:61], v[200:203], v[212:215], v[58:61]
	v_mfma_f32_16x16x32_bf16 v[62:65], v[200:203], v[216:219], v[62:65]
	v_mfma_f32_16x16x32_bf16 v[26:29], v[200:203], v[220:223], v[26:29]
	v_mfma_f32_16x16x32_bf16 v[30:33], v[200:203], v[224:227], v[30:33]
	ds_read_b128 v[200:203], v244 offset:2368
	s_waitcnt lgkmcnt(7)
	v_mfma_f32_16x16x32_bf16 v[34:37], v[204:207], v[212:215], v[34:37]
	v_mfma_f32_16x16x32_bf16 v[38:41], v[204:207], v[216:219], v[38:41]
	v_mfma_f32_16x16x32_bf16 v[2:5], v[204:207], v[220:223], v[2:5]
	v_mfma_f32_16x16x32_bf16 v[6:9], v[204:207], v[224:227], v[6:9]
	ds_read_b128 v[204:207], v244 offset:4672
	s_waitcnt lgkmcnt(7)
	v_mfma_f32_16x16x32_bf16 v[42:45], v[208:211], v[212:215], v[42:45]
	v_mfma_f32_16x16x32_bf16 v[46:49], v[208:211], v[216:219], v[46:49]
	v_mfma_f32_16x16x32_bf16 v[10:13], v[208:211], v[220:223], v[10:13]
	v_mfma_f32_16x16x32_bf16 v[14:17], v[208:211], v[224:227], v[14:17]
	ds_read_b128 v[208:211], v244 offset:6976
	s_waitcnt lgkmcnt(3)
	v_mfma_f32_16x16x32_bf16 v[50:53], v[196:199], v[228:231], v[50:53]
	v_mfma_f32_16x16x32_bf16 v[54:57], v[196:199], v[232:235], v[54:57]
	v_mfma_f32_16x16x32_bf16 v[18:21], v[196:199], v[236:239], v[18:21]
	v_mfma_f32_16x16x32_bf16 v[22:25], v[196:199], v[240:243], v[22:25]
	s_waitcnt vmcnt(15)
	ds_write_b128 v98, v[102:105] offset:18432
	s_waitcnt vmcnt(14)
	ds_write_b128 v98, v[106:109] offset:23040
	s_waitcnt lgkmcnt(4)
	v_mfma_f32_16x16x32_bf16 v[58:61], v[200:203], v[228:231], v[58:61]
	v_mfma_f32_16x16x32_bf16 v[62:65], v[200:203], v[232:235], v[62:65]
	v_mfma_f32_16x16x32_bf16 v[26:29], v[200:203], v[236:239], v[26:29]
	v_mfma_f32_16x16x32_bf16 v[30:33], v[200:203], v[240:243], v[30:33]
	s_waitcnt vmcnt(13)
	ds_write_b128 v98, v[110:113] offset:27648
	s_waitcnt vmcnt(12)
	ds_write_b128 v98, v[114:117] offset:32256
	s_waitcnt lgkmcnt(5)
	v_mfma_f32_16x16x32_bf16 v[34:37], v[204:207], v[228:231], v[34:37]
	v_mfma_f32_16x16x32_bf16 v[38:41], v[204:207], v[232:235], v[38:41]
	v_mfma_f32_16x16x32_bf16 v[2:5], v[204:207], v[236:239], v[2:5]
	v_mfma_f32_16x16x32_bf16 v[6:9], v[204:207], v[240:243], v[6:9]
	s_waitcnt vmcnt(11)
	ds_write_b128 v98, v[118:121] offset:55296
	s_waitcnt vmcnt(10)
	ds_write_b128 v98, v[122:125] offset:59904
	s_waitcnt lgkmcnt(6)
	v_mfma_f32_16x16x32_bf16 v[42:45], v[208:211], v[228:231], v[42:45]
	v_mfma_f32_16x16x32_bf16 v[46:49], v[208:211], v[232:235], v[46:49]
	v_mfma_f32_16x16x32_bf16 v[10:13], v[208:211], v[236:239], v[10:13]
	v_mfma_f32_16x16x32_bf16 v[14:17], v[208:211], v[240:243], v[14:17]
	s_waitcnt vmcnt(9)
	ds_write_b128 v98, v[126:129] offset:64512
	s_waitcnt vmcnt(8)
	ds_write_b128 v99, v[132:135] offset:32256
	s_waitcnt lgkmcnt(0)
	s_barrier
	global_load_dwordx4 v[102:105], v[74:75], off offset:640
	global_load_dwordx4 v[106:109], v[76:77], off offset:640
	global_load_dwordx4 v[110:113], v[78:79], off offset:640
	global_load_dwordx4 v[114:117], v[80:81], off offset:640
	global_load_dwordx4 v[118:121], v[82:83], off offset:640
	global_load_dwordx4 v[122:125], v[84:85], off offset:640
	global_load_dwordx4 v[126:129], v[86:87], off offset:640
	global_load_dwordx4 v[132:135], v[88:89], off offset:640
	ds_read_b128 v[212:215], v245 offset:55296
	ds_read_b128 v[196:199], v244 offset:18432
	ds_read_b128 v[216:219], v245 offset:57600
	ds_read_b128 v[220:223], v245 offset:59904
	ds_read_b128 v[224:227], v245 offset:62208
	ds_read_b128 v[200:203], v244 offset:20736
	ds_read_b128 v[204:207], v244 offset:23040
	ds_read_b128 v[208:211], v244 offset:25344
	s_waitcnt lgkmcnt(6)
	v_mfma_f32_16x16x32_bf16 v[50:53], v[196:199], v[212:215], v[50:53]
	ds_read_b128 v[228:231], v245 offset:55360
	s_waitcnt lgkmcnt(6)
	v_mfma_f32_16x16x32_bf16 v[54:57], v[196:199], v[216:219], v[54:57]
	ds_read_b128 v[232:235], v245 offset:57664
	s_waitcnt lgkmcnt(6)
	v_mfma_f32_16x16x32_bf16 v[18:21], v[196:199], v[220:223], v[18:21]
	ds_read_b128 v[236:239], v245 offset:59968
	s_waitcnt lgkmcnt(6)
	v_mfma_f32_16x16x32_bf16 v[22:25], v[196:199], v[224:227], v[22:25]
	ds_read_b128 v[240:243], v245 offset:62272
	ds_read_b128 v[196:199], v244 offset:18496
	s_waitcnt lgkmcnt(7)
	v_mfma_f32_16x16x32_bf16 v[58:61], v[200:203], v[212:215], v[58:61]
	v_mfma_f32_16x16x32_bf16 v[62:65], v[200:203], v[216:219], v[62:65]
	v_mfma_f32_16x16x32_bf16 v[26:29], v[200:203], v[220:223], v[26:29]
	v_mfma_f32_16x16x32_bf16 v[30:33], v[200:203], v[224:227], v[30:33]
	ds_read_b128 v[200:203], v244 offset:20800
	s_waitcnt lgkmcnt(7)
	v_mfma_f32_16x16x32_bf16 v[34:37], v[204:207], v[212:215], v[34:37]
	v_mfma_f32_16x16x32_bf16 v[38:41], v[204:207], v[216:219], v[38:41]
	v_mfma_f32_16x16x32_bf16 v[2:5], v[204:207], v[220:223], v[2:5]
	v_mfma_f32_16x16x32_bf16 v[6:9], v[204:207], v[224:227], v[6:9]
	ds_read_b128 v[204:207], v244 offset:23104
	s_waitcnt lgkmcnt(7)
	v_mfma_f32_16x16x32_bf16 v[42:45], v[208:211], v[212:215], v[42:45]
	v_mfma_f32_16x16x32_bf16 v[46:49], v[208:211], v[216:219], v[46:49]
	v_mfma_f32_16x16x32_bf16 v[10:13], v[208:211], v[220:223], v[10:13]
	v_mfma_f32_16x16x32_bf16 v[14:17], v[208:211], v[224:227], v[14:17]
	ds_read_b128 v[208:211], v244 offset:25408
	s_waitcnt lgkmcnt(3)
	v_mfma_f32_16x16x32_bf16 v[50:53], v[196:199], v[228:231], v[50:53]
	v_mfma_f32_16x16x32_bf16 v[54:57], v[196:199], v[232:235], v[54:57]
	v_mfma_f32_16x16x32_bf16 v[18:21], v[196:199], v[236:239], v[18:21]
	v_mfma_f32_16x16x32_bf16 v[22:25], v[196:199], v[240:243], v[22:25]
	s_waitcnt vmcnt(15)
	ds_write_b128 v98, v[136:139]
	s_waitcnt vmcnt(14)
	ds_write_b128 v98, v[140:143] offset:4608
	s_waitcnt lgkmcnt(4)
	v_mfma_f32_16x16x32_bf16 v[58:61], v[200:203], v[228:231], v[58:61]
	v_mfma_f32_16x16x32_bf16 v[62:65], v[200:203], v[232:235], v[62:65]
	v_mfma_f32_16x16x32_bf16 v[26:29], v[200:203], v[236:239], v[26:29]
	v_mfma_f32_16x16x32_bf16 v[30:33], v[200:203], v[240:243], v[30:33]
	s_waitcnt vmcnt(13)
	ds_write_b128 v98, v[144:147] offset:9216
	s_waitcnt vmcnt(12)
	ds_write_b128 v98, v[148:151] offset:13824
	s_waitcnt lgkmcnt(5)
	v_mfma_f32_16x16x32_bf16 v[34:37], v[204:207], v[228:231], v[34:37]
	v_mfma_f32_16x16x32_bf16 v[38:41], v[204:207], v[232:235], v[38:41]
	v_mfma_f32_16x16x32_bf16 v[2:5], v[204:207], v[236:239], v[2:5]
	v_mfma_f32_16x16x32_bf16 v[6:9], v[204:207], v[240:243], v[6:9]
	s_waitcnt vmcnt(11)
	ds_write_b128 v98, v[152:155] offset:36864
	s_waitcnt vmcnt(10)
	ds_write_b128 v98, v[156:159] offset:41472
	s_waitcnt lgkmcnt(6)
	v_mfma_f32_16x16x32_bf16 v[42:45], v[208:211], v[228:231], v[42:45]
	v_mfma_f32_16x16x32_bf16 v[46:49], v[208:211], v[232:235], v[46:49]
	v_mfma_f32_16x16x32_bf16 v[10:13], v[208:211], v[236:239], v[10:13]
	v_mfma_f32_16x16x32_bf16 v[14:17], v[208:211], v[240:243], v[14:17]
	s_waitcnt vmcnt(9)
	ds_write_b128 v98, v[160:163] offset:46080
	s_waitcnt vmcnt(8)
	ds_write_b128 v98, v[164:167] offset:50688
	s_waitcnt lgkmcnt(0)
	s_barrier
	global_load_dwordx4 v[136:139], v[74:75], off offset:768
	global_load_dwordx4 v[140:143], v[76:77], off offset:768
	global_load_dwordx4 v[144:147], v[78:79], off offset:768
	global_load_dwordx4 v[148:151], v[80:81], off offset:768
	global_load_dwordx4 v[152:155], v[82:83], off offset:768
	global_load_dwordx4 v[156:159], v[84:85], off offset:768
	global_load_dwordx4 v[160:163], v[86:87], off offset:768
	global_load_dwordx4 v[164:167], v[88:89], off offset:768
	ds_read_b128 v[212:215], v245 offset:36864
	ds_read_b128 v[196:199], v244
	ds_read_b128 v[216:219], v245 offset:39168
	ds_read_b128 v[220:223], v245 offset:41472
	ds_read_b128 v[224:227], v245 offset:43776
	ds_read_b128 v[200:203], v244 offset:2304
	ds_read_b128 v[204:207], v244 offset:4608
	ds_read_b128 v[208:211], v244 offset:6912
	s_waitcnt lgkmcnt(6)
	v_mfma_f32_16x16x32_bf16 v[50:53], v[196:199], v[212:215], v[50:53]
	ds_read_b128 v[228:231], v245 offset:36928
	s_waitcnt lgkmcnt(6)
	v_mfma_f32_16x16x32_bf16 v[54:57], v[196:199], v[216:219], v[54:57]
	ds_read_b128 v[232:235], v245 offset:39232
	s_waitcnt lgkmcnt(6)
	v_mfma_f32_16x16x32_bf16 v[18:21], v[196:199], v[220:223], v[18:21]
	ds_read_b128 v[236:239], v245 offset:41536
	s_waitcnt lgkmcnt(6)
	v_mfma_f32_16x16x32_bf16 v[22:25], v[196:199], v[224:227], v[22:25]
	ds_read_b128 v[240:243], v245 offset:43840
	ds_read_b128 v[196:199], v244 offset:64
	s_waitcnt lgkmcnt(7)
	v_mfma_f32_16x16x32_bf16 v[58:61], v[200:203], v[212:215], v[58:61]
	v_mfma_f32_16x16x32_bf16 v[62:65], v[200:203], v[216:219], v[62:65]
	v_mfma_f32_16x16x32_bf16 v[26:29], v[200:203], v[220:223], v[26:29]
	v_mfma_f32_16x16x32_bf16 v[30:33], v[200:203], v[224:227], v[30:33]
	ds_read_b128 v[200:203], v244 offset:2368
	s_waitcnt lgkmcnt(7)
	v_mfma_f32_16x16x32_bf16 v[34:37], v[204:207], v[212:215], v[34:37]
	v_mfma_f32_16x16x32_bf16 v[38:41], v[204:207], v[216:219], v[38:41]
	v_mfma_f32_16x16x32_bf16 v[2:5], v[204:207], v[220:223], v[2:5]
	v_mfma_f32_16x16x32_bf16 v[6:9], v[204:207], v[224:227], v[6:9]
	ds_read_b128 v[204:207], v244 offset:4672
	s_waitcnt lgkmcnt(7)
	v_mfma_f32_16x16x32_bf16 v[42:45], v[208:211], v[212:215], v[42:45]
	v_mfma_f32_16x16x32_bf16 v[46:49], v[208:211], v[216:219], v[46:49]
	v_mfma_f32_16x16x32_bf16 v[10:13], v[208:211], v[220:223], v[10:13]
	v_mfma_f32_16x16x32_bf16 v[14:17], v[208:211], v[224:227], v[14:17]
	ds_read_b128 v[208:211], v244 offset:6976
	s_waitcnt lgkmcnt(3)
	v_mfma_f32_16x16x32_bf16 v[50:53], v[196:199], v[228:231], v[50:53]
	v_mfma_f32_16x16x32_bf16 v[54:57], v[196:199], v[232:235], v[54:57]
	v_mfma_f32_16x16x32_bf16 v[18:21], v[196:199], v[236:239], v[18:21]
	v_mfma_f32_16x16x32_bf16 v[22:25], v[196:199], v[240:243], v[22:25]
	s_waitcnt vmcnt(15)
	ds_write_b128 v98, v[102:105] offset:18432
	s_waitcnt vmcnt(14)
	ds_write_b128 v98, v[106:109] offset:23040
	s_waitcnt lgkmcnt(4)
	v_mfma_f32_16x16x32_bf16 v[58:61], v[200:203], v[228:231], v[58:61]
	v_mfma_f32_16x16x32_bf16 v[62:65], v[200:203], v[232:235], v[62:65]
	v_mfma_f32_16x16x32_bf16 v[26:29], v[200:203], v[236:239], v[26:29]
	v_mfma_f32_16x16x32_bf16 v[30:33], v[200:203], v[240:243], v[30:33]
	s_waitcnt vmcnt(13)
	ds_write_b128 v98, v[110:113] offset:27648
	s_waitcnt vmcnt(12)
	ds_write_b128 v98, v[114:117] offset:32256
	s_waitcnt lgkmcnt(5)
	v_mfma_f32_16x16x32_bf16 v[34:37], v[204:207], v[228:231], v[34:37]
	v_mfma_f32_16x16x32_bf16 v[38:41], v[204:207], v[232:235], v[38:41]
	v_mfma_f32_16x16x32_bf16 v[2:5], v[204:207], v[236:239], v[2:5]
	v_mfma_f32_16x16x32_bf16 v[6:9], v[204:207], v[240:243], v[6:9]
	s_waitcnt vmcnt(11)
	ds_write_b128 v98, v[118:121] offset:55296
	s_waitcnt vmcnt(10)
	ds_write_b128 v98, v[122:125] offset:59904
	s_waitcnt lgkmcnt(6)
	v_mfma_f32_16x16x32_bf16 v[42:45], v[208:211], v[228:231], v[42:45]
	v_mfma_f32_16x16x32_bf16 v[46:49], v[208:211], v[232:235], v[46:49]
	v_mfma_f32_16x16x32_bf16 v[10:13], v[208:211], v[236:239], v[10:13]
	v_mfma_f32_16x16x32_bf16 v[14:17], v[208:211], v[240:243], v[14:17]
	s_waitcnt vmcnt(9)
	ds_write_b128 v98, v[126:129] offset:64512
	s_waitcnt vmcnt(8)
	ds_write_b128 v99, v[132:135] offset:32256
	s_waitcnt lgkmcnt(0)
	s_barrier
	global_load_dwordx4 v[102:105], v[74:75], off offset:896
	global_load_dwordx4 v[106:109], v[76:77], off offset:896
	global_load_dwordx4 v[110:113], v[78:79], off offset:896
	global_load_dwordx4 v[114:117], v[80:81], off offset:896
	global_load_dwordx4 v[118:121], v[82:83], off offset:896
	global_load_dwordx4 v[122:125], v[84:85], off offset:896
	global_load_dwordx4 v[126:129], v[86:87], off offset:896
	global_load_dwordx4 v[132:135], v[88:89], off offset:896
	ds_read_b128 v[212:215], v245 offset:55296
	ds_read_b128 v[196:199], v244 offset:18432
	ds_read_b128 v[216:219], v245 offset:57600
	ds_read_b128 v[220:223], v245 offset:59904
	ds_read_b128 v[224:227], v245 offset:62208
	ds_read_b128 v[200:203], v244 offset:20736
	ds_read_b128 v[204:207], v244 offset:23040
	ds_read_b128 v[208:211], v244 offset:25344
	s_waitcnt lgkmcnt(6)
	v_mfma_f32_16x16x32_bf16 v[50:53], v[196:199], v[212:215], v[50:53]
	ds_read_b128 v[228:231], v245 offset:55360
	s_waitcnt lgkmcnt(6)
	v_mfma_f32_16x16x32_bf16 v[54:57], v[196:199], v[216:219], v[54:57]
	ds_read_b128 v[232:235], v245 offset:57664
	s_waitcnt lgkmcnt(6)
	v_mfma_f32_16x16x32_bf16 v[18:21], v[196:199], v[220:223], v[18:21]
	ds_read_b128 v[236:239], v245 offset:59968
	s_waitcnt lgkmcnt(6)
	v_mfma_f32_16x16x32_bf16 v[22:25], v[196:199], v[224:227], v[22:25]
	ds_read_b128 v[240:243], v245 offset:62272
	ds_read_b128 v[196:199], v244 offset:18496
	s_waitcnt lgkmcnt(7)
	v_mfma_f32_16x16x32_bf16 v[58:61], v[200:203], v[212:215], v[58:61]
	v_mfma_f32_16x16x32_bf16 v[62:65], v[200:203], v[216:219], v[62:65]
	v_mfma_f32_16x16x32_bf16 v[26:29], v[200:203], v[220:223], v[26:29]
	v_mfma_f32_16x16x32_bf16 v[30:33], v[200:203], v[224:227], v[30:33]
	ds_read_b128 v[200:203], v244 offset:20800
	s_waitcnt lgkmcnt(7)
	v_mfma_f32_16x16x32_bf16 v[34:37], v[204:207], v[212:215], v[34:37]
	v_mfma_f32_16x16x32_bf16 v[38:41], v[204:207], v[216:219], v[38:41]
	v_mfma_f32_16x16x32_bf16 v[2:5], v[204:207], v[220:223], v[2:5]
	v_mfma_f32_16x16x32_bf16 v[6:9], v[204:207], v[224:227], v[6:9]
	ds_read_b128 v[204:207], v244 offset:23104
	s_waitcnt lgkmcnt(7)
	v_mfma_f32_16x16x32_bf16 v[42:45], v[208:211], v[212:215], v[42:45]
	v_mfma_f32_16x16x32_bf16 v[46:49], v[208:211], v[216:219], v[46:49]
	v_mfma_f32_16x16x32_bf16 v[10:13], v[208:211], v[220:223], v[10:13]
	v_mfma_f32_16x16x32_bf16 v[14:17], v[208:211], v[224:227], v[14:17]
	ds_read_b128 v[208:211], v244 offset:25408
	s_waitcnt lgkmcnt(3)
	v_mfma_f32_16x16x32_bf16 v[50:53], v[196:199], v[228:231], v[50:53]
	v_mfma_f32_16x16x32_bf16 v[54:57], v[196:199], v[232:235], v[54:57]
	v_mfma_f32_16x16x32_bf16 v[18:21], v[196:199], v[236:239], v[18:21]
	v_mfma_f32_16x16x32_bf16 v[22:25], v[196:199], v[240:243], v[22:25]
	s_waitcnt vmcnt(15)
	ds_write_b128 v98, v[136:139]
	s_waitcnt vmcnt(14)
	ds_write_b128 v98, v[140:143] offset:4608
	s_waitcnt lgkmcnt(4)
	v_mfma_f32_16x16x32_bf16 v[58:61], v[200:203], v[228:231], v[58:61]
	v_mfma_f32_16x16x32_bf16 v[62:65], v[200:203], v[232:235], v[62:65]
	v_mfma_f32_16x16x32_bf16 v[26:29], v[200:203], v[236:239], v[26:29]
	v_mfma_f32_16x16x32_bf16 v[30:33], v[200:203], v[240:243], v[30:33]
	s_waitcnt vmcnt(13)
	ds_write_b128 v98, v[144:147] offset:9216
	s_waitcnt vmcnt(12)
	ds_write_b128 v98, v[148:151] offset:13824
	s_waitcnt lgkmcnt(5)
	v_mfma_f32_16x16x32_bf16 v[34:37], v[204:207], v[228:231], v[34:37]
	v_mfma_f32_16x16x32_bf16 v[38:41], v[204:207], v[232:235], v[38:41]
	v_mfma_f32_16x16x32_bf16 v[2:5], v[204:207], v[236:239], v[2:5]
	v_mfma_f32_16x16x32_bf16 v[6:9], v[204:207], v[240:243], v[6:9]
	s_waitcnt vmcnt(11)
	ds_write_b128 v98, v[152:155] offset:36864
	s_waitcnt vmcnt(10)
	ds_write_b128 v98, v[156:159] offset:41472
	s_waitcnt lgkmcnt(6)
	v_mfma_f32_16x16x32_bf16 v[42:45], v[208:211], v[228:231], v[42:45]
	v_mfma_f32_16x16x32_bf16 v[46:49], v[208:211], v[232:235], v[46:49]
	v_mfma_f32_16x16x32_bf16 v[10:13], v[208:211], v[236:239], v[10:13]
	v_mfma_f32_16x16x32_bf16 v[14:17], v[208:211], v[240:243], v[14:17]
	s_waitcnt vmcnt(9)
	ds_write_b128 v98, v[160:163] offset:46080
	s_waitcnt vmcnt(8)
	ds_write_b128 v98, v[164:167] offset:50688
	s_waitcnt lgkmcnt(0)
	s_barrier
	global_load_dwordx4 v[136:139], v[74:75], off offset:1024
	global_load_dwordx4 v[140:143], v[76:77], off offset:1024
	global_load_dwordx4 v[144:147], v[78:79], off offset:1024
	global_load_dwordx4 v[148:151], v[80:81], off offset:1024
	global_load_dwordx4 v[152:155], v[82:83], off offset:1024
	global_load_dwordx4 v[156:159], v[84:85], off offset:1024
	global_load_dwordx4 v[160:163], v[86:87], off offset:1024
	global_load_dwordx4 v[164:167], v[88:89], off offset:1024
	ds_read_b128 v[212:215], v245 offset:36864
	ds_read_b128 v[196:199], v244
	ds_read_b128 v[216:219], v245 offset:39168
	ds_read_b128 v[220:223], v245 offset:41472
	ds_read_b128 v[224:227], v245 offset:43776
	ds_read_b128 v[200:203], v244 offset:2304
	ds_read_b128 v[204:207], v244 offset:4608
	ds_read_b128 v[208:211], v244 offset:6912
	s_waitcnt lgkmcnt(6)
	v_mfma_f32_16x16x32_bf16 v[50:53], v[196:199], v[212:215], v[50:53]
	ds_read_b128 v[228:231], v245 offset:36928
	s_waitcnt lgkmcnt(6)
	v_mfma_f32_16x16x32_bf16 v[54:57], v[196:199], v[216:219], v[54:57]
	ds_read_b128 v[232:235], v245 offset:39232
	s_waitcnt lgkmcnt(6)
	v_mfma_f32_16x16x32_bf16 v[18:21], v[196:199], v[220:223], v[18:21]
	ds_read_b128 v[236:239], v245 offset:41536
	s_waitcnt lgkmcnt(6)
	v_mfma_f32_16x16x32_bf16 v[22:25], v[196:199], v[224:227], v[22:25]
	ds_read_b128 v[240:243], v245 offset:43840
	ds_read_b128 v[196:199], v244 offset:64
	s_waitcnt lgkmcnt(7)
	v_mfma_f32_16x16x32_bf16 v[58:61], v[200:203], v[212:215], v[58:61]
	v_mfma_f32_16x16x32_bf16 v[62:65], v[200:203], v[216:219], v[62:65]
	v_mfma_f32_16x16x32_bf16 v[26:29], v[200:203], v[220:223], v[26:29]
	v_mfma_f32_16x16x32_bf16 v[30:33], v[200:203], v[224:227], v[30:33]
	ds_read_b128 v[200:203], v244 offset:2368
	s_waitcnt lgkmcnt(7)
	v_mfma_f32_16x16x32_bf16 v[34:37], v[204:207], v[212:215], v[34:37]
	v_mfma_f32_16x16x32_bf16 v[38:41], v[204:207], v[216:219], v[38:41]
	v_mfma_f32_16x16x32_bf16 v[2:5], v[204:207], v[220:223], v[2:5]
	v_mfma_f32_16x16x32_bf16 v[6:9], v[204:207], v[224:227], v[6:9]
	ds_read_b128 v[204:207], v244 offset:4672
	s_waitcnt lgkmcnt(7)
	v_mfma_f32_16x16x32_bf16 v[42:45], v[208:211], v[212:215], v[42:45]
	v_mfma_f32_16x16x32_bf16 v[46:49], v[208:211], v[216:219], v[46:49]
	v_mfma_f32_16x16x32_bf16 v[10:13], v[208:211], v[220:223], v[10:13]
	v_mfma_f32_16x16x32_bf16 v[14:17], v[208:211], v[224:227], v[14:17]
	ds_read_b128 v[208:211], v244 offset:6976
	s_waitcnt lgkmcnt(3)
	v_mfma_f32_16x16x32_bf16 v[50:53], v[196:199], v[228:231], v[50:53]
	v_mfma_f32_16x16x32_bf16 v[54:57], v[196:199], v[232:235], v[54:57]
	v_mfma_f32_16x16x32_bf16 v[18:21], v[196:199], v[236:239], v[18:21]
	v_mfma_f32_16x16x32_bf16 v[22:25], v[196:199], v[240:243], v[22:25]
	s_waitcnt vmcnt(15)
	ds_write_b128 v98, v[102:105] offset:18432
	s_waitcnt vmcnt(14)
	ds_write_b128 v98, v[106:109] offset:23040
	s_waitcnt lgkmcnt(4)
	v_mfma_f32_16x16x32_bf16 v[58:61], v[200:203], v[228:231], v[58:61]
	v_mfma_f32_16x16x32_bf16 v[62:65], v[200:203], v[232:235], v[62:65]
	v_mfma_f32_16x16x32_bf16 v[26:29], v[200:203], v[236:239], v[26:29]
	v_mfma_f32_16x16x32_bf16 v[30:33], v[200:203], v[240:243], v[30:33]
	s_waitcnt vmcnt(13)
	ds_write_b128 v98, v[110:113] offset:27648
	s_waitcnt vmcnt(12)
	ds_write_b128 v98, v[114:117] offset:32256
	s_waitcnt lgkmcnt(5)
	v_mfma_f32_16x16x32_bf16 v[34:37], v[204:207], v[228:231], v[34:37]
	v_mfma_f32_16x16x32_bf16 v[38:41], v[204:207], v[232:235], v[38:41]
	v_mfma_f32_16x16x32_bf16 v[2:5], v[204:207], v[236:239], v[2:5]
	v_mfma_f32_16x16x32_bf16 v[6:9], v[204:207], v[240:243], v[6:9]
	s_waitcnt vmcnt(11)
	ds_write_b128 v98, v[118:121] offset:55296
	s_waitcnt vmcnt(10)
	ds_write_b128 v98, v[122:125] offset:59904
	s_waitcnt lgkmcnt(6)
	v_mfma_f32_16x16x32_bf16 v[42:45], v[208:211], v[228:231], v[42:45]
	v_mfma_f32_16x16x32_bf16 v[46:49], v[208:211], v[232:235], v[46:49]
	v_mfma_f32_16x16x32_bf16 v[10:13], v[208:211], v[236:239], v[10:13]
	v_mfma_f32_16x16x32_bf16 v[14:17], v[208:211], v[240:243], v[14:17]
	s_waitcnt vmcnt(9)
	ds_write_b128 v98, v[126:129] offset:64512
	s_waitcnt vmcnt(8)
	ds_write_b128 v99, v[132:135] offset:32256
	s_waitcnt lgkmcnt(0)
	s_barrier
	global_load_dwordx4 v[102:105], v[74:75], off offset:1152
	global_load_dwordx4 v[106:109], v[76:77], off offset:1152
	global_load_dwordx4 v[110:113], v[78:79], off offset:1152
	global_load_dwordx4 v[114:117], v[80:81], off offset:1152
	global_load_dwordx4 v[118:121], v[82:83], off offset:1152
	global_load_dwordx4 v[122:125], v[84:85], off offset:1152
	global_load_dwordx4 v[126:129], v[86:87], off offset:1152
	global_load_dwordx4 v[132:135], v[88:89], off offset:1152
	ds_read_b128 v[212:215], v245 offset:55296
	ds_read_b128 v[196:199], v244 offset:18432
	ds_read_b128 v[216:219], v245 offset:57600
	ds_read_b128 v[220:223], v245 offset:59904
	ds_read_b128 v[224:227], v245 offset:62208
	ds_read_b128 v[200:203], v244 offset:20736
	ds_read_b128 v[204:207], v244 offset:23040
	ds_read_b128 v[208:211], v244 offset:25344
	s_waitcnt lgkmcnt(6)
	v_mfma_f32_16x16x32_bf16 v[50:53], v[196:199], v[212:215], v[50:53]
	ds_read_b128 v[228:231], v245 offset:55360
	s_waitcnt lgkmcnt(6)
	v_mfma_f32_16x16x32_bf16 v[54:57], v[196:199], v[216:219], v[54:57]
	ds_read_b128 v[232:235], v245 offset:57664
	s_waitcnt lgkmcnt(6)
	v_mfma_f32_16x16x32_bf16 v[18:21], v[196:199], v[220:223], v[18:21]
	ds_read_b128 v[236:239], v245 offset:59968
	s_waitcnt lgkmcnt(6)
	v_mfma_f32_16x16x32_bf16 v[22:25], v[196:199], v[224:227], v[22:25]
	ds_read_b128 v[240:243], v245 offset:62272
	ds_read_b128 v[196:199], v244 offset:18496
	s_waitcnt lgkmcnt(7)
	v_mfma_f32_16x16x32_bf16 v[58:61], v[200:203], v[212:215], v[58:61]
	v_mfma_f32_16x16x32_bf16 v[62:65], v[200:203], v[216:219], v[62:65]
	v_mfma_f32_16x16x32_bf16 v[26:29], v[200:203], v[220:223], v[26:29]
	v_mfma_f32_16x16x32_bf16 v[30:33], v[200:203], v[224:227], v[30:33]
	ds_read_b128 v[200:203], v244 offset:20800
	s_waitcnt lgkmcnt(7)
	v_mfma_f32_16x16x32_bf16 v[34:37], v[204:207], v[212:215], v[34:37]
	v_mfma_f32_16x16x32_bf16 v[38:41], v[204:207], v[216:219], v[38:41]
	v_mfma_f32_16x16x32_bf16 v[2:5], v[204:207], v[220:223], v[2:5]
	v_mfma_f32_16x16x32_bf16 v[6:9], v[204:207], v[224:227], v[6:9]
	ds_read_b128 v[204:207], v244 offset:23104
	s_waitcnt lgkmcnt(7)
	v_mfma_f32_16x16x32_bf16 v[42:45], v[208:211], v[212:215], v[42:45]
	v_mfma_f32_16x16x32_bf16 v[46:49], v[208:211], v[216:219], v[46:49]
	v_mfma_f32_16x16x32_bf16 v[10:13], v[208:211], v[220:223], v[10:13]
	v_mfma_f32_16x16x32_bf16 v[14:17], v[208:211], v[224:227], v[14:17]
	ds_read_b128 v[208:211], v244 offset:25408
	s_waitcnt lgkmcnt(3)
	v_mfma_f32_16x16x32_bf16 v[50:53], v[196:199], v[228:231], v[50:53]
	v_mfma_f32_16x16x32_bf16 v[54:57], v[196:199], v[232:235], v[54:57]
	v_mfma_f32_16x16x32_bf16 v[18:21], v[196:199], v[236:239], v[18:21]
	v_mfma_f32_16x16x32_bf16 v[22:25], v[196:199], v[240:243], v[22:25]
	s_waitcnt vmcnt(15)
	ds_write_b128 v98, v[136:139]
	s_waitcnt vmcnt(14)
	ds_write_b128 v98, v[140:143] offset:4608
	s_waitcnt lgkmcnt(4)
	v_mfma_f32_16x16x32_bf16 v[58:61], v[200:203], v[228:231], v[58:61]
	v_mfma_f32_16x16x32_bf16 v[62:65], v[200:203], v[232:235], v[62:65]
	v_mfma_f32_16x16x32_bf16 v[26:29], v[200:203], v[236:239], v[26:29]
	v_mfma_f32_16x16x32_bf16 v[30:33], v[200:203], v[240:243], v[30:33]
	s_waitcnt vmcnt(13)
	ds_write_b128 v98, v[144:147] offset:9216
	s_waitcnt vmcnt(12)
	ds_write_b128 v98, v[148:151] offset:13824
	s_waitcnt lgkmcnt(5)
	v_mfma_f32_16x16x32_bf16 v[34:37], v[204:207], v[228:231], v[34:37]
	v_mfma_f32_16x16x32_bf16 v[38:41], v[204:207], v[232:235], v[38:41]
	v_mfma_f32_16x16x32_bf16 v[2:5], v[204:207], v[236:239], v[2:5]
	v_mfma_f32_16x16x32_bf16 v[6:9], v[204:207], v[240:243], v[6:9]
	s_waitcnt vmcnt(11)
	ds_write_b128 v98, v[152:155] offset:36864
	s_waitcnt vmcnt(10)
	ds_write_b128 v98, v[156:159] offset:41472
	s_waitcnt lgkmcnt(6)
	v_mfma_f32_16x16x32_bf16 v[42:45], v[208:211], v[228:231], v[42:45]
	v_mfma_f32_16x16x32_bf16 v[46:49], v[208:211], v[232:235], v[46:49]
	v_mfma_f32_16x16x32_bf16 v[10:13], v[208:211], v[236:239], v[10:13]
	v_mfma_f32_16x16x32_bf16 v[14:17], v[208:211], v[240:243], v[14:17]
	s_waitcnt vmcnt(9)
	ds_write_b128 v98, v[160:163] offset:46080
	s_waitcnt vmcnt(8)
	ds_write_b128 v98, v[164:167] offset:50688
	s_waitcnt lgkmcnt(0)
	s_barrier
	global_load_dwordx4 v[136:139], v[74:75], off offset:1280
	global_load_dwordx4 v[140:143], v[76:77], off offset:1280
	global_load_dwordx4 v[144:147], v[78:79], off offset:1280
	global_load_dwordx4 v[148:151], v[80:81], off offset:1280
	global_load_dwordx4 v[152:155], v[82:83], off offset:1280
	global_load_dwordx4 v[156:159], v[84:85], off offset:1280
	global_load_dwordx4 v[160:163], v[86:87], off offset:1280
	global_load_dwordx4 v[164:167], v[88:89], off offset:1280
	ds_read_b128 v[212:215], v245 offset:36864
	ds_read_b128 v[196:199], v244
	ds_read_b128 v[216:219], v245 offset:39168
	ds_read_b128 v[220:223], v245 offset:41472
	ds_read_b128 v[224:227], v245 offset:43776
	ds_read_b128 v[200:203], v244 offset:2304
	ds_read_b128 v[204:207], v244 offset:4608
	ds_read_b128 v[208:211], v244 offset:6912
	s_waitcnt lgkmcnt(6)
	v_mfma_f32_16x16x32_bf16 v[50:53], v[196:199], v[212:215], v[50:53]
	ds_read_b128 v[228:231], v245 offset:36928
	s_waitcnt lgkmcnt(6)
	v_mfma_f32_16x16x32_bf16 v[54:57], v[196:199], v[216:219], v[54:57]
	ds_read_b128 v[232:235], v245 offset:39232
	s_waitcnt lgkmcnt(6)
	v_mfma_f32_16x16x32_bf16 v[18:21], v[196:199], v[220:223], v[18:21]
	ds_read_b128 v[236:239], v245 offset:41536
	s_waitcnt lgkmcnt(6)
	v_mfma_f32_16x16x32_bf16 v[22:25], v[196:199], v[224:227], v[22:25]
	ds_read_b128 v[240:243], v245 offset:43840
	ds_read_b128 v[196:199], v244 offset:64
	s_waitcnt lgkmcnt(7)
	v_mfma_f32_16x16x32_bf16 v[58:61], v[200:203], v[212:215], v[58:61]
	v_mfma_f32_16x16x32_bf16 v[62:65], v[200:203], v[216:219], v[62:65]
	v_mfma_f32_16x16x32_bf16 v[26:29], v[200:203], v[220:223], v[26:29]
	v_mfma_f32_16x16x32_bf16 v[30:33], v[200:203], v[224:227], v[30:33]
	ds_read_b128 v[200:203], v244 offset:2368
	s_waitcnt lgkmcnt(7)
	v_mfma_f32_16x16x32_bf16 v[34:37], v[204:207], v[212:215], v[34:37]
	v_mfma_f32_16x16x32_bf16 v[38:41], v[204:207], v[216:219], v[38:41]
	v_mfma_f32_16x16x32_bf16 v[2:5], v[204:207], v[220:223], v[2:5]
	v_mfma_f32_16x16x32_bf16 v[6:9], v[204:207], v[224:227], v[6:9]
	ds_read_b128 v[204:207], v244 offset:4672
	s_waitcnt lgkmcnt(7)
	v_mfma_f32_16x16x32_bf16 v[42:45], v[208:211], v[212:215], v[42:45]
	v_mfma_f32_16x16x32_bf16 v[46:49], v[208:211], v[216:219], v[46:49]
	v_mfma_f32_16x16x32_bf16 v[10:13], v[208:211], v[220:223], v[10:13]
	v_mfma_f32_16x16x32_bf16 v[14:17], v[208:211], v[224:227], v[14:17]
	ds_read_b128 v[208:211], v244 offset:6976
	s_waitcnt lgkmcnt(3)
	v_mfma_f32_16x16x32_bf16 v[50:53], v[196:199], v[228:231], v[50:53]
	v_mfma_f32_16x16x32_bf16 v[54:57], v[196:199], v[232:235], v[54:57]
	v_mfma_f32_16x16x32_bf16 v[18:21], v[196:199], v[236:239], v[18:21]
	v_mfma_f32_16x16x32_bf16 v[22:25], v[196:199], v[240:243], v[22:25]
	s_waitcnt vmcnt(15)
	ds_write_b128 v98, v[102:105] offset:18432
	s_waitcnt vmcnt(14)
	ds_write_b128 v98, v[106:109] offset:23040
	s_waitcnt lgkmcnt(4)
	v_mfma_f32_16x16x32_bf16 v[58:61], v[200:203], v[228:231], v[58:61]
	v_mfma_f32_16x16x32_bf16 v[62:65], v[200:203], v[232:235], v[62:65]
	v_mfma_f32_16x16x32_bf16 v[26:29], v[200:203], v[236:239], v[26:29]
	v_mfma_f32_16x16x32_bf16 v[30:33], v[200:203], v[240:243], v[30:33]
	s_waitcnt vmcnt(13)
	ds_write_b128 v98, v[110:113] offset:27648
	s_waitcnt vmcnt(12)
	ds_write_b128 v98, v[114:117] offset:32256
	s_waitcnt lgkmcnt(5)
	v_mfma_f32_16x16x32_bf16 v[34:37], v[204:207], v[228:231], v[34:37]
	v_mfma_f32_16x16x32_bf16 v[38:41], v[204:207], v[232:235], v[38:41]
	v_mfma_f32_16x16x32_bf16 v[2:5], v[204:207], v[236:239], v[2:5]
	v_mfma_f32_16x16x32_bf16 v[6:9], v[204:207], v[240:243], v[6:9]
	s_waitcnt vmcnt(11)
	ds_write_b128 v98, v[118:121] offset:55296
	s_waitcnt vmcnt(10)
	ds_write_b128 v98, v[122:125] offset:59904
	s_waitcnt lgkmcnt(6)
	v_mfma_f32_16x16x32_bf16 v[42:45], v[208:211], v[228:231], v[42:45]
	v_mfma_f32_16x16x32_bf16 v[46:49], v[208:211], v[232:235], v[46:49]
	v_mfma_f32_16x16x32_bf16 v[10:13], v[208:211], v[236:239], v[10:13]
	v_mfma_f32_16x16x32_bf16 v[14:17], v[208:211], v[240:243], v[14:17]
	s_waitcnt vmcnt(9)
	ds_write_b128 v98, v[126:129] offset:64512
	s_waitcnt vmcnt(8)
	ds_write_b128 v99, v[132:135] offset:32256
	s_waitcnt lgkmcnt(0)
	s_barrier
	global_load_dwordx4 v[102:105], v[74:75], off offset:1408
	global_load_dwordx4 v[106:109], v[76:77], off offset:1408
	global_load_dwordx4 v[110:113], v[78:79], off offset:1408
	global_load_dwordx4 v[114:117], v[80:81], off offset:1408
	global_load_dwordx4 v[118:121], v[82:83], off offset:1408
	global_load_dwordx4 v[122:125], v[84:85], off offset:1408
	global_load_dwordx4 v[126:129], v[86:87], off offset:1408
	global_load_dwordx4 v[132:135], v[88:89], off offset:1408
	ds_read_b128 v[212:215], v245 offset:55296
	ds_read_b128 v[196:199], v244 offset:18432
	ds_read_b128 v[216:219], v245 offset:57600
	ds_read_b128 v[220:223], v245 offset:59904
	ds_read_b128 v[224:227], v245 offset:62208
	ds_read_b128 v[200:203], v244 offset:20736
	ds_read_b128 v[204:207], v244 offset:23040
	ds_read_b128 v[208:211], v244 offset:25344
	s_waitcnt lgkmcnt(6)
	v_mfma_f32_16x16x32_bf16 v[50:53], v[196:199], v[212:215], v[50:53]
	ds_read_b128 v[228:231], v245 offset:55360
	s_waitcnt lgkmcnt(6)
	v_mfma_f32_16x16x32_bf16 v[54:57], v[196:199], v[216:219], v[54:57]
	ds_read_b128 v[232:235], v245 offset:57664
	s_waitcnt lgkmcnt(6)
	v_mfma_f32_16x16x32_bf16 v[18:21], v[196:199], v[220:223], v[18:21]
	ds_read_b128 v[236:239], v245 offset:59968
	s_waitcnt lgkmcnt(6)
	v_mfma_f32_16x16x32_bf16 v[22:25], v[196:199], v[224:227], v[22:25]
	ds_read_b128 v[240:243], v245 offset:62272
	ds_read_b128 v[196:199], v244 offset:18496
	s_waitcnt lgkmcnt(7)
	v_mfma_f32_16x16x32_bf16 v[58:61], v[200:203], v[212:215], v[58:61]
	v_mfma_f32_16x16x32_bf16 v[62:65], v[200:203], v[216:219], v[62:65]
	v_mfma_f32_16x16x32_bf16 v[26:29], v[200:203], v[220:223], v[26:29]
	v_mfma_f32_16x16x32_bf16 v[30:33], v[200:203], v[224:227], v[30:33]
	ds_read_b128 v[200:203], v244 offset:20800
	s_waitcnt lgkmcnt(7)
	v_mfma_f32_16x16x32_bf16 v[34:37], v[204:207], v[212:215], v[34:37]
	v_mfma_f32_16x16x32_bf16 v[38:41], v[204:207], v[216:219], v[38:41]
	v_mfma_f32_16x16x32_bf16 v[2:5], v[204:207], v[220:223], v[2:5]
	v_mfma_f32_16x16x32_bf16 v[6:9], v[204:207], v[224:227], v[6:9]
	ds_read_b128 v[204:207], v244 offset:23104
	s_waitcnt lgkmcnt(7)
	v_mfma_f32_16x16x32_bf16 v[42:45], v[208:211], v[212:215], v[42:45]
	v_mfma_f32_16x16x32_bf16 v[46:49], v[208:211], v[216:219], v[46:49]
	v_mfma_f32_16x16x32_bf16 v[10:13], v[208:211], v[220:223], v[10:13]
	v_mfma_f32_16x16x32_bf16 v[14:17], v[208:211], v[224:227], v[14:17]
	ds_read_b128 v[208:211], v244 offset:25408
	s_waitcnt lgkmcnt(3)
	v_mfma_f32_16x16x32_bf16 v[50:53], v[196:199], v[228:231], v[50:53]
	v_mfma_f32_16x16x32_bf16 v[54:57], v[196:199], v[232:235], v[54:57]
	v_mfma_f32_16x16x32_bf16 v[18:21], v[196:199], v[236:239], v[18:21]
	v_mfma_f32_16x16x32_bf16 v[22:25], v[196:199], v[240:243], v[22:25]
	s_waitcnt vmcnt(15)
	ds_write_b128 v98, v[136:139]
	s_waitcnt vmcnt(14)
	ds_write_b128 v98, v[140:143] offset:4608
	s_waitcnt lgkmcnt(4)
	v_mfma_f32_16x16x32_bf16 v[58:61], v[200:203], v[228:231], v[58:61]
	v_mfma_f32_16x16x32_bf16 v[62:65], v[200:203], v[232:235], v[62:65]
	v_mfma_f32_16x16x32_bf16 v[26:29], v[200:203], v[236:239], v[26:29]
	v_mfma_f32_16x16x32_bf16 v[30:33], v[200:203], v[240:243], v[30:33]
	s_waitcnt vmcnt(13)
	ds_write_b128 v98, v[144:147] offset:9216
	s_waitcnt vmcnt(12)
	ds_write_b128 v98, v[148:151] offset:13824
	s_waitcnt lgkmcnt(5)
	v_mfma_f32_16x16x32_bf16 v[34:37], v[204:207], v[228:231], v[34:37]
	v_mfma_f32_16x16x32_bf16 v[38:41], v[204:207], v[232:235], v[38:41]
	v_mfma_f32_16x16x32_bf16 v[2:5], v[204:207], v[236:239], v[2:5]
	v_mfma_f32_16x16x32_bf16 v[6:9], v[204:207], v[240:243], v[6:9]
	s_waitcnt vmcnt(11)
	ds_write_b128 v98, v[152:155] offset:36864
	s_waitcnt vmcnt(10)
	ds_write_b128 v98, v[156:159] offset:41472
	s_waitcnt lgkmcnt(6)
	v_mfma_f32_16x16x32_bf16 v[42:45], v[208:211], v[228:231], v[42:45]
	v_mfma_f32_16x16x32_bf16 v[46:49], v[208:211], v[232:235], v[46:49]
	v_mfma_f32_16x16x32_bf16 v[10:13], v[208:211], v[236:239], v[10:13]
	v_mfma_f32_16x16x32_bf16 v[14:17], v[208:211], v[240:243], v[14:17]
	s_waitcnt vmcnt(9)
	ds_write_b128 v98, v[160:163] offset:46080
	s_waitcnt vmcnt(8)
	ds_write_b128 v98, v[164:167] offset:50688
	s_waitcnt lgkmcnt(0)
	s_barrier
	global_load_dwordx4 v[136:139], v[74:75], off offset:1536
	global_load_dwordx4 v[140:143], v[76:77], off offset:1536
	global_load_dwordx4 v[144:147], v[78:79], off offset:1536
	global_load_dwordx4 v[148:151], v[80:81], off offset:1536
	global_load_dwordx4 v[152:155], v[82:83], off offset:1536
	global_load_dwordx4 v[156:159], v[84:85], off offset:1536
	global_load_dwordx4 v[160:163], v[86:87], off offset:1536
	global_load_dwordx4 v[164:167], v[88:89], off offset:1536
	ds_read_b128 v[212:215], v245 offset:36864
	ds_read_b128 v[196:199], v244
	ds_read_b128 v[216:219], v245 offset:39168
	ds_read_b128 v[220:223], v245 offset:41472
	ds_read_b128 v[224:227], v245 offset:43776
	ds_read_b128 v[200:203], v244 offset:2304
	ds_read_b128 v[204:207], v244 offset:4608
	ds_read_b128 v[208:211], v244 offset:6912
	s_waitcnt lgkmcnt(6)
	v_mfma_f32_16x16x32_bf16 v[50:53], v[196:199], v[212:215], v[50:53]
	ds_read_b128 v[228:231], v245 offset:36928
	s_waitcnt lgkmcnt(6)
	v_mfma_f32_16x16x32_bf16 v[54:57], v[196:199], v[216:219], v[54:57]
	ds_read_b128 v[232:235], v245 offset:39232
	s_waitcnt lgkmcnt(6)
	v_mfma_f32_16x16x32_bf16 v[18:21], v[196:199], v[220:223], v[18:21]
	ds_read_b128 v[236:239], v245 offset:41536
	s_waitcnt lgkmcnt(6)
	v_mfma_f32_16x16x32_bf16 v[22:25], v[196:199], v[224:227], v[22:25]
	ds_read_b128 v[240:243], v245 offset:43840
	ds_read_b128 v[196:199], v244 offset:64
	s_waitcnt lgkmcnt(7)
	v_mfma_f32_16x16x32_bf16 v[58:61], v[200:203], v[212:215], v[58:61]
	v_mfma_f32_16x16x32_bf16 v[62:65], v[200:203], v[216:219], v[62:65]
	v_mfma_f32_16x16x32_bf16 v[26:29], v[200:203], v[220:223], v[26:29]
	v_mfma_f32_16x16x32_bf16 v[30:33], v[200:203], v[224:227], v[30:33]
	ds_read_b128 v[200:203], v244 offset:2368
	s_waitcnt lgkmcnt(7)
	v_mfma_f32_16x16x32_bf16 v[34:37], v[204:207], v[212:215], v[34:37]
	v_mfma_f32_16x16x32_bf16 v[38:41], v[204:207], v[216:219], v[38:41]
	v_mfma_f32_16x16x32_bf16 v[2:5], v[204:207], v[220:223], v[2:5]
	v_mfma_f32_16x16x32_bf16 v[6:9], v[204:207], v[224:227], v[6:9]
	ds_read_b128 v[204:207], v244 offset:4672
	s_waitcnt lgkmcnt(7)
	v_mfma_f32_16x16x32_bf16 v[42:45], v[208:211], v[212:215], v[42:45]
	v_mfma_f32_16x16x32_bf16 v[46:49], v[208:211], v[216:219], v[46:49]
	v_mfma_f32_16x16x32_bf16 v[10:13], v[208:211], v[220:223], v[10:13]
	v_mfma_f32_16x16x32_bf16 v[14:17], v[208:211], v[224:227], v[14:17]
	ds_read_b128 v[208:211], v244 offset:6976
	s_waitcnt lgkmcnt(3)
	v_mfma_f32_16x16x32_bf16 v[50:53], v[196:199], v[228:231], v[50:53]
	v_mfma_f32_16x16x32_bf16 v[54:57], v[196:199], v[232:235], v[54:57]
	v_mfma_f32_16x16x32_bf16 v[18:21], v[196:199], v[236:239], v[18:21]
	v_mfma_f32_16x16x32_bf16 v[22:25], v[196:199], v[240:243], v[22:25]
	s_waitcnt vmcnt(15)
	ds_write_b128 v98, v[102:105] offset:18432
	s_waitcnt vmcnt(14)
	ds_write_b128 v98, v[106:109] offset:23040
	s_waitcnt lgkmcnt(4)
	v_mfma_f32_16x16x32_bf16 v[58:61], v[200:203], v[228:231], v[58:61]
	v_mfma_f32_16x16x32_bf16 v[62:65], v[200:203], v[232:235], v[62:65]
	v_mfma_f32_16x16x32_bf16 v[26:29], v[200:203], v[236:239], v[26:29]
	v_mfma_f32_16x16x32_bf16 v[30:33], v[200:203], v[240:243], v[30:33]
	s_waitcnt vmcnt(13)
	ds_write_b128 v98, v[110:113] offset:27648
	s_waitcnt vmcnt(12)
	ds_write_b128 v98, v[114:117] offset:32256
	s_waitcnt lgkmcnt(5)
	v_mfma_f32_16x16x32_bf16 v[34:37], v[204:207], v[228:231], v[34:37]
	v_mfma_f32_16x16x32_bf16 v[38:41], v[204:207], v[232:235], v[38:41]
	v_mfma_f32_16x16x32_bf16 v[2:5], v[204:207], v[236:239], v[2:5]
	v_mfma_f32_16x16x32_bf16 v[6:9], v[204:207], v[240:243], v[6:9]
	s_waitcnt vmcnt(11)
	ds_write_b128 v98, v[118:121] offset:55296
	s_waitcnt vmcnt(10)
	ds_write_b128 v98, v[122:125] offset:59904
	s_waitcnt lgkmcnt(6)
	v_mfma_f32_16x16x32_bf16 v[42:45], v[208:211], v[228:231], v[42:45]
	v_mfma_f32_16x16x32_bf16 v[46:49], v[208:211], v[232:235], v[46:49]
	v_mfma_f32_16x16x32_bf16 v[10:13], v[208:211], v[236:239], v[10:13]
	v_mfma_f32_16x16x32_bf16 v[14:17], v[208:211], v[240:243], v[14:17]
	s_waitcnt vmcnt(9)
	ds_write_b128 v98, v[126:129] offset:64512
	s_waitcnt vmcnt(8)
	ds_write_b128 v99, v[132:135] offset:32256
	s_waitcnt lgkmcnt(0)
	s_barrier
	global_load_dwordx4 v[102:105], v[74:75], off offset:1664
	global_load_dwordx4 v[106:109], v[76:77], off offset:1664
	global_load_dwordx4 v[110:113], v[78:79], off offset:1664
	global_load_dwordx4 v[114:117], v[80:81], off offset:1664
	global_load_dwordx4 v[118:121], v[82:83], off offset:1664
	global_load_dwordx4 v[122:125], v[84:85], off offset:1664
	global_load_dwordx4 v[126:129], v[86:87], off offset:1664
	global_load_dwordx4 v[132:135], v[88:89], off offset:1664
	ds_read_b128 v[212:215], v245 offset:55296
	ds_read_b128 v[196:199], v244 offset:18432
	ds_read_b128 v[216:219], v245 offset:57600
	ds_read_b128 v[220:223], v245 offset:59904
	ds_read_b128 v[224:227], v245 offset:62208
	ds_read_b128 v[200:203], v244 offset:20736
	ds_read_b128 v[204:207], v244 offset:23040
	ds_read_b128 v[208:211], v244 offset:25344
	s_waitcnt lgkmcnt(6)
	v_mfma_f32_16x16x32_bf16 v[50:53], v[196:199], v[212:215], v[50:53]
	ds_read_b128 v[228:231], v245 offset:55360
	s_waitcnt lgkmcnt(6)
	v_mfma_f32_16x16x32_bf16 v[54:57], v[196:199], v[216:219], v[54:57]
	ds_read_b128 v[232:235], v245 offset:57664
	s_waitcnt lgkmcnt(6)
	v_mfma_f32_16x16x32_bf16 v[18:21], v[196:199], v[220:223], v[18:21]
	ds_read_b128 v[236:239], v245 offset:59968
	s_waitcnt lgkmcnt(6)
	v_mfma_f32_16x16x32_bf16 v[22:25], v[196:199], v[224:227], v[22:25]
	ds_read_b128 v[240:243], v245 offset:62272
	ds_read_b128 v[196:199], v244 offset:18496
	s_waitcnt lgkmcnt(7)
	v_mfma_f32_16x16x32_bf16 v[58:61], v[200:203], v[212:215], v[58:61]
	v_mfma_f32_16x16x32_bf16 v[62:65], v[200:203], v[216:219], v[62:65]
	v_mfma_f32_16x16x32_bf16 v[26:29], v[200:203], v[220:223], v[26:29]
	v_mfma_f32_16x16x32_bf16 v[30:33], v[200:203], v[224:227], v[30:33]
	ds_read_b128 v[200:203], v244 offset:20800
	s_waitcnt lgkmcnt(7)
	v_mfma_f32_16x16x32_bf16 v[34:37], v[204:207], v[212:215], v[34:37]
	v_mfma_f32_16x16x32_bf16 v[38:41], v[204:207], v[216:219], v[38:41]
	v_mfma_f32_16x16x32_bf16 v[2:5], v[204:207], v[220:223], v[2:5]
	v_mfma_f32_16x16x32_bf16 v[6:9], v[204:207], v[224:227], v[6:9]
	ds_read_b128 v[204:207], v244 offset:23104
	s_waitcnt lgkmcnt(7)
	v_mfma_f32_16x16x32_bf16 v[42:45], v[208:211], v[212:215], v[42:45]
	v_mfma_f32_16x16x32_bf16 v[46:49], v[208:211], v[216:219], v[46:49]
	v_mfma_f32_16x16x32_bf16 v[10:13], v[208:211], v[220:223], v[10:13]
	v_mfma_f32_16x16x32_bf16 v[14:17], v[208:211], v[224:227], v[14:17]
	ds_read_b128 v[208:211], v244 offset:25408
	s_waitcnt lgkmcnt(3)
	v_mfma_f32_16x16x32_bf16 v[50:53], v[196:199], v[228:231], v[50:53]
	v_mfma_f32_16x16x32_bf16 v[54:57], v[196:199], v[232:235], v[54:57]
	v_mfma_f32_16x16x32_bf16 v[18:21], v[196:199], v[236:239], v[18:21]
	v_mfma_f32_16x16x32_bf16 v[22:25], v[196:199], v[240:243], v[22:25]
	s_waitcnt vmcnt(15)
	ds_write_b128 v98, v[136:139]
	s_waitcnt vmcnt(14)
	ds_write_b128 v98, v[140:143] offset:4608
	s_waitcnt lgkmcnt(4)
	v_mfma_f32_16x16x32_bf16 v[58:61], v[200:203], v[228:231], v[58:61]
	v_mfma_f32_16x16x32_bf16 v[62:65], v[200:203], v[232:235], v[62:65]
	v_mfma_f32_16x16x32_bf16 v[26:29], v[200:203], v[236:239], v[26:29]
	v_mfma_f32_16x16x32_bf16 v[30:33], v[200:203], v[240:243], v[30:33]
	s_waitcnt vmcnt(13)
	ds_write_b128 v98, v[144:147] offset:9216
	s_waitcnt vmcnt(12)
	ds_write_b128 v98, v[148:151] offset:13824
	s_waitcnt lgkmcnt(5)
	v_mfma_f32_16x16x32_bf16 v[34:37], v[204:207], v[228:231], v[34:37]
	v_mfma_f32_16x16x32_bf16 v[38:41], v[204:207], v[232:235], v[38:41]
	v_mfma_f32_16x16x32_bf16 v[2:5], v[204:207], v[236:239], v[2:5]
	v_mfma_f32_16x16x32_bf16 v[6:9], v[204:207], v[240:243], v[6:9]
	s_waitcnt vmcnt(11)
	ds_write_b128 v98, v[152:155] offset:36864
	s_waitcnt vmcnt(10)
	ds_write_b128 v98, v[156:159] offset:41472
	s_waitcnt lgkmcnt(6)
	v_mfma_f32_16x16x32_bf16 v[42:45], v[208:211], v[228:231], v[42:45]
	v_mfma_f32_16x16x32_bf16 v[46:49], v[208:211], v[232:235], v[46:49]
	v_mfma_f32_16x16x32_bf16 v[10:13], v[208:211], v[236:239], v[10:13]
	v_mfma_f32_16x16x32_bf16 v[14:17], v[208:211], v[240:243], v[14:17]
	s_waitcnt vmcnt(9)
	ds_write_b128 v98, v[160:163] offset:46080
	s_waitcnt vmcnt(8)
	ds_write_b128 v98, v[164:167] offset:50688
	s_waitcnt lgkmcnt(0)
	s_barrier
	global_load_dwordx4 v[136:139], v[74:75], off offset:1792
	global_load_dwordx4 v[140:143], v[76:77], off offset:1792
	global_load_dwordx4 v[144:147], v[78:79], off offset:1792
	global_load_dwordx4 v[148:151], v[80:81], off offset:1792
	global_load_dwordx4 v[152:155], v[82:83], off offset:1792
	global_load_dwordx4 v[156:159], v[84:85], off offset:1792
	global_load_dwordx4 v[160:163], v[86:87], off offset:1792
	global_load_dwordx4 v[164:167], v[88:89], off offset:1792
	ds_read_b128 v[212:215], v245 offset:36864
	ds_read_b128 v[196:199], v244
	ds_read_b128 v[216:219], v245 offset:39168
	ds_read_b128 v[220:223], v245 offset:41472
	ds_read_b128 v[224:227], v245 offset:43776
	ds_read_b128 v[200:203], v244 offset:2304
	ds_read_b128 v[204:207], v244 offset:4608
	ds_read_b128 v[208:211], v244 offset:6912
	s_waitcnt lgkmcnt(6)
	v_mfma_f32_16x16x32_bf16 v[50:53], v[196:199], v[212:215], v[50:53]
	ds_read_b128 v[228:231], v245 offset:36928
	s_waitcnt lgkmcnt(6)
	v_mfma_f32_16x16x32_bf16 v[54:57], v[196:199], v[216:219], v[54:57]
	ds_read_b128 v[232:235], v245 offset:39232
	s_waitcnt lgkmcnt(6)
	v_mfma_f32_16x16x32_bf16 v[18:21], v[196:199], v[220:223], v[18:21]
	ds_read_b128 v[236:239], v245 offset:41536
	s_waitcnt lgkmcnt(6)
	v_mfma_f32_16x16x32_bf16 v[22:25], v[196:199], v[224:227], v[22:25]
	ds_read_b128 v[240:243], v245 offset:43840
	ds_read_b128 v[196:199], v244 offset:64
	s_waitcnt lgkmcnt(7)
	v_mfma_f32_16x16x32_bf16 v[58:61], v[200:203], v[212:215], v[58:61]
	v_mfma_f32_16x16x32_bf16 v[62:65], v[200:203], v[216:219], v[62:65]
	v_mfma_f32_16x16x32_bf16 v[26:29], v[200:203], v[220:223], v[26:29]
	v_mfma_f32_16x16x32_bf16 v[30:33], v[200:203], v[224:227], v[30:33]
	ds_read_b128 v[200:203], v244 offset:2368
	s_waitcnt lgkmcnt(7)
	v_mfma_f32_16x16x32_bf16 v[34:37], v[204:207], v[212:215], v[34:37]
	v_mfma_f32_16x16x32_bf16 v[38:41], v[204:207], v[216:219], v[38:41]
	v_mfma_f32_16x16x32_bf16 v[2:5], v[204:207], v[220:223], v[2:5]
	v_mfma_f32_16x16x32_bf16 v[6:9], v[204:207], v[224:227], v[6:9]
	ds_read_b128 v[204:207], v244 offset:4672
	s_waitcnt lgkmcnt(7)
	v_mfma_f32_16x16x32_bf16 v[42:45], v[208:211], v[212:215], v[42:45]
	v_mfma_f32_16x16x32_bf16 v[46:49], v[208:211], v[216:219], v[46:49]
	v_mfma_f32_16x16x32_bf16 v[10:13], v[208:211], v[220:223], v[10:13]
	v_mfma_f32_16x16x32_bf16 v[14:17], v[208:211], v[224:227], v[14:17]
	ds_read_b128 v[208:211], v244 offset:6976
	s_waitcnt lgkmcnt(3)
	v_mfma_f32_16x16x32_bf16 v[50:53], v[196:199], v[228:231], v[50:53]
	v_mfma_f32_16x16x32_bf16 v[54:57], v[196:199], v[232:235], v[54:57]
	v_mfma_f32_16x16x32_bf16 v[18:21], v[196:199], v[236:239], v[18:21]
	v_mfma_f32_16x16x32_bf16 v[22:25], v[196:199], v[240:243], v[22:25]
	s_waitcnt vmcnt(15)
	ds_write_b128 v98, v[102:105] offset:18432
	s_waitcnt vmcnt(14)
	ds_write_b128 v98, v[106:109] offset:23040
	s_waitcnt lgkmcnt(4)
	v_mfma_f32_16x16x32_bf16 v[58:61], v[200:203], v[228:231], v[58:61]
	v_mfma_f32_16x16x32_bf16 v[62:65], v[200:203], v[232:235], v[62:65]
	v_mfma_f32_16x16x32_bf16 v[26:29], v[200:203], v[236:239], v[26:29]
	v_mfma_f32_16x16x32_bf16 v[30:33], v[200:203], v[240:243], v[30:33]
	s_waitcnt vmcnt(13)
	ds_write_b128 v98, v[110:113] offset:27648
	s_waitcnt vmcnt(12)
	ds_write_b128 v98, v[114:117] offset:32256
	s_waitcnt lgkmcnt(5)
	v_mfma_f32_16x16x32_bf16 v[34:37], v[204:207], v[228:231], v[34:37]
	v_mfma_f32_16x16x32_bf16 v[38:41], v[204:207], v[232:235], v[38:41]
	v_mfma_f32_16x16x32_bf16 v[2:5], v[204:207], v[236:239], v[2:5]
	v_mfma_f32_16x16x32_bf16 v[6:9], v[204:207], v[240:243], v[6:9]
	s_waitcnt vmcnt(11)
	ds_write_b128 v98, v[118:121] offset:55296
	s_waitcnt vmcnt(10)
	ds_write_b128 v98, v[122:125] offset:59904
	s_waitcnt lgkmcnt(6)
	v_mfma_f32_16x16x32_bf16 v[42:45], v[208:211], v[228:231], v[42:45]
	v_mfma_f32_16x16x32_bf16 v[46:49], v[208:211], v[232:235], v[46:49]
	v_mfma_f32_16x16x32_bf16 v[10:13], v[208:211], v[236:239], v[10:13]
	v_mfma_f32_16x16x32_bf16 v[14:17], v[208:211], v[240:243], v[14:17]
	s_waitcnt vmcnt(9)
	ds_write_b128 v98, v[126:129] offset:64512
	s_waitcnt vmcnt(8)
	ds_write_b128 v99, v[132:135] offset:32256
	s_waitcnt lgkmcnt(0)
	s_barrier
	global_load_dwordx4 v[102:105], v[74:75], off offset:1920
	s_nop 0
	global_load_dwordx4 v[74:77], v[76:77], off offset:1920
	s_nop 0
	global_load_dwordx4 v[106:109], v[78:79], off offset:1920
	s_nop 0
	global_load_dwordx4 v[78:81], v[80:81], off offset:1920
	s_nop 0
	global_load_dwordx4 v[110:113], v[82:83], off offset:1920
	s_nop 0
	global_load_dwordx4 v[82:85], v[84:85], off offset:1920
	s_nop 0
	global_load_dwordx4 v[114:117], v[86:87], off offset:1920
	s_nop 0
	global_load_dwordx4 v[86:89], v[88:89], off offset:1920
	ds_read_b128 v[212:215], v245 offset:55296
	ds_read_b128 v[196:199], v244 offset:18432
	ds_read_b128 v[216:219], v245 offset:57600
	ds_read_b128 v[220:223], v245 offset:59904
	ds_read_b128 v[224:227], v245 offset:62208
	ds_read_b128 v[200:203], v244 offset:20736
	ds_read_b128 v[204:207], v244 offset:23040
	ds_read_b128 v[208:211], v244 offset:25344
	s_waitcnt lgkmcnt(6)
	v_mfma_f32_16x16x32_bf16 v[50:53], v[196:199], v[212:215], v[50:53]
	ds_read_b128 v[228:231], v245 offset:55360
	s_waitcnt lgkmcnt(6)
	v_mfma_f32_16x16x32_bf16 v[54:57], v[196:199], v[216:219], v[54:57]
	ds_read_b128 v[232:235], v245 offset:57664
	s_waitcnt lgkmcnt(6)
	v_mfma_f32_16x16x32_bf16 v[18:21], v[196:199], v[220:223], v[18:21]
	ds_read_b128 v[236:239], v245 offset:59968
	s_waitcnt lgkmcnt(6)
	v_mfma_f32_16x16x32_bf16 v[22:25], v[196:199], v[224:227], v[22:25]
	ds_read_b128 v[240:243], v245 offset:62272
	ds_read_b128 v[196:199], v244 offset:18496
	s_waitcnt lgkmcnt(7)
	v_mfma_f32_16x16x32_bf16 v[58:61], v[200:203], v[212:215], v[58:61]
	v_mfma_f32_16x16x32_bf16 v[62:65], v[200:203], v[216:219], v[62:65]
	v_mfma_f32_16x16x32_bf16 v[26:29], v[200:203], v[220:223], v[26:29]
	v_mfma_f32_16x16x32_bf16 v[30:33], v[200:203], v[224:227], v[30:33]
	ds_read_b128 v[200:203], v244 offset:20800
	s_waitcnt lgkmcnt(7)
	v_mfma_f32_16x16x32_bf16 v[34:37], v[204:207], v[212:215], v[34:37]
	v_mfma_f32_16x16x32_bf16 v[38:41], v[204:207], v[216:219], v[38:41]
	v_mfma_f32_16x16x32_bf16 v[2:5], v[204:207], v[220:223], v[2:5]
	v_mfma_f32_16x16x32_bf16 v[6:9], v[204:207], v[224:227], v[6:9]
	ds_read_b128 v[204:207], v244 offset:23104
	s_waitcnt lgkmcnt(7)
	v_mfma_f32_16x16x32_bf16 v[42:45], v[208:211], v[212:215], v[42:45]
	v_mfma_f32_16x16x32_bf16 v[46:49], v[208:211], v[216:219], v[46:49]
	v_mfma_f32_16x16x32_bf16 v[10:13], v[208:211], v[220:223], v[10:13]
	v_mfma_f32_16x16x32_bf16 v[14:17], v[208:211], v[224:227], v[14:17]
	ds_read_b128 v[208:211], v244 offset:25408
	s_waitcnt lgkmcnt(3)
	v_mfma_f32_16x16x32_bf16 v[50:53], v[196:199], v[228:231], v[50:53]
	v_mfma_f32_16x16x32_bf16 v[54:57], v[196:199], v[232:235], v[54:57]
	v_mfma_f32_16x16x32_bf16 v[18:21], v[196:199], v[236:239], v[18:21]
	v_mfma_f32_16x16x32_bf16 v[22:25], v[196:199], v[240:243], v[22:25]
	s_waitcnt vmcnt(15)
	ds_write_b128 v98, v[136:139]
	s_waitcnt vmcnt(14)
	ds_write_b128 v98, v[140:143] offset:4608
	s_waitcnt lgkmcnt(4)
	v_mfma_f32_16x16x32_bf16 v[58:61], v[200:203], v[228:231], v[58:61]
	v_mfma_f32_16x16x32_bf16 v[62:65], v[200:203], v[232:235], v[62:65]
	v_mfma_f32_16x16x32_bf16 v[26:29], v[200:203], v[236:239], v[26:29]
	v_mfma_f32_16x16x32_bf16 v[30:33], v[200:203], v[240:243], v[30:33]
	s_waitcnt vmcnt(13)
	ds_write_b128 v98, v[144:147] offset:9216
	s_waitcnt vmcnt(12)
	ds_write_b128 v98, v[148:151] offset:13824
	s_waitcnt lgkmcnt(5)
	v_mfma_f32_16x16x32_bf16 v[34:37], v[204:207], v[228:231], v[34:37]
	v_mfma_f32_16x16x32_bf16 v[38:41], v[204:207], v[232:235], v[38:41]
	v_mfma_f32_16x16x32_bf16 v[2:5], v[204:207], v[236:239], v[2:5]
	v_mfma_f32_16x16x32_bf16 v[6:9], v[204:207], v[240:243], v[6:9]
	s_waitcnt vmcnt(11)
	ds_write_b128 v98, v[152:155] offset:36864
	s_waitcnt vmcnt(10)
	ds_write_b128 v98, v[156:159] offset:41472
	s_waitcnt lgkmcnt(6)
	v_mfma_f32_16x16x32_bf16 v[42:45], v[208:211], v[228:231], v[42:45]
	v_mfma_f32_16x16x32_bf16 v[46:49], v[208:211], v[232:235], v[46:49]
	v_mfma_f32_16x16x32_bf16 v[10:13], v[208:211], v[236:239], v[10:13]
	v_mfma_f32_16x16x32_bf16 v[14:17], v[208:211], v[240:243], v[14:17]
	s_waitcnt vmcnt(9)
	ds_write_b128 v98, v[160:163] offset:46080
	s_waitcnt vmcnt(8)
	ds_write_b128 v98, v[164:167] offset:50688
	s_waitcnt lgkmcnt(0)
	s_barrier
	ds_read_b128 v[212:215], v245 offset:36864
	ds_read_b128 v[196:199], v244
	ds_read_b128 v[216:219], v245 offset:39168
	ds_read_b128 v[220:223], v245 offset:41472
	ds_read_b128 v[224:227], v245 offset:43776
	ds_read_b128 v[200:203], v244 offset:2304
	ds_read_b128 v[204:207], v244 offset:4608
	ds_read_b128 v[208:211], v244 offset:6912
	s_waitcnt lgkmcnt(6)
	v_mfma_f32_16x16x32_bf16 v[50:53], v[196:199], v[212:215], v[50:53]
	ds_read_b128 v[228:231], v245 offset:36928
	s_waitcnt lgkmcnt(6)
	v_mfma_f32_16x16x32_bf16 v[54:57], v[196:199], v[216:219], v[54:57]
	ds_read_b128 v[232:235], v245 offset:39232
	s_waitcnt lgkmcnt(6)
	v_mfma_f32_16x16x32_bf16 v[18:21], v[196:199], v[220:223], v[18:21]
	ds_read_b128 v[236:239], v245 offset:41536
	s_waitcnt lgkmcnt(6)
	v_mfma_f32_16x16x32_bf16 v[22:25], v[196:199], v[224:227], v[22:25]
	ds_read_b128 v[240:243], v245 offset:43840
	ds_read_b128 v[196:199], v244 offset:64
	s_waitcnt lgkmcnt(7)
	v_mfma_f32_16x16x32_bf16 v[58:61], v[200:203], v[212:215], v[58:61]
	v_mfma_f32_16x16x32_bf16 v[62:65], v[200:203], v[216:219], v[62:65]
	v_mfma_f32_16x16x32_bf16 v[26:29], v[200:203], v[220:223], v[26:29]
	v_mfma_f32_16x16x32_bf16 v[30:33], v[200:203], v[224:227], v[30:33]
	ds_read_b128 v[200:203], v244 offset:2368
	s_waitcnt lgkmcnt(7)
	v_mfma_f32_16x16x32_bf16 v[34:37], v[204:207], v[212:215], v[34:37]
	v_mfma_f32_16x16x32_bf16 v[38:41], v[204:207], v[216:219], v[38:41]
	v_mfma_f32_16x16x32_bf16 v[2:5], v[204:207], v[220:223], v[2:5]
	v_mfma_f32_16x16x32_bf16 v[6:9], v[204:207], v[224:227], v[6:9]
	ds_read_b128 v[204:207], v244 offset:4672
	s_waitcnt lgkmcnt(7)
	v_mfma_f32_16x16x32_bf16 v[42:45], v[208:211], v[212:215], v[42:45]
	v_mfma_f32_16x16x32_bf16 v[46:49], v[208:211], v[216:219], v[46:49]
	v_mfma_f32_16x16x32_bf16 v[10:13], v[208:211], v[220:223], v[10:13]
	v_mfma_f32_16x16x32_bf16 v[14:17], v[208:211], v[224:227], v[14:17]
	ds_read_b128 v[208:211], v244 offset:6976
	s_waitcnt lgkmcnt(3)
	v_mfma_f32_16x16x32_bf16 v[50:53], v[196:199], v[228:231], v[50:53]
	v_mfma_f32_16x16x32_bf16 v[54:57], v[196:199], v[232:235], v[54:57]
	v_mfma_f32_16x16x32_bf16 v[18:21], v[196:199], v[236:239], v[18:21]
	v_mfma_f32_16x16x32_bf16 v[22:25], v[196:199], v[240:243], v[22:25]
	s_waitcnt vmcnt(7)
	ds_write_b128 v98, v[102:105] offset:18432
	s_waitcnt vmcnt(6)
	ds_write_b128 v98, v[74:77] offset:23040
	s_waitcnt lgkmcnt(4)
	v_mfma_f32_16x16x32_bf16 v[58:61], v[200:203], v[228:231], v[58:61]
	v_mfma_f32_16x16x32_bf16 v[62:65], v[200:203], v[232:235], v[62:65]
	v_mfma_f32_16x16x32_bf16 v[26:29], v[200:203], v[236:239], v[26:29]
	v_mfma_f32_16x16x32_bf16 v[30:33], v[200:203], v[240:243], v[30:33]
	s_waitcnt vmcnt(5)
	ds_write_b128 v98, v[106:109] offset:27648
	s_waitcnt vmcnt(4)
	ds_write_b128 v98, v[78:81] offset:32256
	s_waitcnt lgkmcnt(5)
	v_mfma_f32_16x16x32_bf16 v[34:37], v[204:207], v[228:231], v[34:37]
	v_mfma_f32_16x16x32_bf16 v[38:41], v[204:207], v[232:235], v[38:41]
	v_mfma_f32_16x16x32_bf16 v[2:5], v[204:207], v[236:239], v[2:5]
	v_mfma_f32_16x16x32_bf16 v[6:9], v[204:207], v[240:243], v[6:9]
	s_waitcnt vmcnt(3)
	ds_write_b128 v98, v[110:113] offset:55296
	s_waitcnt vmcnt(2)
	ds_write_b128 v98, v[82:85] offset:59904
	s_waitcnt lgkmcnt(6)
	v_mfma_f32_16x16x32_bf16 v[42:45], v[208:211], v[228:231], v[42:45]
	v_mfma_f32_16x16x32_bf16 v[46:49], v[208:211], v[232:235], v[46:49]
	v_mfma_f32_16x16x32_bf16 v[10:13], v[208:211], v[236:239], v[10:13]
	v_mfma_f32_16x16x32_bf16 v[14:17], v[208:211], v[240:243], v[14:17]
	s_waitcnt vmcnt(1)
	ds_write_b128 v98, v[114:117] offset:64512
	s_waitcnt vmcnt(0)
	ds_write_b128 v99, v[86:89] offset:32256
	s_waitcnt lgkmcnt(0)
	s_barrier
	ds_read_b128 v[212:215], v245 offset:55296
	ds_read_b128 v[196:199], v244 offset:18432
	ds_read_b128 v[216:219], v245 offset:57600
	ds_read_b128 v[220:223], v245 offset:59904
	ds_read_b128 v[224:227], v245 offset:62208
	ds_read_b128 v[200:203], v244 offset:20736
	ds_read_b128 v[204:207], v244 offset:23040
	ds_read_b128 v[208:211], v244 offset:25344
	s_waitcnt lgkmcnt(6)
	v_mfma_f32_16x16x32_bf16 v[50:53], v[196:199], v[212:215], v[50:53]
	ds_read_b128 v[228:231], v245 offset:55360
	s_waitcnt lgkmcnt(6)
	v_mfma_f32_16x16x32_bf16 v[54:57], v[196:199], v[216:219], v[54:57]
	ds_read_b128 v[232:235], v245 offset:57664
	s_waitcnt lgkmcnt(6)
	v_mfma_f32_16x16x32_bf16 v[18:21], v[196:199], v[220:223], v[18:21]
	ds_read_b128 v[236:239], v245 offset:59968
	s_waitcnt lgkmcnt(6)
	v_mfma_f32_16x16x32_bf16 v[22:25], v[196:199], v[224:227], v[22:25]
	ds_read_b128 v[240:243], v245 offset:62272
	ds_read_b128 v[196:199], v244 offset:18496
	s_waitcnt lgkmcnt(7)
	v_mfma_f32_16x16x32_bf16 v[58:61], v[200:203], v[212:215], v[58:61]
	v_mfma_f32_16x16x32_bf16 v[62:65], v[200:203], v[216:219], v[62:65]
	v_mfma_f32_16x16x32_bf16 v[26:29], v[200:203], v[220:223], v[26:29]
	v_mfma_f32_16x16x32_bf16 v[30:33], v[200:203], v[224:227], v[30:33]
	ds_read_b128 v[200:203], v244 offset:20800
	s_waitcnt lgkmcnt(7)
	v_mfma_f32_16x16x32_bf16 v[34:37], v[204:207], v[212:215], v[34:37]
	v_mfma_f32_16x16x32_bf16 v[38:41], v[204:207], v[216:219], v[38:41]
	v_mfma_f32_16x16x32_bf16 v[2:5], v[204:207], v[220:223], v[2:5]
	v_mfma_f32_16x16x32_bf16 v[6:9], v[204:207], v[224:227], v[6:9]
	ds_read_b128 v[204:207], v244 offset:23104
	s_waitcnt lgkmcnt(7)
	v_mfma_f32_16x16x32_bf16 v[42:45], v[208:211], v[212:215], v[42:45]
	v_mfma_f32_16x16x32_bf16 v[46:49], v[208:211], v[216:219], v[46:49]
	v_mfma_f32_16x16x32_bf16 v[10:13], v[208:211], v[220:223], v[10:13]
	v_mfma_f32_16x16x32_bf16 v[14:17], v[208:211], v[224:227], v[14:17]
	ds_read_b128 v[208:211], v244 offset:25408
	s_waitcnt lgkmcnt(3)
	v_mfma_f32_16x16x32_bf16 v[50:53], v[196:199], v[228:231], v[50:53]
	v_mfma_f32_16x16x32_bf16 v[54:57], v[196:199], v[232:235], v[54:57]
	v_mfma_f32_16x16x32_bf16 v[18:21], v[196:199], v[236:239], v[18:21]
	v_mfma_f32_16x16x32_bf16 v[22:25], v[196:199], v[240:243], v[22:25]
	s_waitcnt lgkmcnt(2)
	v_mfma_f32_16x16x32_bf16 v[58:61], v[200:203], v[228:231], v[58:61]
	v_mfma_f32_16x16x32_bf16 v[62:65], v[200:203], v[232:235], v[62:65]
	v_mfma_f32_16x16x32_bf16 v[26:29], v[200:203], v[236:239], v[26:29]
	v_mfma_f32_16x16x32_bf16 v[30:33], v[200:203], v[240:243], v[30:33]
	s_waitcnt lgkmcnt(1)
	v_mfma_f32_16x16x32_bf16 v[34:37], v[204:207], v[228:231], v[34:37]
	v_mfma_f32_16x16x32_bf16 v[38:41], v[204:207], v[232:235], v[38:41]
	v_mfma_f32_16x16x32_bf16 v[2:5], v[204:207], v[236:239], v[2:5]
	v_mfma_f32_16x16x32_bf16 v[6:9], v[204:207], v[240:243], v[6:9]
	s_waitcnt lgkmcnt(0)
	v_mfma_f32_16x16x32_bf16 v[42:45], v[208:211], v[228:231], v[42:45]
	v_mfma_f32_16x16x32_bf16 v[46:49], v[208:211], v[232:235], v[46:49]
	v_mfma_f32_16x16x32_bf16 v[10:13], v[208:211], v[236:239], v[10:13]
	v_mfma_f32_16x16x32_bf16 v[14:17], v[208:211], v[240:243], v[14:17]
	s_lshr_b32 s14, s2, 3
	s_bfe_u32 s13, s2, 0x10002
	s_cmp_lt_i32 s14, 1
	s_mov_b64 s[2:3], -1
	s_waitcnt lgkmcnt(0)
	s_barrier
	s_nop 7
	v_permlane16_swap_b32_e32 v50, v54
	v_permlane16_swap_b32_e32 v51, v55
	v_permlane16_swap_b32_e32 v52, v56
	v_permlane16_swap_b32_e32 v53, v57
	v_permlane16_swap_b32_e32 v58, v62
	v_permlane16_swap_b32_e32 v59, v63
	v_permlane16_swap_b32_e32 v60, v64
	v_permlane16_swap_b32_e32 v61, v65
	v_permlane16_swap_b32_e32 v18, v22
	v_permlane16_swap_b32_e32 v19, v23
	v_permlane16_swap_b32_e32 v20, v24
	v_permlane16_swap_b32_e32 v21, v25
	v_permlane16_swap_b32_e32 v26, v30
	v_permlane16_swap_b32_e32 v27, v31
	v_permlane16_swap_b32_e32 v28, v32
	v_permlane16_swap_b32_e32 v29, v33
	v_permlane16_swap_b32_e32 v34, v38
	v_permlane16_swap_b32_e32 v35, v39
	v_permlane16_swap_b32_e32 v36, v40
	v_permlane16_swap_b32_e32 v37, v41
	v_permlane16_swap_b32_e32 v42, v46
	v_permlane16_swap_b32_e32 v43, v47
	v_permlane16_swap_b32_e32 v44, v48
	v_permlane16_swap_b32_e32 v45, v49
	v_permlane16_swap_b32_e32 v2, v6
	v_permlane16_swap_b32_e32 v3, v7
	v_permlane16_swap_b32_e32 v4, v8
	v_permlane16_swap_b32_e32 v5, v9
	v_permlane16_swap_b32_e32 v10, v14
	v_permlane16_swap_b32_e32 v11, v15
	v_permlane16_swap_b32_e32 v12, v16
	v_permlane16_swap_b32_e32 v13, v17
	v_permlane32_swap_b32_e32 v50, v54
	v_permlane32_swap_b32_e32 v51, v55
	v_permlane32_swap_b32_e32 v52, v56
	v_permlane32_swap_b32_e32 v53, v57
	v_permlane32_swap_b32_e32 v58, v62
	v_permlane32_swap_b32_e32 v59, v63
	v_permlane32_swap_b32_e32 v60, v64
	v_permlane32_swap_b32_e32 v61, v65
	v_permlane32_swap_b32_e32 v18, v22
	v_permlane32_swap_b32_e32 v19, v23
	v_permlane32_swap_b32_e32 v20, v24
	v_permlane32_swap_b32_e32 v21, v25
	v_permlane32_swap_b32_e32 v26, v30
	v_permlane32_swap_b32_e32 v27, v31
	v_permlane32_swap_b32_e32 v28, v32
	v_permlane32_swap_b32_e32 v29, v33
	v_permlane32_swap_b32_e32 v34, v38
	v_permlane32_swap_b32_e32 v35, v39
	v_permlane32_swap_b32_e32 v36, v40
	v_permlane32_swap_b32_e32 v37, v41
	v_permlane32_swap_b32_e32 v42, v46
	v_permlane32_swap_b32_e32 v43, v47
	v_permlane32_swap_b32_e32 v44, v48
	v_permlane32_swap_b32_e32 v45, v49
	v_permlane32_swap_b32_e32 v2, v6
	v_permlane32_swap_b32_e32 v3, v7
	v_permlane32_swap_b32_e32 v4, v8
	v_permlane32_swap_b32_e32 v5, v9
	v_permlane32_swap_b32_e32 v10, v14
	v_permlane32_swap_b32_e32 v11, v15
	v_permlane32_swap_b32_e32 v12, v16
	v_permlane32_swap_b32_e32 v13, v17
	s_cbranch_scc1 .LBB0_1647
	s_and_b32 s2, 0xffff, s14
	s_cmp_lg_u32 s2, 1
	s_mov_b64 s[2:3], -1
	s_cbranch_scc0 .LBB0_1644
	s_cmp_eq_u32 s13, 0
	s_cselect_b32 s12, 3, 10
	s_mov_b64 s[2:3], 0
